# static priority (doc 7.4): per-segment s_setprio flips removed from the 8 main K-loops, trail half (wr=1) runs each K-loop at priority 1, lead at 0; on top of v68
# speedup vs baseline: 1.0043x; 1.0043x over previous
; #define PG8_STAGEX(rs, bufoff, soff, voff) do { _Pragma("unroll") for (int _i = 0; _i < 2; ++_i) \
;         __builtin_amdgcn_raw_ptr_buffer_load_lds(rs, (LAS unsigned*)(lds + (bufoff) + ldsw + _i * 8192), 16, (voff)[_i], (soff), 0, 0); } while (0)
; #define PG8_LDA(dst, b, h) do { _Pragma("unroll") for (int m = 0; m < 4; ++m) _Pragma("unroll") for (int k = 0; k < 2; ++k) dst[m][k] = *(const LAS bf16x8*)(lds + PG8_SA(b, h) + aoff + m * 2048 + k * 1024); } while (0)
; #define PG8_LDB(dst, b, h) do { _Pragma("unroll") for (int n = 0; n < 2; ++n) _Pragma("unroll") for (int k = 0; k < 2; ++k) dst[n][k] = *(const LAS bf16x8*)(lds + PG8_SB(b, h) + boff + n * 2048 + k * 1024); } while (0)
; #define PG8_WAIT_V(n) asm volatile("s_waitcnt vmcnt(" #n ")" ::: "memory")
; #define PG8_WAIT_L(n) asm volatile("s_waitcnt lgkmcnt(" #n ")" ::: "memory")
; #define PG8_BAR __builtin_amdgcn_s_barrier()
; #define PG8_SCHED __builtin_amdgcn_sched_barrier(0)
;     ...
;             PG8_LDB(B0, 0, 0); PG8_LDB(B1, 0, 1); PG8_SCHED; PG8_LDA(At, 0, 0); PG8_STAGEX(rsA, PG8_SA(1, 1), a1 + hstepA, voffA);
;             PG8_WAIT_V(8); PG8_WAIT_L(0); PG8_BAR; PG8_MMA(0, 0, At, B0); PG8_MMA(0, 1, At, B1); PG8_BAR; PG8_SCHED;
;     ...
;         if (!cur.keep) {
; #pragma unroll
;             for (int a = 0; a < 2; ++a)
; #pragma unroll
;                 for (int b = 0; b < 2; ++b)
; #pragma unroll
;                     for (int m = 0; m < 4; ++m)
; #pragma unroll
;                         for (int n = 0; n < 2; ++n) { f32x2 z0, z1; asm("v_mov_b64 %0, 0\n\tv_mov_b64 %1, 0" : "=v"(z0), "=v"(z1));
;                     acc[a][b][m][n] = __builtin_shufflevector(z0, z1, 0, 1, 2, 3); }
.LBB0_222:
	s_lshl_b32 s28, s27, 20
	s_and_b64 s[30:31], s[38:39], exec
	s_cselect_b32 s30, s28, s50
	s_lshl_b32 s29, s26, 20
	s_and_b64 s[52:53], s[38:39], exec
	v_mov_b64_e32 v[12:13], v[4:5]
	v_mov_b64_e32 v[20:21], v[4:5]
	s_waitcnt vmcnt(15)
	v_mov_b64_e32 v[28:29], v[4:5]
	v_mov_b64_e32 v[36:37], v[4:5]
	v_mov_b64_e32 v[44:45], v[4:5]
	v_mov_b64_e32 v[52:53], v[4:5]
	v_mov_b64_e32 v[60:61], v[4:5]
	v_mov_b64_e32 v[8:9], v[4:5]
	v_mov_b64_e32 v[16:17], v[4:5]
	v_mov_b64_e32 v[24:25], v[4:5]
	v_mov_b64_e32 v[32:33], v[4:5]
	v_mov_b64_e32 v[40:41], v[4:5]
	v_mov_b64_e32 v[48:49], v[4:5]
	v_mov_b64_e32 v[56:57], v[4:5]
	v_mov_b64_e32 v[64:65], v[4:5]
	v_mov_b64_e32 v[68:69], v[4:5]
	v_mov_b64_e32 v[76:77], v[4:5]
	v_mov_b64_e32 v[92:93], v[4:5]
	v_mov_b64_e32 v[108:109], v[4:5]
	v_mov_b64_e32 v[116:117], v[4:5]
	v_mov_b64_e32 v[124:125], v[4:5]
	v_mov_b64_e32 v[132:133], v[4:5]
	v_mov_b64_e32 v[140:141], v[4:5]
	v_mov_b64_e32 v[72:73], v[4:5]
	v_mov_b64_e32 v[80:81], v[4:5]
	v_mov_b64_e32 v[96:97], v[4:5]
	v_mov_b64_e32 v[112:113], v[4:5]
	v_mov_b64_e32 v[120:121], v[4:5]
	v_mov_b64_e32 v[128:129], v[4:5]
	v_mov_b64_e32 v[136:137], v[4:5]
	v_mov_b64_e32 v[144:145], v[4:5]
	s_cselect_b32 s31, s29, s42
	s_add_i32 s50, s50, 0x80080
	s_add_i32 s51, s42, 0x100
	s_mov_b32 s52, -2
	v_mov_b64_e32 v[10:11], v[2:3]
	v_mov_b64_e32 v[18:19], v[2:3]
	v_mov_b64_e32 v[26:27], v[2:3]
	v_mov_b64_e32 v[34:35], v[2:3]
	v_mov_b64_e32 v[42:43], v[2:3]
	v_mov_b64_e32 v[50:51], v[2:3]
	v_mov_b64_e32 v[58:59], v[2:3]
	v_mov_b64_e32 v[6:7], v[2:3]
	v_mov_b64_e32 v[14:15], v[2:3]
	v_mov_b64_e32 v[22:23], v[2:3]
	v_mov_b64_e32 v[30:31], v[2:3]
	v_mov_b64_e32 v[38:39], v[2:3]
	v_mov_b64_e32 v[46:47], v[2:3]
	v_mov_b64_e32 v[54:55], v[2:3]
	v_mov_b64_e32 v[62:63], v[2:3]
	v_mov_b64_e32 v[66:67], v[2:3]
	v_mov_b64_e32 v[74:75], v[2:3]
	v_mov_b64_e32 v[90:91], v[2:3]
	v_mov_b64_e32 v[106:107], v[2:3]
	v_mov_b64_e32 v[114:115], v[2:3]
	v_mov_b64_e32 v[122:123], v[2:3]
	v_mov_b64_e32 v[130:131], v[2:3]
	v_mov_b64_e32 v[138:139], v[2:3]
	v_mov_b64_e32 v[70:71], v[2:3]
	v_mov_b64_e32 v[78:79], v[2:3]
	v_mov_b64_e32 v[94:95], v[2:3]
	v_mov_b64_e32 v[110:111], v[2:3]
	v_mov_b64_e32 v[118:119], v[2:3]
	v_mov_b64_e32 v[126:127], v[2:3]
	v_mov_b64_e32 v[134:135], v[2:3]
	v_mov_b64_e32 v[142:143], v[2:3]
	s_and_b64 vcc, exec, s[44:45]
	s_cbranch_vccz .Lsp_223
	s_setprio 1
.Lsp_223:
	.p2align	6
.LBB0_223:
	v_add_u32_e32 v102, 0x10000, v172
	v_add_u32_e32 v146, 0x14000, v172
	ds_read_b128 v[82:85], v102
	ds_read_b128 v[86:89], v102 offset:1024
	ds_read_b128 v[98:101], v102 offset:2048
	ds_read_b128 v[102:105], v102 offset:3072
	ds_read_b128 v[150:153], v146
	ds_read_b128 v[154:157], v146 offset:1024
	ds_read_b128 v[182:185], v146 offset:2048
	ds_read_b128 v[186:189], v146 offset:3072
	s_add_i32 s42, s50, 0xfff80080
	s_cmp_eq_u32 s52, 28
	s_cselect_b32 s55, s30, s42
	s_cselect_b32 s54, s31, s51
	s_or_b32 s53, s55, 0x80
	s_mov_b32 m0, s22
	ds_read_b128 v[190:193], v173
	ds_read_b128 v[194:197], v173 offset:1024
	ds_read_b128 v[198:201], v173 offset:2048
	ds_read_b128 v[202:205], v173 offset:3072
	ds_read_b128 v[206:209], v173 offset:4096
	ds_read_b128 v[210:213], v173 offset:5120
	ds_read_b128 v[214:217], v173 offset:6144
	ds_read_b128 v[218:221], v173 offset:7168
	buffer_load_dwordx4 v159, s[76:79], s50 offen lds
	s_mov_b32 m0, s23
	s_nop 0
	buffer_load_dwordx4 v163, s[76:79], s50 offen lds
	s_waitcnt vmcnt(8)
	s_waitcnt lgkmcnt(0)
	s_barrier
	v_mfma_f32_16x16x32_bf16 v[142:145], v[82:85], v[190:193], v[142:145]
	v_mfma_f32_16x16x32_bf16 v[142:145], v[86:89], v[194:197], v[142:145]
	v_mfma_f32_16x16x32_bf16 v[134:137], v[102:105], v[194:197], v[134:137]
	v_mfma_f32_16x16x32_bf16 v[134:137], v[98:101], v[190:193], v[134:137]
	v_mfma_f32_16x16x32_bf16 v[118:121], v[98:101], v[198:201], v[118:121]
	v_mfma_f32_16x16x32_bf16 v[118:121], v[102:105], v[202:205], v[118:121]
	v_mfma_f32_16x16x32_bf16 v[126:129], v[86:89], v[202:205], v[126:129]
	v_mfma_f32_16x16x32_bf16 v[126:129], v[82:85], v[198:201], v[126:129]
	v_mfma_f32_16x16x32_bf16 v[110:113], v[82:85], v[206:209], v[110:113]
	v_mfma_f32_16x16x32_bf16 v[110:113], v[86:89], v[210:213], v[110:113]
	v_mfma_f32_16x16x32_bf16 v[94:97], v[102:105], v[210:213], v[94:97]
	v_mfma_f32_16x16x32_bf16 v[94:97], v[98:101], v[206:209], v[94:97]
	v_mfma_f32_16x16x32_bf16 v[70:73], v[98:101], v[214:217], v[70:73]
	v_mfma_f32_16x16x32_bf16 v[70:73], v[102:105], v[218:221], v[70:73]
	v_mfma_f32_16x16x32_bf16 v[78:81], v[86:89], v[218:221], v[78:81]
	v_mfma_f32_16x16x32_bf16 v[78:81], v[82:85], v[214:217], v[78:81]
	v_mfma_f32_16x16x32_bf16 v[138:141], v[150:153], v[190:193], v[138:141]
	v_mfma_f32_16x16x32_bf16 v[138:141], v[154:157], v[194:197], v[138:141]
	v_mfma_f32_16x16x32_bf16 v[130:133], v[186:189], v[194:197], v[130:133]
	v_mfma_f32_16x16x32_bf16 v[130:133], v[182:185], v[190:193], v[130:133]
	v_mfma_f32_16x16x32_bf16 v[114:117], v[182:185], v[198:201], v[114:117]
	v_mfma_f32_16x16x32_bf16 v[114:117], v[186:189], v[202:205], v[114:117]
	v_mfma_f32_16x16x32_bf16 v[122:125], v[154:157], v[202:205], v[122:125]
	v_mfma_f32_16x16x32_bf16 v[122:125], v[150:153], v[198:201], v[122:125]
	v_mfma_f32_16x16x32_bf16 v[106:109], v[150:153], v[206:209], v[106:109]
	v_mfma_f32_16x16x32_bf16 v[106:109], v[154:157], v[210:213], v[106:109]
	v_mfma_f32_16x16x32_bf16 v[90:93], v[186:189], v[210:213], v[90:93]
	v_mfma_f32_16x16x32_bf16 v[90:93], v[182:185], v[206:209], v[90:93]
	v_mfma_f32_16x16x32_bf16 v[66:69], v[182:185], v[214:217], v[66:69]
	v_mfma_f32_16x16x32_bf16 v[66:69], v[186:189], v[218:221], v[66:69]
	v_mfma_f32_16x16x32_bf16 v[74:77], v[154:157], v[218:221], v[74:77]
	v_mfma_f32_16x16x32_bf16 v[74:77], v[150:153], v[214:217], v[74:77]
	s_barrier
; #define PG8_STAGEX(rs, bufoff, soff, voff) do { _Pragma("unroll") for (int _i = 0; _i < 2; ++_i) \
;         __builtin_amdgcn_raw_ptr_buffer_load_lds(rs, (LAS unsigned*)(lds + (bufoff) + ldsw + _i * 8192), 16, (voff)[_i], (soff), 0, 0); } while (0)
; #define PG8_LDA(dst, b, h) do { _Pragma("unroll") for (int m = 0; m < 4; ++m) _Pragma("unroll") for (int k = 0; k < 2; ++k) dst[m][k] = *(const LAS bf16x8*)(lds + PG8_SA(b, h) + aoff + m * 2048 + k * 1024); } while (0)
; #define PG8_LDB(dst, b, h) do { _Pragma("unroll") for (int n = 0; n < 2; ++n) _Pragma("unroll") for (int k = 0; k < 2; ++k) dst[n][k] = *(const LAS bf16x8*)(lds + PG8_SB(b, h) + boff + n * 2048 + k * 1024); } while (0)
; #define PG8_WAIT_V(n) asm volatile("s_waitcnt vmcnt(" #n ")" ::: "memory")
; #define PG8_WAIT_L(n) asm volatile("s_waitcnt lgkmcnt(" #n ")" ::: "memory")
; #define PG8_BAR __builtin_amdgcn_s_barrier()
; #define PG8_SCHED __builtin_amdgcn_sched_barrier(0)
;     ...
;             PG8_LDA(At, 0, 1); PG8_STAGEX(rsB, PG8_SB(0, 0), b2, voffB); PG8_STAGEX(rsB, PG8_SB(0, 1), b2 + hstepB, voffB); PG8_STAGEX(rsA, PG8_SA(0, 0), a2, voffA);
;             PG8_WAIT_V(8); PG8_WAIT_L(0); PG8_BAR; PG8_MMA(1, 0, At, B0); PG8_MMA(1, 1, At, B1); PG8_BAR; PG8_SCHED;
;             PG8_LDB(B0, 1, 0); PG8_LDB(B1, 1, 1); PG8_SCHED; PG8_LDA(At, 1, 0); PG8_STAGEX(rsA, PG8_SA(0, 1), a2 + hstepA, voffA);
	s_mov_b32 m0, s9
	s_mov_b32 s42, s78
	s_mov_b32 s43, s79
	ds_read_b128 v[190:193], v173 offset:16384
	ds_read_b128 v[194:197], v173 offset:17408
	ds_read_b128 v[198:201], v173 offset:18432
	ds_read_b128 v[202:205], v173 offset:19456
	ds_read_b128 v[206:209], v173 offset:20480
	ds_read_b128 v[210:213], v173 offset:21504
	ds_read_b128 v[214:217], v173 offset:22528
	ds_read_b128 v[218:221], v173 offset:23552
	buffer_load_dwordx4 v161, s[40:43], s54 offen lds
	s_mov_b32 m0, s10
	s_add_i32 s56, s54, 0x80000
	buffer_load_dwordx4 v165, s[40:43], s54 offen lds
	s_mov_b32 m0, s11
	s_nop 0
	buffer_load_dwordx4 v161, s[40:43], s56 offen lds
	s_mov_b32 m0, s12
	s_nop 0
	buffer_load_dwordx4 v165, s[40:43], s56 offen lds
	s_mov_b32 m0, s8
	s_nop 0
	buffer_load_dwordx4 v159, s[76:79], s55 offen lds
	s_mov_b32 m0, s13
	s_nop 0
	buffer_load_dwordx4 v163, s[76:79], s55 offen lds
	s_waitcnt vmcnt(8)
	s_waitcnt lgkmcnt(0)
	s_barrier
	v_mfma_f32_16x16x32_bf16 v[62:65], v[82:85], v[190:193], v[62:65]
	v_mfma_f32_16x16x32_bf16 v[62:65], v[86:89], v[194:197], v[62:65]
	v_mfma_f32_16x16x32_bf16 v[54:57], v[102:105], v[194:197], v[54:57]
	v_mfma_f32_16x16x32_bf16 v[54:57], v[98:101], v[190:193], v[54:57]
	v_mfma_f32_16x16x32_bf16 v[38:41], v[98:101], v[198:201], v[38:41]
	v_mfma_f32_16x16x32_bf16 v[38:41], v[102:105], v[202:205], v[38:41]
	v_mfma_f32_16x16x32_bf16 v[46:49], v[86:89], v[202:205], v[46:49]
	v_mfma_f32_16x16x32_bf16 v[46:49], v[82:85], v[198:201], v[46:49]
	v_mfma_f32_16x16x32_bf16 v[30:33], v[82:85], v[206:209], v[30:33]
	v_mfma_f32_16x16x32_bf16 v[30:33], v[86:89], v[210:213], v[30:33]
	v_mfma_f32_16x16x32_bf16 v[22:25], v[102:105], v[210:213], v[22:25]
	v_mfma_f32_16x16x32_bf16 v[22:25], v[98:101], v[206:209], v[22:25]
	v_mfma_f32_16x16x32_bf16 v[6:9], v[98:101], v[214:217], v[6:9]
	v_mfma_f32_16x16x32_bf16 v[6:9], v[102:105], v[218:221], v[6:9]
	v_mfma_f32_16x16x32_bf16 v[14:17], v[86:89], v[218:221], v[14:17]
	v_mfma_f32_16x16x32_bf16 v[14:17], v[82:85], v[214:217], v[14:17]
	v_mfma_f32_16x16x32_bf16 v[58:61], v[150:153], v[190:193], v[58:61]
	v_mfma_f32_16x16x32_bf16 v[58:61], v[154:157], v[194:197], v[58:61]
	v_mfma_f32_16x16x32_bf16 v[50:53], v[186:189], v[194:197], v[50:53]
	v_mfma_f32_16x16x32_bf16 v[50:53], v[182:185], v[190:193], v[50:53]
	v_mfma_f32_16x16x32_bf16 v[34:37], v[182:185], v[198:201], v[34:37]
	v_mfma_f32_16x16x32_bf16 v[34:37], v[186:189], v[202:205], v[34:37]
	v_mfma_f32_16x16x32_bf16 v[42:45], v[154:157], v[202:205], v[42:45]
	v_mfma_f32_16x16x32_bf16 v[42:45], v[150:153], v[198:201], v[42:45]
	v_mfma_f32_16x16x32_bf16 v[26:29], v[150:153], v[206:209], v[26:29]
	v_mfma_f32_16x16x32_bf16 v[26:29], v[154:157], v[210:213], v[26:29]
	v_mfma_f32_16x16x32_bf16 v[18:21], v[186:189], v[210:213], v[18:21]
	v_mfma_f32_16x16x32_bf16 v[18:21], v[182:185], v[206:209], v[18:21]
	v_mfma_f32_16x16x32_bf16 v[2:5], v[182:185], v[214:217], v[2:5]
	v_mfma_f32_16x16x32_bf16 v[2:5], v[186:189], v[218:221], v[2:5]
	v_mfma_f32_16x16x32_bf16 v[10:13], v[154:157], v[218:221], v[10:13]
	v_mfma_f32_16x16x32_bf16 v[10:13], v[150:153], v[214:217], v[10:13]
	s_barrier
	v_add_u32_e32 v102, 0x18000, v172
	v_add_u32_e32 v146, 0x1c000, v172
	ds_read_b128 v[82:85], v102
	ds_read_b128 v[86:89], v102 offset:1024
	ds_read_b128 v[98:101], v102 offset:2048
	ds_read_b128 v[102:105], v102 offset:3072
	ds_read_b128 v[150:153], v146
	ds_read_b128 v[154:157], v146 offset:1024
	ds_read_b128 v[182:185], v146 offset:2048
	ds_read_b128 v[186:189], v146 offset:3072
	s_add_i32 s55, s55, 0x80000
	s_mov_b32 m0, s14
	ds_read_b128 v[190:193], v173 offset:32768
	ds_read_b128 v[194:197], v173 offset:33792
	ds_read_b128 v[198:201], v173 offset:34816
	ds_read_b128 v[202:205], v173 offset:35840
	ds_read_b128 v[206:209], v173 offset:36864
	ds_read_b128 v[210:213], v173 offset:37888
	ds_read_b128 v[214:217], v173 offset:38912
	ds_read_b128 v[218:221], v173 offset:39936
	buffer_load_dwordx4 v159, s[76:79], s55 offen lds
	s_mov_b32 m0, s15
	s_nop 0
	buffer_load_dwordx4 v163, s[76:79], s55 offen lds
	s_waitcnt vmcnt(8)
	s_waitcnt lgkmcnt(0)
	s_barrier
; #define PG8_STAGEX(rs, bufoff, soff, voff) do { _Pragma("unroll") for (int _i = 0; _i < 2; ++_i) \
;         __builtin_amdgcn_raw_ptr_buffer_load_lds(rs, (LAS unsigned*)(lds + (bufoff) + ldsw + _i * 8192), 16, (voff)[_i], (soff), 0, 0); } while (0)
; #define PG8_LDA(dst, b, h) do { _Pragma("unroll") for (int m = 0; m < 4; ++m) _Pragma("unroll") for (int k = 0; k < 2; ++k) dst[m][k] = *(const LAS bf16x8*)(lds + PG8_SA(b, h) + aoff + m * 2048 + k * 1024); } while (0)
; #define PG8_WAIT_V(n) asm volatile("s_waitcnt vmcnt(" #n ")" ::: "memory")
; #define PG8_WAIT_L(n) asm volatile("s_waitcnt lgkmcnt(" #n ")" ::: "memory")
; #define PG8_BAR __builtin_amdgcn_s_barrier()
; #define PG8_SCHED __builtin_amdgcn_sched_barrier(0)
;     ...
;             PG8_WAIT_V(8); PG8_WAIT_L(0); PG8_BAR; PG8_MMA(0, 0, At, B0); PG8_MMA(0, 1, At, B1); PG8_BAR; PG8_SCHED;
;             PG8_LDA(At, 1, 1); PG8_STAGEX(rsB, PG8_SB(1, 0), b3, voffB); PG8_STAGEX(rsB, PG8_SB(1, 1), b3 + hstepB, voffB); PG8_STAGEX(rsA, PG8_SA(1, 0), a3, voffA);
;             PG8_WAIT_V(8); PG8_WAIT_L(0); PG8_BAR; PG8_MMA(1, 0, At, B0); PG8_MMA(1, 1, At, B1); PG8_BAR; PG8_SCHED;
;         }
;     ...
;         if (wr == 0) PG8_BAR;
	v_mfma_f32_16x16x32_bf16 v[142:145], v[82:85], v[190:193], v[142:145]
	v_mfma_f32_16x16x32_bf16 v[142:145], v[86:89], v[194:197], v[142:145]
	v_mfma_f32_16x16x32_bf16 v[134:137], v[102:105], v[194:197], v[134:137]
	v_mfma_f32_16x16x32_bf16 v[134:137], v[98:101], v[190:193], v[134:137]
	v_mfma_f32_16x16x32_bf16 v[118:121], v[98:101], v[198:201], v[118:121]
	v_mfma_f32_16x16x32_bf16 v[118:121], v[102:105], v[202:205], v[118:121]
	v_mfma_f32_16x16x32_bf16 v[126:129], v[86:89], v[202:205], v[126:129]
	v_mfma_f32_16x16x32_bf16 v[126:129], v[82:85], v[198:201], v[126:129]
	v_mfma_f32_16x16x32_bf16 v[110:113], v[82:85], v[206:209], v[110:113]
	v_mfma_f32_16x16x32_bf16 v[110:113], v[86:89], v[210:213], v[110:113]
	v_mfma_f32_16x16x32_bf16 v[94:97], v[102:105], v[210:213], v[94:97]
	v_mfma_f32_16x16x32_bf16 v[94:97], v[98:101], v[206:209], v[94:97]
	v_mfma_f32_16x16x32_bf16 v[70:73], v[98:101], v[214:217], v[70:73]
	v_mfma_f32_16x16x32_bf16 v[70:73], v[102:105], v[218:221], v[70:73]
	v_mfma_f32_16x16x32_bf16 v[78:81], v[86:89], v[218:221], v[78:81]
	v_mfma_f32_16x16x32_bf16 v[78:81], v[82:85], v[214:217], v[78:81]
	v_mfma_f32_16x16x32_bf16 v[138:141], v[150:153], v[190:193], v[138:141]
	v_mfma_f32_16x16x32_bf16 v[138:141], v[154:157], v[194:197], v[138:141]
	v_mfma_f32_16x16x32_bf16 v[130:133], v[186:189], v[194:197], v[130:133]
	v_mfma_f32_16x16x32_bf16 v[130:133], v[182:185], v[190:193], v[130:133]
	v_mfma_f32_16x16x32_bf16 v[114:117], v[182:185], v[198:201], v[114:117]
	v_mfma_f32_16x16x32_bf16 v[114:117], v[186:189], v[202:205], v[114:117]
	v_mfma_f32_16x16x32_bf16 v[122:125], v[154:157], v[202:205], v[122:125]
	v_mfma_f32_16x16x32_bf16 v[122:125], v[150:153], v[198:201], v[122:125]
	v_mfma_f32_16x16x32_bf16 v[106:109], v[150:153], v[206:209], v[106:109]
	v_mfma_f32_16x16x32_bf16 v[106:109], v[154:157], v[210:213], v[106:109]
	v_mfma_f32_16x16x32_bf16 v[90:93], v[186:189], v[210:213], v[90:93]
	v_mfma_f32_16x16x32_bf16 v[90:93], v[182:185], v[206:209], v[90:93]
	v_mfma_f32_16x16x32_bf16 v[66:69], v[182:185], v[214:217], v[66:69]
	v_mfma_f32_16x16x32_bf16 v[66:69], v[186:189], v[218:221], v[66:69]
	v_mfma_f32_16x16x32_bf16 v[74:77], v[154:157], v[218:221], v[74:77]
	v_mfma_f32_16x16x32_bf16 v[74:77], v[150:153], v[214:217], v[74:77]
	s_barrier
	s_mov_b32 m0, s16
	s_or_b32 s55, s54, 0x80
	ds_read_b128 v[190:193], v173 offset:49152
	ds_read_b128 v[194:197], v173 offset:50176
	ds_read_b128 v[198:201], v173 offset:51200
	ds_read_b128 v[202:205], v173 offset:52224
	ds_read_b128 v[206:209], v173 offset:53248
	ds_read_b128 v[210:213], v173 offset:54272
	ds_read_b128 v[214:217], v173 offset:55296
	ds_read_b128 v[218:221], v173 offset:56320
	buffer_load_dwordx4 v161, s[40:43], s55 offen lds
	s_mov_b32 m0, s17
	s_add_i32 s54, s54, 0x80080
	buffer_load_dwordx4 v165, s[40:43], s55 offen lds
	s_mov_b32 m0, s20
	s_nop 0
	buffer_load_dwordx4 v161, s[40:43], s54 offen lds
	s_mov_b32 m0, s21
	s_nop 0
	buffer_load_dwordx4 v165, s[40:43], s54 offen lds
	s_mov_b32 m0, s18
	s_nop 0
	buffer_load_dwordx4 v159, s[76:79], s53 offen lds
	s_mov_b32 m0, s19
	s_nop 0
	buffer_load_dwordx4 v163, s[76:79], s53 offen lds
	s_waitcnt vmcnt(8)
	s_waitcnt lgkmcnt(0)
	s_barrier
	v_mfma_f32_16x16x32_bf16 v[62:65], v[82:85], v[190:193], v[62:65]
	v_mfma_f32_16x16x32_bf16 v[62:65], v[86:89], v[194:197], v[62:65]
	v_mfma_f32_16x16x32_bf16 v[54:57], v[102:105], v[194:197], v[54:57]
	v_mfma_f32_16x16x32_bf16 v[54:57], v[98:101], v[190:193], v[54:57]
	v_mfma_f32_16x16x32_bf16 v[38:41], v[98:101], v[198:201], v[38:41]
	v_mfma_f32_16x16x32_bf16 v[38:41], v[102:105], v[202:205], v[38:41]
	v_mfma_f32_16x16x32_bf16 v[46:49], v[86:89], v[202:205], v[46:49]
	v_mfma_f32_16x16x32_bf16 v[46:49], v[82:85], v[198:201], v[46:49]
	v_mfma_f32_16x16x32_bf16 v[30:33], v[82:85], v[206:209], v[30:33]
	v_mfma_f32_16x16x32_bf16 v[30:33], v[86:89], v[210:213], v[30:33]
	v_mfma_f32_16x16x32_bf16 v[22:25], v[102:105], v[210:213], v[22:25]
	v_mfma_f32_16x16x32_bf16 v[22:25], v[98:101], v[206:209], v[22:25]
	v_mfma_f32_16x16x32_bf16 v[6:9], v[98:101], v[214:217], v[6:9]
	v_mfma_f32_16x16x32_bf16 v[6:9], v[102:105], v[218:221], v[6:9]
	v_mfma_f32_16x16x32_bf16 v[14:17], v[86:89], v[218:221], v[14:17]
	v_mfma_f32_16x16x32_bf16 v[14:17], v[82:85], v[214:217], v[14:17]
	v_mfma_f32_16x16x32_bf16 v[58:61], v[150:153], v[190:193], v[58:61]
	v_mfma_f32_16x16x32_bf16 v[58:61], v[154:157], v[194:197], v[58:61]
	v_mfma_f32_16x16x32_bf16 v[50:53], v[186:189], v[194:197], v[50:53]
	v_mfma_f32_16x16x32_bf16 v[50:53], v[182:185], v[190:193], v[50:53]
	v_mfma_f32_16x16x32_bf16 v[34:37], v[182:185], v[198:201], v[34:37]
	v_mfma_f32_16x16x32_bf16 v[34:37], v[186:189], v[202:205], v[34:37]
	v_mfma_f32_16x16x32_bf16 v[42:45], v[154:157], v[202:205], v[42:45]
	v_mfma_f32_16x16x32_bf16 v[42:45], v[150:153], v[198:201], v[42:45]
	v_mfma_f32_16x16x32_bf16 v[26:29], v[150:153], v[206:209], v[26:29]
	v_mfma_f32_16x16x32_bf16 v[26:29], v[154:157], v[210:213], v[26:29]
	v_mfma_f32_16x16x32_bf16 v[18:21], v[186:189], v[210:213], v[18:21]
	v_mfma_f32_16x16x32_bf16 v[18:21], v[182:185], v[206:209], v[18:21]
	v_mfma_f32_16x16x32_bf16 v[2:5], v[182:185], v[214:217], v[2:5]
	v_mfma_f32_16x16x32_bf16 v[2:5], v[186:189], v[218:221], v[2:5]
	v_mfma_f32_16x16x32_bf16 v[10:13], v[154:157], v[218:221], v[10:13]
	v_mfma_f32_16x16x32_bf16 v[10:13], v[150:153], v[214:217], v[10:13]
	s_barrier
	s_add_i32 s52, s52, 2
	s_addk_i32 s50, 0x100
	s_addk_i32 s51, 0x100
	s_cmp_gt_u32 s52, 29
	s_cbranch_scc0 .LBB0_223
	s_setprio 0
	s_and_b64 vcc, exec, s[46:47]
	s_cbranch_vccz .LBB0_226
	s_barrier

;     ...
;         bool has_next; if constexpr (QV == 2) has_next = S.next_tail(ui + 1, nxt); else has_next = S.next(ui + 1, nxt);
;         const unsigned nA = has_next ? (unsigned)nxt.pm * tstepA + nxt.aoff : cA, nB = has_next ? (unsigned)nxt.pn * tstepB + nxt.boff : cB;
;         if constexpr (QV == 0) {
; #pragma nounroll
;         for (int t = 0; t < nt; t += 2) {
;             const bool last = (t == nt - 2);
;             const unsigned a1 = cA + (unsigned)(t + 1) * kstep;
;             const unsigned a2 = last ? nA : cA + (unsigned)(t + 2) * kstep, b2 = last ? nB : cB + (unsigned)(t + 2) * kstep;
;             const unsigned a3 = a2 + kstep, b3 = b2 + kstep;
;     ...
;         if (!cur.keep) {
; #pragma unroll
;             for (int a = 0; a < 2; ++a)
; #pragma unroll
;                 for (int b = 0; b < 2; ++b)
; #pragma unroll
;                     for (int m = 0; m < 4; ++m)
; #pragma unroll
;                         for (int n = 0; n < 2; ++n) { f32x2 z0, z1; asm("v_mov_b64 %0, 0\n\tv_mov_b64 %1, 0" : "=v"(z0), "=v"(z1));
;                     acc[a][b][m][n] = __builtin_shufflevector(z0, z1, 0, 1, 2, 3); }
.LBB0_322:
	s_mul_i32 s74, s58, 0x2b0000
	s_and_b64 s[30:31], s[52:53], exec
	s_mul_i32 s75, s43, 0x2b0000
	s_waitcnt lgkmcnt(0)
	v_mov_b64_e32 v[8:9], v[4:5]
	v_mov_b64_e32 v[12:13], v[4:5]
	v_mov_b64_e32 v[16:17], v[4:5]
	v_mov_b64_e32 v[20:21], v[4:5]
	v_mov_b64_e32 v[24:25], v[4:5]
	s_waitcnt vmcnt(15)
	v_mov_b64_e32 v[28:29], v[4:5]
	v_mov_b64_e32 v[32:33], v[4:5]
	v_mov_b64_e32 v[68:69], v[4:5]
	v_mov_b64_e32 v[72:73], v[4:5]
	v_mov_b64_e32 v[76:77], v[4:5]
	v_mov_b64_e32 v[80:81], v[4:5]
	v_mov_b64_e32 v[84:85], v[4:5]
	v_mov_b64_e32 v[88:89], v[4:5]
	v_mov_b64_e32 v[92:93], v[4:5]
	v_mov_b64_e32 v[96:97], v[4:5]
	v_mov_b64_e32 v[36:37], v[4:5]
	v_mov_b64_e32 v[40:41], v[4:5]
	v_mov_b64_e32 v[44:45], v[4:5]
	v_mov_b64_e32 v[48:49], v[4:5]
	v_mov_b64_e32 v[52:53], v[4:5]
	v_mov_b64_e32 v[56:57], v[4:5]
	v_mov_b64_e32 v[60:61], v[4:5]
	v_mov_b64_e32 v[64:65], v[4:5]
	v_mov_b64_e32 v[100:101], v[4:5]
	v_mov_b64_e32 v[104:105], v[4:5]
	v_mov_b64_e32 v[128:129], v[4:5]
	v_mov_b64_e32 v[132:133], v[4:5]
	v_mov_b64_e32 v[140:141], v[4:5]
	v_mov_b64_e32 v[144:145], v[4:5]
	v_mov_b64_e32 v[148:149], v[4:5]
	v_mov_b64_e32 v[152:153], v[4:5]
	s_mov_b32 s73, s58
	s_mov_b32 s72, s43
	s_cselect_b32 s30, s74, s51
	s_cselect_b32 s31, s75, s57
	s_add_i32 s51, s51, 0x158080
	s_addk_i32 s57, 0x100
	s_mov_b32 s58, -2
	v_mov_b64_e32 v[6:7], v[2:3]
	v_mov_b64_e32 v[10:11], v[2:3]
	v_mov_b64_e32 v[14:15], v[2:3]
	v_mov_b64_e32 v[18:19], v[2:3]
	v_mov_b64_e32 v[22:23], v[2:3]
	v_mov_b64_e32 v[26:27], v[2:3]
	v_mov_b64_e32 v[30:31], v[2:3]
	v_mov_b64_e32 v[66:67], v[2:3]
	v_mov_b64_e32 v[70:71], v[2:3]
	v_mov_b64_e32 v[74:75], v[2:3]
	v_mov_b64_e32 v[78:79], v[2:3]
	v_mov_b64_e32 v[82:83], v[2:3]
	v_mov_b64_e32 v[86:87], v[2:3]
	v_mov_b64_e32 v[90:91], v[2:3]
	v_mov_b64_e32 v[94:95], v[2:3]
	v_mov_b64_e32 v[34:35], v[2:3]
	v_mov_b64_e32 v[38:39], v[2:3]
	v_mov_b64_e32 v[42:43], v[2:3]
	v_mov_b64_e32 v[46:47], v[2:3]
	v_mov_b64_e32 v[50:51], v[2:3]
	v_mov_b64_e32 v[54:55], v[2:3]
	v_mov_b64_e32 v[58:59], v[2:3]
	v_mov_b64_e32 v[62:63], v[2:3]
	v_mov_b64_e32 v[98:99], v[2:3]
	v_mov_b64_e32 v[102:103], v[2:3]
	v_mov_b64_e32 v[126:127], v[2:3]
	v_mov_b64_e32 v[130:131], v[2:3]
	v_mov_b64_e32 v[138:139], v[2:3]
	v_mov_b64_e32 v[142:143], v[2:3]
	v_mov_b64_e32 v[146:147], v[2:3]
	v_mov_b64_e32 v[150:151], v[2:3]
	s_and_b64 vcc, exec, s[46:47]
	s_cbranch_vccz .Lsp_323
	s_setprio 1

; #define PG8_STAGEX(rs, bufoff, soff, voff) do { _Pragma("unroll") for (int _i = 0; _i < 2; ++_i) \
;         __builtin_amdgcn_raw_ptr_buffer_load_lds(rs, (LAS unsigned*)(lds + (bufoff) + ldsw + _i * 8192), 16, (voff)[_i], (soff), 0, 0); } while (0)
; #define PG8_LDA(dst, b, h) do { _Pragma("unroll") for (int m = 0; m < 4; ++m) _Pragma("unroll") for (int k = 0; k < 2; ++k) dst[m][k] = *(const LAS bf16x8*)(lds + PG8_SA(b, h) + aoff + m * 2048 + k * 1024); } while (0)
; #define PG8_LDB(dst, b, h) do { _Pragma("unroll") for (int n = 0; n < 2; ++n) _Pragma("unroll") for (int k = 0; k < 2; ++k) dst[n][k] = *(const LAS bf16x8*)(lds + PG8_SB(b, h) + boff + n * 2048 + k * 1024); } while (0)
; #define PG8_WAIT_V(n) asm volatile("s_waitcnt vmcnt(" #n ")" ::: "memory")
; #define PG8_WAIT_L(n) asm volatile("s_waitcnt lgkmcnt(" #n ")" ::: "memory")
; #define PG8_BAR __builtin_amdgcn_s_barrier()
; #define PG8_SCHED __builtin_amdgcn_sched_barrier(0)
;     ...
;             PG8_LDB(B0, 0, 0); PG8_LDB(B1, 0, 1); PG8_SCHED; PG8_LDA(At, 0, 0); PG8_STAGEX(rsA, PG8_SA(1, 1), a1 + hstepA, voffA);
;             PG8_WAIT_V(8); PG8_WAIT_L(0); PG8_BAR; PG8_MMA(0, 0, At, B0); PG8_MMA(0, 1, At, B1); PG8_BAR; PG8_SCHED;
;             PG8_LDA(At, 0, 1); PG8_STAGEX(rsB, PG8_SB(0, 0), b2, voffB); PG8_STAGEX(rsB, PG8_SB(0, 1), b2 + hstepB, voffB); PG8_STAGEX(rsA, PG8_SA(0, 0), a2, voffA);
;             PG8_WAIT_V(8); PG8_WAIT_L(0); PG8_BAR; PG8_MMA(1, 0, At, B0); PG8_MMA(1, 1, At, B1); PG8_BAR; PG8_SCHED;
.LBB0_323:
	v_add_u32_e32 v118, 0x10000, v210
	v_add_u32_e32 v160, 0x14000, v210
	ds_read_b128 v[106:109], v118
	ds_read_b128 v[110:113], v118 offset:1024
	ds_read_b128 v[114:117], v118 offset:2048
	ds_read_b128 v[118:121], v118 offset:3072
	ds_read_b128 v[122:125], v160
	ds_read_b128 v[134:137], v160 offset:1024
	ds_read_b128 v[156:159], v160 offset:2048
	ds_read_b128 v[160:163], v160 offset:3072
	s_add_i32 s42, s51, 0xffea8080
	s_cmpk_eq_i32 s58, 0x52
	s_cselect_b32 s61, s30, s42
	s_cselect_b32 s60, s31, s57
	s_or_b32 s59, s61, 0x80
	s_mov_b32 m0, s68
	ds_read_b128 v[164:167], v211
	ds_read_b128 v[168:171], v211 offset:1024
	ds_read_b128 v[182:185], v211 offset:2048
	ds_read_b128 v[186:189], v211 offset:3072
	ds_read_b128 v[190:193], v211 offset:4096
	ds_read_b128 v[194:197], v211 offset:5120
	ds_read_b128 v[198:201], v211 offset:6144
	ds_read_b128 v[202:205], v211 offset:7168
	buffer_load_dwordx4 v178, s[76:79], s51 offen lds
	s_mov_b32 m0, s69
	s_nop 0
	buffer_load_dwordx4 v206, s[76:79], s51 offen lds
	s_waitcnt vmcnt(8)
	s_waitcnt lgkmcnt(0)
	s_barrier
	v_mfma_f32_16x16x32_bf16 v[150:153], v[106:109], v[164:167], v[150:153]
	v_mfma_f32_16x16x32_bf16 v[150:153], v[110:113], v[168:171], v[150:153]
	v_mfma_f32_16x16x32_bf16 v[146:149], v[118:121], v[168:171], v[146:149]
	v_mfma_f32_16x16x32_bf16 v[146:149], v[114:117], v[164:167], v[146:149]
	v_mfma_f32_16x16x32_bf16 v[138:141], v[114:117], v[182:185], v[138:141]
	v_mfma_f32_16x16x32_bf16 v[138:141], v[118:121], v[186:189], v[138:141]
	v_mfma_f32_16x16x32_bf16 v[142:145], v[110:113], v[186:189], v[142:145]
	v_mfma_f32_16x16x32_bf16 v[142:145], v[106:109], v[182:185], v[142:145]
	v_mfma_f32_16x16x32_bf16 v[130:133], v[106:109], v[190:193], v[130:133]
	v_mfma_f32_16x16x32_bf16 v[130:133], v[110:113], v[194:197], v[130:133]
	v_mfma_f32_16x16x32_bf16 v[126:129], v[118:121], v[194:197], v[126:129]
	v_mfma_f32_16x16x32_bf16 v[126:129], v[114:117], v[190:193], v[126:129]
	v_mfma_f32_16x16x32_bf16 v[98:101], v[114:117], v[198:201], v[98:101]
	v_mfma_f32_16x16x32_bf16 v[98:101], v[118:121], v[202:205], v[98:101]
	v_mfma_f32_16x16x32_bf16 v[102:105], v[110:113], v[202:205], v[102:105]
	v_mfma_f32_16x16x32_bf16 v[102:105], v[106:109], v[198:201], v[102:105]
	v_mfma_f32_16x16x32_bf16 v[62:65], v[122:125], v[164:167], v[62:65]
	v_mfma_f32_16x16x32_bf16 v[62:65], v[134:137], v[168:171], v[62:65]
	v_mfma_f32_16x16x32_bf16 v[58:61], v[160:163], v[168:171], v[58:61]
	v_mfma_f32_16x16x32_bf16 v[58:61], v[156:159], v[164:167], v[58:61]
	v_mfma_f32_16x16x32_bf16 v[50:53], v[156:159], v[182:185], v[50:53]
	v_mfma_f32_16x16x32_bf16 v[50:53], v[160:163], v[186:189], v[50:53]
	v_mfma_f32_16x16x32_bf16 v[54:57], v[134:137], v[186:189], v[54:57]
	v_mfma_f32_16x16x32_bf16 v[54:57], v[122:125], v[182:185], v[54:57]
	v_mfma_f32_16x16x32_bf16 v[46:49], v[122:125], v[190:193], v[46:49]
	v_mfma_f32_16x16x32_bf16 v[46:49], v[134:137], v[194:197], v[46:49]
	v_mfma_f32_16x16x32_bf16 v[42:45], v[160:163], v[194:197], v[42:45]
	v_mfma_f32_16x16x32_bf16 v[42:45], v[156:159], v[190:193], v[42:45]
	v_mfma_f32_16x16x32_bf16 v[34:37], v[156:159], v[198:201], v[34:37]
	v_mfma_f32_16x16x32_bf16 v[34:37], v[160:163], v[202:205], v[34:37]
	v_mfma_f32_16x16x32_bf16 v[38:41], v[134:137], v[202:205], v[38:41]
	v_mfma_f32_16x16x32_bf16 v[38:41], v[122:125], v[198:201], v[38:41]
	s_barrier
	s_mov_b32 m0, s15
	s_mov_b32 s42, s78
	s_mov_b32 s43, s79
	ds_read_b128 v[164:167], v211 offset:16384
	ds_read_b128 v[168:171], v211 offset:17408
	ds_read_b128 v[182:185], v211 offset:18432
	ds_read_b128 v[186:189], v211 offset:19456
	ds_read_b128 v[190:193], v211 offset:20480
	ds_read_b128 v[194:197], v211 offset:21504
	ds_read_b128 v[198:201], v211 offset:22528
	ds_read_b128 v[202:205], v211 offset:23552
	buffer_load_dwordx4 v179, s[40:43], s60 offen lds
	s_mov_b32 m0, s16
	s_add_i32 s62, s60, 0x158000
	buffer_load_dwordx4 v207, s[40:43], s60 offen lds
	s_mov_b32 m0, s17
	s_nop 0
	buffer_load_dwordx4 v179, s[40:43], s62 offen lds
	s_mov_b32 m0, s18
	s_nop 0
	buffer_load_dwordx4 v207, s[40:43], s62 offen lds
	s_mov_b32 m0, s14
	s_nop 0
	buffer_load_dwordx4 v178, s[76:79], s61 offen lds
	s_mov_b32 m0, s19
	s_nop 0
	buffer_load_dwordx4 v206, s[76:79], s61 offen lds
	s_waitcnt vmcnt(8)
	s_waitcnt lgkmcnt(0)
	s_barrier
	v_mfma_f32_16x16x32_bf16 v[94:97], v[106:109], v[164:167], v[94:97]
	v_mfma_f32_16x16x32_bf16 v[94:97], v[110:113], v[168:171], v[94:97]
	v_mfma_f32_16x16x32_bf16 v[90:93], v[118:121], v[168:171], v[90:93]
	v_mfma_f32_16x16x32_bf16 v[90:93], v[114:117], v[164:167], v[90:93]
	v_mfma_f32_16x16x32_bf16 v[82:85], v[114:117], v[182:185], v[82:85]
	v_mfma_f32_16x16x32_bf16 v[82:85], v[118:121], v[186:189], v[82:85]
	v_mfma_f32_16x16x32_bf16 v[86:89], v[110:113], v[186:189], v[86:89]
	v_mfma_f32_16x16x32_bf16 v[86:89], v[106:109], v[182:185], v[86:89]
	v_mfma_f32_16x16x32_bf16 v[78:81], v[106:109], v[190:193], v[78:81]
	v_mfma_f32_16x16x32_bf16 v[78:81], v[110:113], v[194:197], v[78:81]
	v_mfma_f32_16x16x32_bf16 v[74:77], v[118:121], v[194:197], v[74:77]
	v_mfma_f32_16x16x32_bf16 v[74:77], v[114:117], v[190:193], v[74:77]
	v_mfma_f32_16x16x32_bf16 v[66:69], v[114:117], v[198:201], v[66:69]
	v_mfma_f32_16x16x32_bf16 v[66:69], v[118:121], v[202:205], v[66:69]
	v_mfma_f32_16x16x32_bf16 v[70:73], v[110:113], v[202:205], v[70:73]
	v_mfma_f32_16x16x32_bf16 v[70:73], v[106:109], v[198:201], v[70:73]
	v_mfma_f32_16x16x32_bf16 v[30:33], v[122:125], v[164:167], v[30:33]
	v_mfma_f32_16x16x32_bf16 v[30:33], v[134:137], v[168:171], v[30:33]
	v_mfma_f32_16x16x32_bf16 v[26:29], v[160:163], v[168:171], v[26:29]
	v_mfma_f32_16x16x32_bf16 v[26:29], v[156:159], v[164:167], v[26:29]
	v_mfma_f32_16x16x32_bf16 v[18:21], v[156:159], v[182:185], v[18:21]
	v_mfma_f32_16x16x32_bf16 v[18:21], v[160:163], v[186:189], v[18:21]
	v_mfma_f32_16x16x32_bf16 v[22:25], v[134:137], v[186:189], v[22:25]
	v_mfma_f32_16x16x32_bf16 v[22:25], v[122:125], v[182:185], v[22:25]
	v_mfma_f32_16x16x32_bf16 v[14:17], v[122:125], v[190:193], v[14:17]
	v_mfma_f32_16x16x32_bf16 v[14:17], v[134:137], v[194:197], v[14:17]
	v_mfma_f32_16x16x32_bf16 v[10:13], v[160:163], v[194:197], v[10:13]
	v_mfma_f32_16x16x32_bf16 v[10:13], v[156:159], v[190:193], v[10:13]
	v_mfma_f32_16x16x32_bf16 v[2:5], v[156:159], v[198:201], v[2:5]
	v_mfma_f32_16x16x32_bf16 v[2:5], v[160:163], v[202:205], v[2:5]
	v_mfma_f32_16x16x32_bf16 v[6:9], v[134:137], v[202:205], v[6:9]
	v_mfma_f32_16x16x32_bf16 v[6:9], v[122:125], v[198:201], v[6:9]
	s_barrier
; #define PG8_STAGEX(rs, bufoff, soff, voff) do { _Pragma("unroll") for (int _i = 0; _i < 2; ++_i) \
;         __builtin_amdgcn_raw_ptr_buffer_load_lds(rs, (LAS unsigned*)(lds + (bufoff) + ldsw + _i * 8192), 16, (voff)[_i], (soff), 0, 0); } while (0)
; #define PG8_LDA(dst, b, h) do { _Pragma("unroll") for (int m = 0; m < 4; ++m) _Pragma("unroll") for (int k = 0; k < 2; ++k) dst[m][k] = *(const LAS bf16x8*)(lds + PG8_SA(b, h) + aoff + m * 2048 + k * 1024); } while (0)
; #define PG8_LDB(dst, b, h) do { _Pragma("unroll") for (int n = 0; n < 2; ++n) _Pragma("unroll") for (int k = 0; k < 2; ++k) dst[n][k] = *(const LAS bf16x8*)(lds + PG8_SB(b, h) + boff + n * 2048 + k * 1024); } while (0)
; #define PG8_WAIT_V(n) asm volatile("s_waitcnt vmcnt(" #n ")" ::: "memory")
; #define PG8_WAIT_L(n) asm volatile("s_waitcnt lgkmcnt(" #n ")" ::: "memory")
; #define PG8_BAR __builtin_amdgcn_s_barrier()
; #define PG8_SCHED __builtin_amdgcn_sched_barrier(0)
;     ...
;             PG8_LDB(B0, 1, 0); PG8_LDB(B1, 1, 1); PG8_SCHED; PG8_LDA(At, 1, 0); PG8_STAGEX(rsA, PG8_SA(0, 1), a2 + hstepA, voffA);
;             PG8_WAIT_V(8); PG8_WAIT_L(0); PG8_BAR; PG8_MMA(0, 0, At, B0); PG8_MMA(0, 1, At, B1); PG8_BAR; PG8_SCHED;
;             PG8_LDA(At, 1, 1); PG8_STAGEX(rsB, PG8_SB(1, 0), b3, voffB); PG8_STAGEX(rsB, PG8_SB(1, 1), b3 + hstepB, voffB); PG8_STAGEX(rsA, PG8_SA(1, 0), a3, voffA);
;             PG8_WAIT_V(8); PG8_WAIT_L(0); PG8_BAR; PG8_MMA(1, 0, At, B0); PG8_MMA(1, 1, At, B1); PG8_BAR; PG8_SCHED;
;         }
;     ...
;         if (wr == 0) PG8_BAR;
	v_add_u32_e32 v118, 0x18000, v210
	v_add_u32_e32 v160, 0x1c000, v210
	ds_read_b128 v[106:109], v118
	ds_read_b128 v[110:113], v118 offset:1024
	ds_read_b128 v[114:117], v118 offset:2048
	ds_read_b128 v[118:121], v118 offset:3072
	ds_read_b128 v[122:125], v160
	ds_read_b128 v[134:137], v160 offset:1024
	ds_read_b128 v[156:159], v160 offset:2048
	ds_read_b128 v[160:163], v160 offset:3072
	s_add_i32 s61, s61, 0x158000
	s_mov_b32 m0, s20
	ds_read_b128 v[164:167], v211 offset:32768
	ds_read_b128 v[168:171], v211 offset:33792
	ds_read_b128 v[182:185], v211 offset:34816
	ds_read_b128 v[186:189], v211 offset:35840
	ds_read_b128 v[190:193], v211 offset:36864
	ds_read_b128 v[194:197], v211 offset:37888
	ds_read_b128 v[198:201], v211 offset:38912
	ds_read_b128 v[202:205], v211 offset:39936
	buffer_load_dwordx4 v178, s[76:79], s61 offen lds
	s_mov_b32 m0, s21
	s_nop 0
	buffer_load_dwordx4 v206, s[76:79], s61 offen lds
	s_waitcnt vmcnt(8)
	s_waitcnt lgkmcnt(0)
	s_barrier
	v_mfma_f32_16x16x32_bf16 v[150:153], v[106:109], v[164:167], v[150:153]
	v_mfma_f32_16x16x32_bf16 v[150:153], v[110:113], v[168:171], v[150:153]
	v_mfma_f32_16x16x32_bf16 v[146:149], v[118:121], v[168:171], v[146:149]
	v_mfma_f32_16x16x32_bf16 v[146:149], v[114:117], v[164:167], v[146:149]
	v_mfma_f32_16x16x32_bf16 v[138:141], v[114:117], v[182:185], v[138:141]
	v_mfma_f32_16x16x32_bf16 v[138:141], v[118:121], v[186:189], v[138:141]
	v_mfma_f32_16x16x32_bf16 v[142:145], v[110:113], v[186:189], v[142:145]
	v_mfma_f32_16x16x32_bf16 v[142:145], v[106:109], v[182:185], v[142:145]
	v_mfma_f32_16x16x32_bf16 v[130:133], v[106:109], v[190:193], v[130:133]
	v_mfma_f32_16x16x32_bf16 v[130:133], v[110:113], v[194:197], v[130:133]
	v_mfma_f32_16x16x32_bf16 v[126:129], v[118:121], v[194:197], v[126:129]
	v_mfma_f32_16x16x32_bf16 v[126:129], v[114:117], v[190:193], v[126:129]
	v_mfma_f32_16x16x32_bf16 v[98:101], v[114:117], v[198:201], v[98:101]
	v_mfma_f32_16x16x32_bf16 v[98:101], v[118:121], v[202:205], v[98:101]
	v_mfma_f32_16x16x32_bf16 v[102:105], v[110:113], v[202:205], v[102:105]
	v_mfma_f32_16x16x32_bf16 v[102:105], v[106:109], v[198:201], v[102:105]
	v_mfma_f32_16x16x32_bf16 v[62:65], v[122:125], v[164:167], v[62:65]
	v_mfma_f32_16x16x32_bf16 v[62:65], v[134:137], v[168:171], v[62:65]
	v_mfma_f32_16x16x32_bf16 v[58:61], v[160:163], v[168:171], v[58:61]
	v_mfma_f32_16x16x32_bf16 v[58:61], v[156:159], v[164:167], v[58:61]
	v_mfma_f32_16x16x32_bf16 v[50:53], v[156:159], v[182:185], v[50:53]
	v_mfma_f32_16x16x32_bf16 v[50:53], v[160:163], v[186:189], v[50:53]
	v_mfma_f32_16x16x32_bf16 v[54:57], v[134:137], v[186:189], v[54:57]
	v_mfma_f32_16x16x32_bf16 v[54:57], v[122:125], v[182:185], v[54:57]
	v_mfma_f32_16x16x32_bf16 v[46:49], v[122:125], v[190:193], v[46:49]
	v_mfma_f32_16x16x32_bf16 v[46:49], v[134:137], v[194:197], v[46:49]
	v_mfma_f32_16x16x32_bf16 v[42:45], v[160:163], v[194:197], v[42:45]
	v_mfma_f32_16x16x32_bf16 v[42:45], v[156:159], v[190:193], v[42:45]
	v_mfma_f32_16x16x32_bf16 v[34:37], v[156:159], v[198:201], v[34:37]
	v_mfma_f32_16x16x32_bf16 v[34:37], v[160:163], v[202:205], v[34:37]
	v_mfma_f32_16x16x32_bf16 v[38:41], v[134:137], v[202:205], v[38:41]
	v_mfma_f32_16x16x32_bf16 v[38:41], v[122:125], v[198:201], v[38:41]
	s_barrier
	s_mov_b32 m0, s28
	s_or_b32 s61, s60, 0x80
	ds_read_b128 v[164:167], v211 offset:49152
	ds_read_b128 v[168:171], v211 offset:50176
	ds_read_b128 v[182:185], v211 offset:51200
	ds_read_b128 v[186:189], v211 offset:52224
	ds_read_b128 v[190:193], v211 offset:53248
	ds_read_b128 v[194:197], v211 offset:54272
	ds_read_b128 v[198:201], v211 offset:55296
	ds_read_b128 v[202:205], v211 offset:56320
	buffer_load_dwordx4 v179, s[40:43], s61 offen lds
	s_mov_b32 m0, s29
	s_add_i32 s60, s60, 0x158080
	buffer_load_dwordx4 v207, s[40:43], s61 offen lds
	s_mov_b32 m0, s66
	s_nop 0
	buffer_load_dwordx4 v179, s[40:43], s60 offen lds
	s_mov_b32 m0, s67
	s_nop 0
	buffer_load_dwordx4 v207, s[40:43], s60 offen lds
	s_mov_b32 m0, s54
	s_nop 0
	buffer_load_dwordx4 v178, s[76:79], s59 offen lds
	s_mov_b32 m0, s55
	s_nop 0
	buffer_load_dwordx4 v206, s[76:79], s59 offen lds
	s_waitcnt vmcnt(8)
	s_waitcnt lgkmcnt(0)
	s_barrier
	v_mfma_f32_16x16x32_bf16 v[94:97], v[106:109], v[164:167], v[94:97]
	v_mfma_f32_16x16x32_bf16 v[94:97], v[110:113], v[168:171], v[94:97]
	v_mfma_f32_16x16x32_bf16 v[90:93], v[118:121], v[168:171], v[90:93]
	v_mfma_f32_16x16x32_bf16 v[90:93], v[114:117], v[164:167], v[90:93]
	v_mfma_f32_16x16x32_bf16 v[82:85], v[114:117], v[182:185], v[82:85]
	v_mfma_f32_16x16x32_bf16 v[82:85], v[118:121], v[186:189], v[82:85]
	v_mfma_f32_16x16x32_bf16 v[86:89], v[110:113], v[186:189], v[86:89]
	v_mfma_f32_16x16x32_bf16 v[86:89], v[106:109], v[182:185], v[86:89]
	v_mfma_f32_16x16x32_bf16 v[78:81], v[106:109], v[190:193], v[78:81]
	v_mfma_f32_16x16x32_bf16 v[78:81], v[110:113], v[194:197], v[78:81]
	v_mfma_f32_16x16x32_bf16 v[74:77], v[118:121], v[194:197], v[74:77]
	v_mfma_f32_16x16x32_bf16 v[74:77], v[114:117], v[190:193], v[74:77]
	v_mfma_f32_16x16x32_bf16 v[66:69], v[114:117], v[198:201], v[66:69]
	v_mfma_f32_16x16x32_bf16 v[66:69], v[118:121], v[202:205], v[66:69]
	v_mfma_f32_16x16x32_bf16 v[70:73], v[110:113], v[202:205], v[70:73]
	v_mfma_f32_16x16x32_bf16 v[70:73], v[106:109], v[198:201], v[70:73]
	v_mfma_f32_16x16x32_bf16 v[30:33], v[122:125], v[164:167], v[30:33]
	v_mfma_f32_16x16x32_bf16 v[30:33], v[134:137], v[168:171], v[30:33]
	v_mfma_f32_16x16x32_bf16 v[26:29], v[160:163], v[168:171], v[26:29]
	v_mfma_f32_16x16x32_bf16 v[26:29], v[156:159], v[164:167], v[26:29]
	v_mfma_f32_16x16x32_bf16 v[18:21], v[156:159], v[182:185], v[18:21]
	v_mfma_f32_16x16x32_bf16 v[18:21], v[160:163], v[186:189], v[18:21]
	v_mfma_f32_16x16x32_bf16 v[22:25], v[134:137], v[186:189], v[22:25]
	v_mfma_f32_16x16x32_bf16 v[22:25], v[122:125], v[182:185], v[22:25]
	v_mfma_f32_16x16x32_bf16 v[14:17], v[122:125], v[190:193], v[14:17]
	v_mfma_f32_16x16x32_bf16 v[14:17], v[134:137], v[194:197], v[14:17]
	v_mfma_f32_16x16x32_bf16 v[10:13], v[160:163], v[194:197], v[10:13]
	v_mfma_f32_16x16x32_bf16 v[10:13], v[156:159], v[190:193], v[10:13]
	v_mfma_f32_16x16x32_bf16 v[2:5], v[156:159], v[198:201], v[2:5]
	v_mfma_f32_16x16x32_bf16 v[2:5], v[160:163], v[202:205], v[2:5]
	v_mfma_f32_16x16x32_bf16 v[6:9], v[134:137], v[202:205], v[6:9]
	v_mfma_f32_16x16x32_bf16 v[6:9], v[122:125], v[198:201], v[6:9]
	s_barrier
	s_add_i32 s58, s58, 2
	s_addk_i32 s51, 0x100
	s_addk_i32 s57, 0x100
	s_cmpk_gt_u32 s58, 0x53
	s_cbranch_scc0 .LBB0_323
	s_setprio 0
	s_and_b64 vcc, exec, s[48:49]
	s_cbranch_vccz .LBB0_326
	s_barrier

;     ...
;         bool has_next; if constexpr (QV == 2) has_next = S.next_tail(ui + 1, nxt); else has_next = S.next(ui + 1, nxt);
;         const unsigned nA = has_next ? (unsigned)nxt.pm * tstepA + nxt.aoff : cA, nB = has_next ? (unsigned)nxt.pn * tstepB + nxt.boff : cB;
;         if constexpr (QV == 0) {
; #pragma nounroll
;         for (int t = 0; t < nt; t += 2) {
;             const bool last = (t == nt - 2);
;             const unsigned a1 = cA + (unsigned)(t + 1) * kstep;
;             const unsigned a2 = last ? nA : cA + (unsigned)(t + 2) * kstep, b2 = last ? nB : cB + (unsigned)(t + 2) * kstep;
;             const unsigned a3 = a2 + kstep, b3 = b2 + kstep;
;     ...
;         if (!cur.keep) {
; #pragma unroll
;             for (int a = 0; a < 2; ++a)
; #pragma unroll
;                 for (int b = 0; b < 2; ++b)
; #pragma unroll
;                     for (int m = 0; m < 4; ++m)
; #pragma unroll
;                         for (int n = 0; n < 2; ++n) { f32x2 z0, z1; asm("v_mov_b64 %0, 0\n\tv_mov_b64 %1, 0" : "=v"(z0), "=v"(z1));
;                     acc[a][b][m][n] = __builtin_shufflevector(z0, z1, 0, 1, 2, 3); }
.LBB0_436:
	s_lshl_b32 s26, s25, 20
	s_and_b64 s[30:31], s[48:49], exec
	s_cselect_b32 s2, s26, s7
	s_lshl_b32 s27, s24, 20
	s_and_b64 s[30:31], s[48:49], exec
	s_waitcnt vmcnt(15)
	v_mov_b64_e32 v[28:29], v[8:9]
	v_mov_b64_e32 v[2:3], v[6:7]
	v_mov_b64_e32 v[20:21], v[8:9]
	v_mov_b64_e32 v[12:13], v[8:9]
	v_mov_b64_e32 v[24:25], v[8:9]
	v_mov_b64_e32 v[16:17], v[8:9]
	v_mov_b64_e32 v[32:33], v[8:9]
	v_mov_b64_e32 v[76:77], v[8:9]
	v_mov_b64_e32 v[92:93], v[8:9]
	v_mov_b64_e32 v[68:69], v[8:9]
	v_mov_b64_e32 v[84:85], v[8:9]
	v_mov_b64_e32 v[72:73], v[8:9]
	v_mov_b64_e32 v[88:89], v[8:9]
	v_mov_b64_e32 v[80:81], v[8:9]
	v_mov_b64_e32 v[96:97], v[8:9]
	v_mov_b64_e32 v[44:45], v[8:9]
	v_mov_b64_e32 v[60:61], v[8:9]
	v_mov_b64_e32 v[36:37], v[8:9]
	v_mov_b64_e32 v[52:53], v[8:9]
	v_mov_b64_e32 v[40:41], v[8:9]
	v_mov_b64_e32 v[56:57], v[8:9]
	v_mov_b64_e32 v[48:49], v[8:9]
	v_mov_b64_e32 v[64:65], v[8:9]
	v_mov_b64_e32 v[108:109], v[8:9]
	v_mov_b64_e32 v[124:125], v[8:9]
	v_mov_b64_e32 v[100:101], v[8:9]
	v_mov_b64_e32 v[116:117], v[8:9]
	v_mov_b64_e32 v[104:105], v[8:9]
	v_mov_b64_e32 v[120:121], v[8:9]
	v_mov_b64_e32 v[112:113], v[8:9]
	v_mov_b64_e32 v[128:129], v[8:9]
	s_cselect_b32 s5, s27, s28
	s_add_i32 s7, s7, 0x80080
	s_addk_i32 s28, 0x100
	s_mov_b32 s29, -2
	v_mov_b64_e32 v[26:27], v[6:7]
	v_mov_b64_e32 v[4:5], v[8:9]
	v_mov_b64_e32 v[18:19], v[6:7]
	v_mov_b64_e32 v[10:11], v[6:7]
	v_mov_b64_e32 v[22:23], v[6:7]
	v_mov_b64_e32 v[14:15], v[6:7]
	v_mov_b64_e32 v[30:31], v[6:7]
	v_mov_b64_e32 v[74:75], v[6:7]
	v_mov_b64_e32 v[90:91], v[6:7]
	v_mov_b64_e32 v[66:67], v[6:7]
	v_mov_b64_e32 v[82:83], v[6:7]
	v_mov_b64_e32 v[70:71], v[6:7]
	v_mov_b64_e32 v[86:87], v[6:7]
	v_mov_b64_e32 v[78:79], v[6:7]
	v_mov_b64_e32 v[94:95], v[6:7]
	v_mov_b64_e32 v[42:43], v[6:7]
	v_mov_b64_e32 v[58:59], v[6:7]
	v_mov_b64_e32 v[34:35], v[6:7]
	v_mov_b64_e32 v[50:51], v[6:7]
	v_mov_b64_e32 v[38:39], v[6:7]
	v_mov_b64_e32 v[54:55], v[6:7]
	v_mov_b64_e32 v[46:47], v[6:7]
	v_mov_b64_e32 v[62:63], v[6:7]
	v_mov_b64_e32 v[106:107], v[6:7]
	v_mov_b64_e32 v[122:123], v[6:7]
	v_mov_b64_e32 v[98:99], v[6:7]
	v_mov_b64_e32 v[114:115], v[6:7]
	v_mov_b64_e32 v[102:103], v[6:7]
	v_mov_b64_e32 v[118:119], v[6:7]
	v_mov_b64_e32 v[110:111], v[6:7]
	v_mov_b64_e32 v[126:127], v[6:7]
	s_and_b64 vcc, exec, s[70:71]
	s_cbranch_vccz .Lsp_437
	s_setprio 1

; #define PG8_STAGEX(rs, bufoff, soff, voff) do { _Pragma("unroll") for (int _i = 0; _i < 2; ++_i) \
;         __builtin_amdgcn_raw_ptr_buffer_load_lds(rs, (LAS unsigned*)(lds + (bufoff) + ldsw + _i * 8192), 16, (voff)[_i], (soff), 0, 0); } while (0)
; #define PG8_LDA(dst, b, h) do { _Pragma("unroll") for (int m = 0; m < 4; ++m) _Pragma("unroll") for (int k = 0; k < 2; ++k) dst[m][k] = *(const LAS bf16x8*)(lds + PG8_SA(b, h) + aoff + m * 2048 + k * 1024); } while (0)
; #define PG8_LDB(dst, b, h) do { _Pragma("unroll") for (int n = 0; n < 2; ++n) _Pragma("unroll") for (int k = 0; k < 2; ++k) dst[n][k] = *(const LAS bf16x8*)(lds + PG8_SB(b, h) + boff + n * 2048 + k * 1024); } while (0)
; #define PG8_WAIT_V(n) asm volatile("s_waitcnt vmcnt(" #n ")" ::: "memory")
; #define PG8_WAIT_L(n) asm volatile("s_waitcnt lgkmcnt(" #n ")" ::: "memory")
; #define PG8_BAR __builtin_amdgcn_s_barrier()
; #define PG8_SCHED __builtin_amdgcn_sched_barrier(0)
;     ...
;             PG8_LDB(B0, 0, 0); PG8_LDB(B1, 0, 1); PG8_SCHED; PG8_LDA(At, 0, 0); PG8_STAGEX(rsA, PG8_SA(1, 1), a1 + hstepA, voffA);
;             PG8_WAIT_V(8); PG8_WAIT_L(0); PG8_BAR; PG8_MMA(0, 0, At, B0); PG8_MMA(0, 1, At, B1); PG8_BAR; PG8_SCHED;
;             PG8_LDA(At, 0, 1); PG8_STAGEX(rsB, PG8_SB(0, 0), b2, voffB); PG8_STAGEX(rsB, PG8_SB(0, 1), b2 + hstepB, voffB); PG8_STAGEX(rsA, PG8_SA(0, 0), a2, voffA);
;             PG8_WAIT_V(8); PG8_WAIT_L(0); PG8_BAR; PG8_MMA(1, 0, At, B0); PG8_MMA(1, 1, At, B1); PG8_BAR; PG8_SCHED;
.LBB0_437:
	v_add_u32_e32 v142, 0x10000, v220
	v_add_u32_e32 v158, 0x14000, v220
	ds_read_b128 v[130:133], v142
	ds_read_b128 v[134:137], v142 offset:1024
	ds_read_b128 v[138:141], v142 offset:2048
	ds_read_b128 v[142:145], v142 offset:3072
	ds_read_b128 v[146:149], v158
	ds_read_b128 v[150:153], v158 offset:1024
	ds_read_b128 v[154:157], v158 offset:2048
	ds_read_b128 v[158:161], v158 offset:3072
	s_add_i32 s30, s7, 0xfff80080
	s_cmp_eq_u32 s29, 28
	s_cselect_b32 s50, s2, s30
	s_cselect_b32 s31, s5, s28
	s_or_b32 s30, s50, 0x80
	s_mov_b32 m0, s20
	ds_read_b128 v[162:165], v221
	ds_read_b128 v[170:173], v221 offset:1024
	ds_read_b128 v[182:185], v221 offset:2048
	ds_read_b128 v[186:189], v221 offset:3072
	ds_read_b128 v[190:193], v221 offset:4096
	ds_read_b128 v[194:197], v221 offset:5120
	ds_read_b128 v[198:201], v221 offset:6144
	ds_read_b128 v[202:205], v221 offset:7168
	buffer_load_dwordx4 v178, s[76:79], s7 offen lds
	s_mov_b32 m0, s22
	s_nop 0
	buffer_load_dwordx4 v210, s[76:79], s7 offen lds
	s_waitcnt vmcnt(8)
	s_waitcnt lgkmcnt(0)
	s_barrier
	v_mfma_f32_16x16x32_bf16 v[126:129], v[130:133], v[162:165], v[126:129]
	v_mfma_f32_16x16x32_bf16 v[126:129], v[134:137], v[170:173], v[126:129]
	v_mfma_f32_16x16x32_bf16 v[110:113], v[142:145], v[170:173], v[110:113]
	v_mfma_f32_16x16x32_bf16 v[110:113], v[138:141], v[162:165], v[110:113]
	v_mfma_f32_16x16x32_bf16 v[102:105], v[138:141], v[182:185], v[102:105]
	v_mfma_f32_16x16x32_bf16 v[102:105], v[142:145], v[186:189], v[102:105]
	v_mfma_f32_16x16x32_bf16 v[118:121], v[134:137], v[186:189], v[118:121]
	v_mfma_f32_16x16x32_bf16 v[118:121], v[130:133], v[182:185], v[118:121]
	v_mfma_f32_16x16x32_bf16 v[114:117], v[130:133], v[190:193], v[114:117]
	v_mfma_f32_16x16x32_bf16 v[114:117], v[134:137], v[194:197], v[114:117]
	v_mfma_f32_16x16x32_bf16 v[98:101], v[142:145], v[194:197], v[98:101]
	v_mfma_f32_16x16x32_bf16 v[98:101], v[138:141], v[190:193], v[98:101]
	v_mfma_f32_16x16x32_bf16 v[106:109], v[138:141], v[198:201], v[106:109]
	v_mfma_f32_16x16x32_bf16 v[106:109], v[142:145], v[202:205], v[106:109]
	v_mfma_f32_16x16x32_bf16 v[122:125], v[134:137], v[202:205], v[122:125]
	v_mfma_f32_16x16x32_bf16 v[122:125], v[130:133], v[198:201], v[122:125]
	v_mfma_f32_16x16x32_bf16 v[62:65], v[146:149], v[162:165], v[62:65]
	v_mfma_f32_16x16x32_bf16 v[62:65], v[150:153], v[170:173], v[62:65]
	v_mfma_f32_16x16x32_bf16 v[46:49], v[158:161], v[170:173], v[46:49]
	v_mfma_f32_16x16x32_bf16 v[46:49], v[154:157], v[162:165], v[46:49]
	v_mfma_f32_16x16x32_bf16 v[38:41], v[154:157], v[182:185], v[38:41]
	v_mfma_f32_16x16x32_bf16 v[38:41], v[158:161], v[186:189], v[38:41]
	v_mfma_f32_16x16x32_bf16 v[54:57], v[150:153], v[186:189], v[54:57]
	v_mfma_f32_16x16x32_bf16 v[54:57], v[146:149], v[182:185], v[54:57]
	v_mfma_f32_16x16x32_bf16 v[50:53], v[146:149], v[190:193], v[50:53]
	v_mfma_f32_16x16x32_bf16 v[50:53], v[150:153], v[194:197], v[50:53]
	v_mfma_f32_16x16x32_bf16 v[34:37], v[158:161], v[194:197], v[34:37]
	v_mfma_f32_16x16x32_bf16 v[34:37], v[154:157], v[190:193], v[34:37]
	v_mfma_f32_16x16x32_bf16 v[42:45], v[154:157], v[198:201], v[42:45]
	v_mfma_f32_16x16x32_bf16 v[42:45], v[158:161], v[202:205], v[42:45]
	v_mfma_f32_16x16x32_bf16 v[58:61], v[150:153], v[202:205], v[58:61]
	v_mfma_f32_16x16x32_bf16 v[58:61], v[146:149], v[198:201], v[58:61]
	s_barrier
	s_mov_b32 m0, s90
	s_mov_b32 s58, s78
	s_mov_b32 s59, s79
	ds_read_b128 v[162:165], v221 offset:16384
	ds_read_b128 v[170:173], v221 offset:17408
	ds_read_b128 v[182:185], v221 offset:18432
	ds_read_b128 v[186:189], v221 offset:19456
	ds_read_b128 v[190:193], v221 offset:20480
	ds_read_b128 v[194:197], v221 offset:21504
	ds_read_b128 v[198:201], v221 offset:22528
	ds_read_b128 v[202:205], v221 offset:23552
	buffer_load_dwordx4 v179, s[56:59], s31 offen lds
	s_mov_b32 m0, s91
	s_add_i32 s51, s31, 0x80000
	buffer_load_dwordx4 v211, s[56:59], s31 offen lds
	s_mov_b32 m0, s9
	s_nop 0
	buffer_load_dwordx4 v179, s[56:59], s51 offen lds
	s_mov_b32 m0, s10
	s_nop 0
	buffer_load_dwordx4 v211, s[56:59], s51 offen lds
	s_mov_b32 m0, s89
	s_nop 0
	buffer_load_dwordx4 v178, s[76:79], s50 offen lds
	s_mov_b32 m0, s11
	s_nop 0
	buffer_load_dwordx4 v210, s[76:79], s50 offen lds
	s_waitcnt vmcnt(8)
	s_waitcnt lgkmcnt(0)
	s_barrier
	v_mfma_f32_16x16x32_bf16 v[94:97], v[130:133], v[162:165], v[94:97]
	v_mfma_f32_16x16x32_bf16 v[94:97], v[134:137], v[170:173], v[94:97]
	v_mfma_f32_16x16x32_bf16 v[78:81], v[142:145], v[170:173], v[78:81]
	v_mfma_f32_16x16x32_bf16 v[78:81], v[138:141], v[162:165], v[78:81]
	v_mfma_f32_16x16x32_bf16 v[70:73], v[138:141], v[182:185], v[70:73]
	v_mfma_f32_16x16x32_bf16 v[70:73], v[142:145], v[186:189], v[70:73]
	v_mfma_f32_16x16x32_bf16 v[86:89], v[134:137], v[186:189], v[86:89]
	v_mfma_f32_16x16x32_bf16 v[86:89], v[130:133], v[182:185], v[86:89]
	v_mfma_f32_16x16x32_bf16 v[82:85], v[130:133], v[190:193], v[82:85]
	v_mfma_f32_16x16x32_bf16 v[82:85], v[134:137], v[194:197], v[82:85]
	v_mfma_f32_16x16x32_bf16 v[66:69], v[142:145], v[194:197], v[66:69]
	v_mfma_f32_16x16x32_bf16 v[66:69], v[138:141], v[190:193], v[66:69]
	v_mfma_f32_16x16x32_bf16 v[74:77], v[138:141], v[198:201], v[74:77]
	v_mfma_f32_16x16x32_bf16 v[74:77], v[142:145], v[202:205], v[74:77]
	v_mfma_f32_16x16x32_bf16 v[90:93], v[134:137], v[202:205], v[90:93]
	v_mfma_f32_16x16x32_bf16 v[90:93], v[130:133], v[198:201], v[90:93]
	v_mfma_f32_16x16x32_bf16 v[30:33], v[146:149], v[162:165], v[30:33]
	v_mfma_f32_16x16x32_bf16 v[30:33], v[150:153], v[170:173], v[30:33]
	v_mfma_f32_16x16x32_bf16 v[14:17], v[158:161], v[170:173], v[14:17]
	v_mfma_f32_16x16x32_bf16 v[14:17], v[154:157], v[162:165], v[14:17]
	v_mfma_f32_16x16x32_bf16 v[10:13], v[154:157], v[182:185], v[10:13]
	v_mfma_f32_16x16x32_bf16 v[10:13], v[158:161], v[186:189], v[10:13]
	v_mfma_f32_16x16x32_bf16 v[22:25], v[150:153], v[186:189], v[22:25]
	v_mfma_f32_16x16x32_bf16 v[22:25], v[146:149], v[182:185], v[22:25]
	v_mfma_f32_16x16x32_bf16 v[18:21], v[146:149], v[190:193], v[18:21]
	v_mfma_f32_16x16x32_bf16 v[18:21], v[150:153], v[194:197], v[18:21]
	v_mfma_f32_16x16x32_bf16 v[2:5], v[158:161], v[194:197], v[2:5]
	v_mfma_f32_16x16x32_bf16 v[2:5], v[154:157], v[190:193], v[2:5]
	v_mfma_f32_16x16x32_bf16 v[6:9], v[154:157], v[198:201], v[6:9]
	v_mfma_f32_16x16x32_bf16 v[6:9], v[158:161], v[202:205], v[6:9]
	v_mfma_f32_16x16x32_bf16 v[26:29], v[150:153], v[202:205], v[26:29]
	v_mfma_f32_16x16x32_bf16 v[26:29], v[146:149], v[198:201], v[26:29]
	s_barrier
; #define PG8_STAGEX(rs, bufoff, soff, voff) do { _Pragma("unroll") for (int _i = 0; _i < 2; ++_i) \
;         __builtin_amdgcn_raw_ptr_buffer_load_lds(rs, (LAS unsigned*)(lds + (bufoff) + ldsw + _i * 8192), 16, (voff)[_i], (soff), 0, 0); } while (0)
; #define PG8_LDA(dst, b, h) do { _Pragma("unroll") for (int m = 0; m < 4; ++m) _Pragma("unroll") for (int k = 0; k < 2; ++k) dst[m][k] = *(const LAS bf16x8*)(lds + PG8_SA(b, h) + aoff + m * 2048 + k * 1024); } while (0)
; #define PG8_LDB(dst, b, h) do { _Pragma("unroll") for (int n = 0; n < 2; ++n) _Pragma("unroll") for (int k = 0; k < 2; ++k) dst[n][k] = *(const LAS bf16x8*)(lds + PG8_SB(b, h) + boff + n * 2048 + k * 1024); } while (0)
; #define PG8_WAIT_V(n) asm volatile("s_waitcnt vmcnt(" #n ")" ::: "memory")
; #define PG8_WAIT_L(n) asm volatile("s_waitcnt lgkmcnt(" #n ")" ::: "memory")
; #define PG8_BAR __builtin_amdgcn_s_barrier()
; #define PG8_SCHED __builtin_amdgcn_sched_barrier(0)
;     ...
;             PG8_LDB(B0, 1, 0); PG8_LDB(B1, 1, 1); PG8_SCHED; PG8_LDA(At, 1, 0); PG8_STAGEX(rsA, PG8_SA(0, 1), a2 + hstepA, voffA);
;             PG8_WAIT_V(8); PG8_WAIT_L(0); PG8_BAR; PG8_MMA(0, 0, At, B0); PG8_MMA(0, 1, At, B1); PG8_BAR; PG8_SCHED;
;             PG8_LDA(At, 1, 1); PG8_STAGEX(rsB, PG8_SB(1, 0), b3, voffB); PG8_STAGEX(rsB, PG8_SB(1, 1), b3 + hstepB, voffB); PG8_STAGEX(rsA, PG8_SA(1, 0), a3, voffA);
;             PG8_WAIT_V(8); PG8_WAIT_L(0); PG8_BAR; PG8_MMA(1, 0, At, B0); PG8_MMA(1, 1, At, B1); PG8_BAR; PG8_SCHED;
;         }
;     ...
;         if (wr == 0) PG8_BAR;
	v_add_u32_e32 v142, 0x18000, v220
	v_add_u32_e32 v158, 0x1c000, v220
	ds_read_b128 v[130:133], v142
	ds_read_b128 v[134:137], v142 offset:1024
	ds_read_b128 v[138:141], v142 offset:2048
	ds_read_b128 v[142:145], v142 offset:3072
	ds_read_b128 v[146:149], v158
	ds_read_b128 v[150:153], v158 offset:1024
	ds_read_b128 v[154:157], v158 offset:2048
	ds_read_b128 v[158:161], v158 offset:3072
	s_add_i32 s50, s50, 0x80000
	s_mov_b32 m0, s74
	ds_read_b128 v[162:165], v221 offset:32768
	ds_read_b128 v[170:173], v221 offset:33792
	ds_read_b128 v[182:185], v221 offset:34816
	ds_read_b128 v[186:189], v221 offset:35840
	ds_read_b128 v[190:193], v221 offset:36864
	ds_read_b128 v[194:197], v221 offset:37888
	ds_read_b128 v[198:201], v221 offset:38912
	ds_read_b128 v[202:205], v221 offset:39936
	buffer_load_dwordx4 v178, s[76:79], s50 offen lds
	s_mov_b32 m0, s12
	s_nop 0
	buffer_load_dwordx4 v210, s[76:79], s50 offen lds
	s_waitcnt vmcnt(8)
	s_waitcnt lgkmcnt(0)
	s_barrier
	v_mfma_f32_16x16x32_bf16 v[126:129], v[130:133], v[162:165], v[126:129]
	v_mfma_f32_16x16x32_bf16 v[126:129], v[134:137], v[170:173], v[126:129]
	v_mfma_f32_16x16x32_bf16 v[110:113], v[142:145], v[170:173], v[110:113]
	v_mfma_f32_16x16x32_bf16 v[110:113], v[138:141], v[162:165], v[110:113]
	v_mfma_f32_16x16x32_bf16 v[102:105], v[138:141], v[182:185], v[102:105]
	v_mfma_f32_16x16x32_bf16 v[102:105], v[142:145], v[186:189], v[102:105]
	v_mfma_f32_16x16x32_bf16 v[118:121], v[134:137], v[186:189], v[118:121]
	v_mfma_f32_16x16x32_bf16 v[118:121], v[130:133], v[182:185], v[118:121]
	v_mfma_f32_16x16x32_bf16 v[114:117], v[130:133], v[190:193], v[114:117]
	v_mfma_f32_16x16x32_bf16 v[114:117], v[134:137], v[194:197], v[114:117]
	v_mfma_f32_16x16x32_bf16 v[98:101], v[142:145], v[194:197], v[98:101]
	v_mfma_f32_16x16x32_bf16 v[98:101], v[138:141], v[190:193], v[98:101]
	v_mfma_f32_16x16x32_bf16 v[106:109], v[138:141], v[198:201], v[106:109]
	v_mfma_f32_16x16x32_bf16 v[106:109], v[142:145], v[202:205], v[106:109]
	v_mfma_f32_16x16x32_bf16 v[122:125], v[134:137], v[202:205], v[122:125]
	v_mfma_f32_16x16x32_bf16 v[122:125], v[130:133], v[198:201], v[122:125]
	v_mfma_f32_16x16x32_bf16 v[62:65], v[146:149], v[162:165], v[62:65]
	v_mfma_f32_16x16x32_bf16 v[62:65], v[150:153], v[170:173], v[62:65]
	v_mfma_f32_16x16x32_bf16 v[46:49], v[158:161], v[170:173], v[46:49]
	v_mfma_f32_16x16x32_bf16 v[46:49], v[154:157], v[162:165], v[46:49]
	v_mfma_f32_16x16x32_bf16 v[38:41], v[154:157], v[182:185], v[38:41]
	v_mfma_f32_16x16x32_bf16 v[38:41], v[158:161], v[186:189], v[38:41]
	v_mfma_f32_16x16x32_bf16 v[54:57], v[150:153], v[186:189], v[54:57]
	v_mfma_f32_16x16x32_bf16 v[54:57], v[146:149], v[182:185], v[54:57]
	v_mfma_f32_16x16x32_bf16 v[50:53], v[146:149], v[190:193], v[50:53]
	v_mfma_f32_16x16x32_bf16 v[50:53], v[150:153], v[194:197], v[50:53]
	v_mfma_f32_16x16x32_bf16 v[34:37], v[158:161], v[194:197], v[34:37]
	v_mfma_f32_16x16x32_bf16 v[34:37], v[154:157], v[190:193], v[34:37]
	v_mfma_f32_16x16x32_bf16 v[42:45], v[154:157], v[198:201], v[42:45]
	v_mfma_f32_16x16x32_bf16 v[42:45], v[158:161], v[202:205], v[42:45]
	v_mfma_f32_16x16x32_bf16 v[58:61], v[150:153], v[202:205], v[58:61]
	v_mfma_f32_16x16x32_bf16 v[58:61], v[146:149], v[198:201], v[58:61]
	s_barrier
	s_mov_b32 m0, s13
	s_or_b32 s50, s31, 0x80
	ds_read_b128 v[162:165], v221 offset:49152
	ds_read_b128 v[170:173], v221 offset:50176
	ds_read_b128 v[182:185], v221 offset:51200
	ds_read_b128 v[186:189], v221 offset:52224
	ds_read_b128 v[190:193], v221 offset:53248
	ds_read_b128 v[194:197], v221 offset:54272
	ds_read_b128 v[198:201], v221 offset:55296
	ds_read_b128 v[202:205], v221 offset:56320
	buffer_load_dwordx4 v179, s[56:59], s50 offen lds
	s_mov_b32 m0, s14
	s_add_i32 s31, s31, 0x80080
	buffer_load_dwordx4 v211, s[56:59], s50 offen lds
	s_mov_b32 m0, s17
	s_nop 0
	buffer_load_dwordx4 v179, s[56:59], s31 offen lds
	s_mov_b32 m0, s18
	s_nop 0
	buffer_load_dwordx4 v211, s[56:59], s31 offen lds
	s_mov_b32 m0, s15
	s_nop 0
	buffer_load_dwordx4 v178, s[76:79], s30 offen lds
	s_mov_b32 m0, s16
	s_nop 0
	buffer_load_dwordx4 v210, s[76:79], s30 offen lds
	s_waitcnt vmcnt(8)
	s_waitcnt lgkmcnt(0)
	s_barrier
	v_mfma_f32_16x16x32_bf16 v[94:97], v[130:133], v[162:165], v[94:97]
	v_mfma_f32_16x16x32_bf16 v[94:97], v[134:137], v[170:173], v[94:97]
	v_mfma_f32_16x16x32_bf16 v[78:81], v[142:145], v[170:173], v[78:81]
	v_mfma_f32_16x16x32_bf16 v[78:81], v[138:141], v[162:165], v[78:81]
	v_mfma_f32_16x16x32_bf16 v[70:73], v[138:141], v[182:185], v[70:73]
	v_mfma_f32_16x16x32_bf16 v[70:73], v[142:145], v[186:189], v[70:73]
	v_mfma_f32_16x16x32_bf16 v[86:89], v[134:137], v[186:189], v[86:89]
	v_mfma_f32_16x16x32_bf16 v[86:89], v[130:133], v[182:185], v[86:89]
	v_mfma_f32_16x16x32_bf16 v[82:85], v[130:133], v[190:193], v[82:85]
	v_mfma_f32_16x16x32_bf16 v[82:85], v[134:137], v[194:197], v[82:85]
	v_mfma_f32_16x16x32_bf16 v[66:69], v[142:145], v[194:197], v[66:69]
	v_mfma_f32_16x16x32_bf16 v[66:69], v[138:141], v[190:193], v[66:69]
	v_mfma_f32_16x16x32_bf16 v[74:77], v[138:141], v[198:201], v[74:77]
	v_mfma_f32_16x16x32_bf16 v[74:77], v[142:145], v[202:205], v[74:77]
	v_mfma_f32_16x16x32_bf16 v[90:93], v[134:137], v[202:205], v[90:93]
	v_mfma_f32_16x16x32_bf16 v[90:93], v[130:133], v[198:201], v[90:93]
	v_mfma_f32_16x16x32_bf16 v[30:33], v[146:149], v[162:165], v[30:33]
	v_mfma_f32_16x16x32_bf16 v[30:33], v[150:153], v[170:173], v[30:33]
	v_mfma_f32_16x16x32_bf16 v[14:17], v[158:161], v[170:173], v[14:17]
	v_mfma_f32_16x16x32_bf16 v[14:17], v[154:157], v[162:165], v[14:17]
	v_mfma_f32_16x16x32_bf16 v[10:13], v[154:157], v[182:185], v[10:13]
	v_mfma_f32_16x16x32_bf16 v[10:13], v[158:161], v[186:189], v[10:13]
	v_mfma_f32_16x16x32_bf16 v[22:25], v[150:153], v[186:189], v[22:25]
	v_mfma_f32_16x16x32_bf16 v[22:25], v[146:149], v[182:185], v[22:25]
	v_mfma_f32_16x16x32_bf16 v[18:21], v[146:149], v[190:193], v[18:21]
	v_mfma_f32_16x16x32_bf16 v[18:21], v[150:153], v[194:197], v[18:21]
	v_mfma_f32_16x16x32_bf16 v[2:5], v[158:161], v[194:197], v[2:5]
	v_mfma_f32_16x16x32_bf16 v[2:5], v[154:157], v[190:193], v[2:5]
	v_mfma_f32_16x16x32_bf16 v[6:9], v[154:157], v[198:201], v[6:9]
	v_mfma_f32_16x16x32_bf16 v[6:9], v[158:161], v[202:205], v[6:9]
	v_mfma_f32_16x16x32_bf16 v[26:29], v[150:153], v[202:205], v[26:29]
	v_mfma_f32_16x16x32_bf16 v[26:29], v[146:149], v[198:201], v[26:29]
	s_barrier
	s_add_i32 s29, s29, 2
	s_addk_i32 s7, 0x100
	s_addk_i32 s28, 0x100
	s_cmp_gt_u32 s29, 29
	s_cbranch_scc0 .LBB0_437
	s_setprio 0
	s_and_b64 vcc, exec, s[84:85]
	s_cbranch_vccz .LBB0_440
	s_barrier

;     ...
;         bool has_next; if constexpr (QV == 2) has_next = S.next_tail(ui + 1, nxt); else has_next = S.next(ui + 1, nxt);
;         const unsigned nA = has_next ? (unsigned)nxt.pm * tstepA + nxt.aoff : cA, nB = has_next ? (unsigned)nxt.pn * tstepB + nxt.boff : cB;
;         if constexpr (QV == 0) {
; #pragma nounroll
;         for (int t = 0; t < nt; t += 2) {
;             const bool last = (t == nt - 2);
;             const unsigned a1 = cA + (unsigned)(t + 1) * kstep;
;             const unsigned a2 = last ? nA : cA + (unsigned)(t + 2) * kstep, b2 = last ? nB : cB + (unsigned)(t + 2) * kstep;
;             const unsigned a3 = a2 + kstep, b3 = b2 + kstep;
;     ...
;         if (!cur.keep) {
; #pragma unroll
;             for (int a = 0; a < 2; ++a)
; #pragma unroll
;                 for (int b = 0; b < 2; ++b)
; #pragma unroll
;                     for (int m = 0; m < 4; ++m)
; #pragma unroll
;                         for (int n = 0; n < 2; ++n) { f32x2 z0, z1; asm("v_mov_b64 %0, 0\n\tv_mov_b64 %1, 0" : "=v"(z0), "=v"(z1));
;                     acc[a][b][m][n] = __builtin_shufflevector(z0, z1, 0, 1, 2, 3); }
.LBB0_1273:
	s_lshl_b32 s65, s64, 20
	s_and_b64 s[30:31], s[38:39], exec
	s_cselect_b32 s30, s65, s62
	s_lshl_b32 s66, s59, 20
	s_and_b64 s[42:43], s[38:39], exec
	v_mov_b64_e32 v[8:9], v[4:5]
	v_mov_b64_e32 v[12:13], v[4:5]
	v_mov_b64_e32 v[16:17], v[4:5]
	v_mov_b64_e32 v[20:21], v[4:5]
	v_mov_b64_e32 v[24:25], v[4:5]
	s_waitcnt vmcnt(15)
	v_mov_b64_e32 v[28:29], v[4:5]
	v_mov_b64_e32 v[32:33], v[4:5]
	v_mov_b64_e32 v[68:69], v[4:5]
	v_mov_b64_e32 v[72:73], v[4:5]
	v_mov_b64_e32 v[76:77], v[4:5]
	v_mov_b64_e32 v[80:81], v[4:5]
	v_mov_b64_e32 v[84:85], v[4:5]
	v_mov_b64_e32 v[88:89], v[4:5]
	v_mov_b64_e32 v[92:93], v[4:5]
	v_mov_b64_e32 v[96:97], v[4:5]
	v_mov_b64_e32 v[36:37], v[4:5]
	v_mov_b64_e32 v[40:41], v[4:5]
	v_mov_b64_e32 v[44:45], v[4:5]
	v_mov_b64_e32 v[48:49], v[4:5]
	v_mov_b64_e32 v[52:53], v[4:5]
	v_mov_b64_e32 v[56:57], v[4:5]
	v_mov_b64_e32 v[60:61], v[4:5]
	v_mov_b64_e32 v[64:65], v[4:5]
	v_mov_b64_e32 v[100:101], v[4:5]
	v_mov_b64_e32 v[104:105], v[4:5]
	v_mov_b64_e32 v[108:109], v[4:5]
	v_mov_b64_e32 v[112:113], v[4:5]
	v_mov_b64_e32 v[116:117], v[4:5]
	v_mov_b64_e32 v[120:121], v[4:5]
	v_mov_b64_e32 v[124:125], v[4:5]
	v_mov_b64_e32 v[128:129], v[4:5]
	s_cselect_b32 s31, s66, s63
	s_add_i32 s62, s62, 0x80080
	s_addk_i32 s63, 0x100
	s_mov_b32 s67, -2
	v_mov_b64_e32 v[6:7], v[2:3]
	v_mov_b64_e32 v[10:11], v[2:3]
	v_mov_b64_e32 v[14:15], v[2:3]
	v_mov_b64_e32 v[18:19], v[2:3]
	v_mov_b64_e32 v[22:23], v[2:3]
	v_mov_b64_e32 v[26:27], v[2:3]
	v_mov_b64_e32 v[30:31], v[2:3]
	v_mov_b64_e32 v[66:67], v[2:3]
	v_mov_b64_e32 v[70:71], v[2:3]
	v_mov_b64_e32 v[74:75], v[2:3]
	v_mov_b64_e32 v[78:79], v[2:3]
	v_mov_b64_e32 v[82:83], v[2:3]
	v_mov_b64_e32 v[86:87], v[2:3]
	v_mov_b64_e32 v[90:91], v[2:3]
	v_mov_b64_e32 v[94:95], v[2:3]
	v_mov_b64_e32 v[34:35], v[2:3]
	v_mov_b64_e32 v[38:39], v[2:3]
	v_mov_b64_e32 v[42:43], v[2:3]
	v_mov_b64_e32 v[46:47], v[2:3]
	v_mov_b64_e32 v[50:51], v[2:3]
	v_mov_b64_e32 v[54:55], v[2:3]
	v_mov_b64_e32 v[58:59], v[2:3]
	v_mov_b64_e32 v[62:63], v[2:3]
	v_mov_b64_e32 v[98:99], v[2:3]
	v_mov_b64_e32 v[102:103], v[2:3]
	v_mov_b64_e32 v[106:107], v[2:3]
	v_mov_b64_e32 v[110:111], v[2:3]
	v_mov_b64_e32 v[114:115], v[2:3]
	v_mov_b64_e32 v[118:119], v[2:3]
	v_mov_b64_e32 v[122:123], v[2:3]
	v_mov_b64_e32 v[126:127], v[2:3]
	s_and_b64 vcc, exec, s[48:49]
	s_cbranch_vccz .Lsp_1274
	s_setprio 1

; #define PG8_STAGEX(rs, bufoff, soff, voff) do { _Pragma("unroll") for (int _i = 0; _i < 2; ++_i) \
;         __builtin_amdgcn_raw_ptr_buffer_load_lds(rs, (LAS unsigned*)(lds + (bufoff) + ldsw + _i * 8192), 16, (voff)[_i], (soff), 0, 0); } while (0)
; #define PG8_LDA(dst, b, h) do { _Pragma("unroll") for (int m = 0; m < 4; ++m) _Pragma("unroll") for (int k = 0; k < 2; ++k) dst[m][k] = *(const LAS bf16x8*)(lds + PG8_SA(b, h) + aoff + m * 2048 + k * 1024); } while (0)
; #define PG8_LDB(dst, b, h) do { _Pragma("unroll") for (int n = 0; n < 2; ++n) _Pragma("unroll") for (int k = 0; k < 2; ++k) dst[n][k] = *(const LAS bf16x8*)(lds + PG8_SB(b, h) + boff + n * 2048 + k * 1024); } while (0)
; #define PG8_WAIT_V(n) asm volatile("s_waitcnt vmcnt(" #n ")" ::: "memory")
; #define PG8_WAIT_L(n) asm volatile("s_waitcnt lgkmcnt(" #n ")" ::: "memory")
; #define PG8_BAR __builtin_amdgcn_s_barrier()
; #define PG8_SCHED __builtin_amdgcn_sched_barrier(0)
;     ...
;             PG8_LDB(B0, 0, 0); PG8_LDB(B1, 0, 1); PG8_SCHED; PG8_LDA(At, 0, 0); PG8_STAGEX(rsA, PG8_SA(1, 1), a1 + hstepA, voffA);
;             PG8_WAIT_V(8); PG8_WAIT_L(0); PG8_BAR; PG8_MMA(0, 0, At, B0); PG8_MMA(0, 1, At, B1); PG8_BAR; PG8_SCHED;
;             PG8_LDA(At, 0, 1); PG8_STAGEX(rsB, PG8_SB(0, 0), b2, voffB); PG8_STAGEX(rsB, PG8_SB(0, 1), b2 + hstepB, voffB); PG8_STAGEX(rsA, PG8_SA(0, 0), a2, voffA);
;             PG8_WAIT_V(8); PG8_WAIT_L(0); PG8_BAR; PG8_MMA(1, 0, At, B0); PG8_MMA(1, 1, At, B1); PG8_BAR; PG8_SCHED;
.LBB0_1274:
	v_add_u32_e32 v142, 0x10000, v157
	v_add_u32_e32 v159, 0x14000, v157
	ds_read_b128 v[130:133], v142
	ds_read_b128 v[134:137], v142 offset:1024
	ds_read_b128 v[138:141], v142 offset:2048
	ds_read_b128 v[142:145], v142 offset:3072
	ds_read_b128 v[146:149], v159
	ds_read_b128 v[164:167], v159 offset:1024
	ds_read_b128 v[168:171], v159 offset:2048
	ds_read_b128 v[182:185], v159 offset:3072
	s_add_i32 s42, s62, 0xfff80080
	s_cmp_eq_u32 s67, 28
	s_cselect_b32 s70, s30, s42
	s_cselect_b32 s69, s31, s63
	s_or_b32 s68, s70, 0x80
	s_mov_b32 m0, s29
	ds_read_b128 v[186:189], v158
	ds_read_b128 v[190:193], v158 offset:1024
	ds_read_b128 v[194:197], v158 offset:2048
	ds_read_b128 v[198:201], v158 offset:3072
	ds_read_b128 v[202:205], v158 offset:4096
	ds_read_b128 v[206:209], v158 offset:5120
	ds_read_b128 v[210:213], v158 offset:6144
	ds_read_b128 v[214:217], v158 offset:7168
	buffer_load_dwordx4 v150, s[76:79], s62 offen lds
	s_mov_b32 m0, s35
	s_nop 0
	buffer_load_dwordx4 v152, s[76:79], s62 offen lds
	s_waitcnt vmcnt(8)
	s_waitcnt lgkmcnt(0)
	s_barrier
	v_mfma_f32_16x16x32_bf16 v[126:129], v[130:133], v[186:189], v[126:129]
	v_mfma_f32_16x16x32_bf16 v[126:129], v[134:137], v[190:193], v[126:129]
	v_mfma_f32_16x16x32_bf16 v[122:125], v[142:145], v[190:193], v[122:125]
	v_mfma_f32_16x16x32_bf16 v[122:125], v[138:141], v[186:189], v[122:125]
	v_mfma_f32_16x16x32_bf16 v[114:117], v[138:141], v[194:197], v[114:117]
	v_mfma_f32_16x16x32_bf16 v[114:117], v[142:145], v[198:201], v[114:117]
	v_mfma_f32_16x16x32_bf16 v[118:121], v[134:137], v[198:201], v[118:121]
	v_mfma_f32_16x16x32_bf16 v[118:121], v[130:133], v[194:197], v[118:121]
	v_mfma_f32_16x16x32_bf16 v[110:113], v[130:133], v[202:205], v[110:113]
	v_mfma_f32_16x16x32_bf16 v[110:113], v[134:137], v[206:209], v[110:113]
	v_mfma_f32_16x16x32_bf16 v[106:109], v[142:145], v[206:209], v[106:109]
	v_mfma_f32_16x16x32_bf16 v[106:109], v[138:141], v[202:205], v[106:109]
	v_mfma_f32_16x16x32_bf16 v[98:101], v[138:141], v[210:213], v[98:101]
	v_mfma_f32_16x16x32_bf16 v[98:101], v[142:145], v[214:217], v[98:101]
	v_mfma_f32_16x16x32_bf16 v[102:105], v[134:137], v[214:217], v[102:105]
	v_mfma_f32_16x16x32_bf16 v[102:105], v[130:133], v[210:213], v[102:105]
	v_mfma_f32_16x16x32_bf16 v[62:65], v[146:149], v[186:189], v[62:65]
	v_mfma_f32_16x16x32_bf16 v[62:65], v[164:167], v[190:193], v[62:65]
	v_mfma_f32_16x16x32_bf16 v[58:61], v[182:185], v[190:193], v[58:61]
	v_mfma_f32_16x16x32_bf16 v[58:61], v[168:171], v[186:189], v[58:61]
	v_mfma_f32_16x16x32_bf16 v[50:53], v[168:171], v[194:197], v[50:53]
	v_mfma_f32_16x16x32_bf16 v[50:53], v[182:185], v[198:201], v[50:53]
	v_mfma_f32_16x16x32_bf16 v[54:57], v[164:167], v[198:201], v[54:57]
	v_mfma_f32_16x16x32_bf16 v[54:57], v[146:149], v[194:197], v[54:57]
	v_mfma_f32_16x16x32_bf16 v[46:49], v[146:149], v[202:205], v[46:49]
	v_mfma_f32_16x16x32_bf16 v[46:49], v[164:167], v[206:209], v[46:49]
	v_mfma_f32_16x16x32_bf16 v[42:45], v[182:185], v[206:209], v[42:45]
	v_mfma_f32_16x16x32_bf16 v[42:45], v[168:171], v[202:205], v[42:45]
	v_mfma_f32_16x16x32_bf16 v[34:37], v[168:171], v[210:213], v[34:37]
	v_mfma_f32_16x16x32_bf16 v[34:37], v[182:185], v[214:217], v[34:37]
	v_mfma_f32_16x16x32_bf16 v[38:41], v[164:167], v[214:217], v[38:41]
	v_mfma_f32_16x16x32_bf16 v[38:41], v[146:149], v[210:213], v[38:41]
	s_barrier
	s_mov_b32 m0, s16
	s_mov_b32 s42, s78
	s_mov_b32 s43, s79
	ds_read_b128 v[186:189], v158 offset:16384
	ds_read_b128 v[190:193], v158 offset:17408
	ds_read_b128 v[194:197], v158 offset:18432
	ds_read_b128 v[198:201], v158 offset:19456
	ds_read_b128 v[202:205], v158 offset:20480
	ds_read_b128 v[206:209], v158 offset:21504
	ds_read_b128 v[210:213], v158 offset:22528
	ds_read_b128 v[214:217], v158 offset:23552
	buffer_load_dwordx4 v151, s[40:43], s69 offen lds
	s_mov_b32 m0, s17
	s_add_i32 s71, s69, 0x80000
	buffer_load_dwordx4 v153, s[40:43], s69 offen lds
	s_mov_b32 m0, s18
	s_nop 0
	buffer_load_dwordx4 v151, s[40:43], s71 offen lds
	s_mov_b32 m0, s19
	s_nop 0
	buffer_load_dwordx4 v153, s[40:43], s71 offen lds
	s_mov_b32 m0, s15
	s_nop 0
	buffer_load_dwordx4 v150, s[76:79], s70 offen lds
	s_mov_b32 m0, s20
	s_nop 0
	buffer_load_dwordx4 v152, s[76:79], s70 offen lds
	s_waitcnt vmcnt(8)
	s_waitcnt lgkmcnt(0)
	s_barrier
	v_mfma_f32_16x16x32_bf16 v[94:97], v[130:133], v[186:189], v[94:97]
	v_mfma_f32_16x16x32_bf16 v[94:97], v[134:137], v[190:193], v[94:97]
	v_mfma_f32_16x16x32_bf16 v[90:93], v[142:145], v[190:193], v[90:93]
	v_mfma_f32_16x16x32_bf16 v[90:93], v[138:141], v[186:189], v[90:93]
	v_mfma_f32_16x16x32_bf16 v[82:85], v[138:141], v[194:197], v[82:85]
	v_mfma_f32_16x16x32_bf16 v[82:85], v[142:145], v[198:201], v[82:85]
	v_mfma_f32_16x16x32_bf16 v[86:89], v[134:137], v[198:201], v[86:89]
	v_mfma_f32_16x16x32_bf16 v[86:89], v[130:133], v[194:197], v[86:89]
	v_mfma_f32_16x16x32_bf16 v[78:81], v[130:133], v[202:205], v[78:81]
	v_mfma_f32_16x16x32_bf16 v[78:81], v[134:137], v[206:209], v[78:81]
	v_mfma_f32_16x16x32_bf16 v[74:77], v[142:145], v[206:209], v[74:77]
	v_mfma_f32_16x16x32_bf16 v[74:77], v[138:141], v[202:205], v[74:77]
	v_mfma_f32_16x16x32_bf16 v[66:69], v[138:141], v[210:213], v[66:69]
	v_mfma_f32_16x16x32_bf16 v[66:69], v[142:145], v[214:217], v[66:69]
	v_mfma_f32_16x16x32_bf16 v[70:73], v[134:137], v[214:217], v[70:73]
	v_mfma_f32_16x16x32_bf16 v[70:73], v[130:133], v[210:213], v[70:73]
	v_mfma_f32_16x16x32_bf16 v[30:33], v[146:149], v[186:189], v[30:33]
	v_mfma_f32_16x16x32_bf16 v[30:33], v[164:167], v[190:193], v[30:33]
	v_mfma_f32_16x16x32_bf16 v[26:29], v[182:185], v[190:193], v[26:29]
	v_mfma_f32_16x16x32_bf16 v[26:29], v[168:171], v[186:189], v[26:29]
	v_mfma_f32_16x16x32_bf16 v[18:21], v[168:171], v[194:197], v[18:21]
	v_mfma_f32_16x16x32_bf16 v[18:21], v[182:185], v[198:201], v[18:21]
	v_mfma_f32_16x16x32_bf16 v[22:25], v[164:167], v[198:201], v[22:25]
	v_mfma_f32_16x16x32_bf16 v[22:25], v[146:149], v[194:197], v[22:25]
	v_mfma_f32_16x16x32_bf16 v[14:17], v[146:149], v[202:205], v[14:17]
	v_mfma_f32_16x16x32_bf16 v[14:17], v[164:167], v[206:209], v[14:17]
	v_mfma_f32_16x16x32_bf16 v[10:13], v[182:185], v[206:209], v[10:13]
	v_mfma_f32_16x16x32_bf16 v[10:13], v[168:171], v[202:205], v[10:13]
	v_mfma_f32_16x16x32_bf16 v[2:5], v[168:171], v[210:213], v[2:5]
	v_mfma_f32_16x16x32_bf16 v[2:5], v[182:185], v[214:217], v[2:5]
	v_mfma_f32_16x16x32_bf16 v[6:9], v[164:167], v[214:217], v[6:9]
	v_mfma_f32_16x16x32_bf16 v[6:9], v[146:149], v[210:213], v[6:9]
	s_barrier
; #define PG8_STAGEX(rs, bufoff, soff, voff) do { _Pragma("unroll") for (int _i = 0; _i < 2; ++_i) \
;         __builtin_amdgcn_raw_ptr_buffer_load_lds(rs, (LAS unsigned*)(lds + (bufoff) + ldsw + _i * 8192), 16, (voff)[_i], (soff), 0, 0); } while (0)
; #define PG8_LDA(dst, b, h) do { _Pragma("unroll") for (int m = 0; m < 4; ++m) _Pragma("unroll") for (int k = 0; k < 2; ++k) dst[m][k] = *(const LAS bf16x8*)(lds + PG8_SA(b, h) + aoff + m * 2048 + k * 1024); } while (0)
; #define PG8_LDB(dst, b, h) do { _Pragma("unroll") for (int n = 0; n < 2; ++n) _Pragma("unroll") for (int k = 0; k < 2; ++k) dst[n][k] = *(const LAS bf16x8*)(lds + PG8_SB(b, h) + boff + n * 2048 + k * 1024); } while (0)
; #define PG8_WAIT_V(n) asm volatile("s_waitcnt vmcnt(" #n ")" ::: "memory")
; #define PG8_WAIT_L(n) asm volatile("s_waitcnt lgkmcnt(" #n ")" ::: "memory")
; #define PG8_BAR __builtin_amdgcn_s_barrier()
; #define PG8_SCHED __builtin_amdgcn_sched_barrier(0)
;     ...
;             PG8_LDB(B0, 1, 0); PG8_LDB(B1, 1, 1); PG8_SCHED; PG8_LDA(At, 1, 0); PG8_STAGEX(rsA, PG8_SA(0, 1), a2 + hstepA, voffA);
;             PG8_WAIT_V(8); PG8_WAIT_L(0); PG8_BAR; PG8_MMA(0, 0, At, B0); PG8_MMA(0, 1, At, B1); PG8_BAR; PG8_SCHED;
;             PG8_LDA(At, 1, 1); PG8_STAGEX(rsB, PG8_SB(1, 0), b3, voffB); PG8_STAGEX(rsB, PG8_SB(1, 1), b3 + hstepB, voffB); PG8_STAGEX(rsA, PG8_SA(1, 0), a3, voffA);
;             PG8_WAIT_V(8); PG8_WAIT_L(0); PG8_BAR; PG8_MMA(1, 0, At, B0); PG8_MMA(1, 1, At, B1); PG8_BAR; PG8_SCHED;
;         }
;     ...
;         if (wr == 0) PG8_BAR;
	v_add_u32_e32 v142, 0x18000, v157
	v_add_u32_e32 v159, 0x1c000, v157
	ds_read_b128 v[130:133], v142
	ds_read_b128 v[134:137], v142 offset:1024
	ds_read_b128 v[138:141], v142 offset:2048
	ds_read_b128 v[142:145], v142 offset:3072
	ds_read_b128 v[146:149], v159
	ds_read_b128 v[164:167], v159 offset:1024
	ds_read_b128 v[168:171], v159 offset:2048
	ds_read_b128 v[182:185], v159 offset:3072
	s_add_i32 s70, s70, 0x80000
	s_mov_b32 m0, s21
	ds_read_b128 v[186:189], v158 offset:32768
	ds_read_b128 v[190:193], v158 offset:33792
	ds_read_b128 v[194:197], v158 offset:34816
	ds_read_b128 v[198:201], v158 offset:35840
	ds_read_b128 v[202:205], v158 offset:36864
	ds_read_b128 v[206:209], v158 offset:37888
	ds_read_b128 v[210:213], v158 offset:38912
	ds_read_b128 v[214:217], v158 offset:39936
	buffer_load_dwordx4 v150, s[76:79], s70 offen lds
	s_mov_b32 m0, s22
	s_nop 0
	buffer_load_dwordx4 v152, s[76:79], s70 offen lds
	s_waitcnt vmcnt(8)
	s_waitcnt lgkmcnt(0)
	s_barrier
	v_mfma_f32_16x16x32_bf16 v[126:129], v[130:133], v[186:189], v[126:129]
	v_mfma_f32_16x16x32_bf16 v[126:129], v[134:137], v[190:193], v[126:129]
	v_mfma_f32_16x16x32_bf16 v[122:125], v[142:145], v[190:193], v[122:125]
	v_mfma_f32_16x16x32_bf16 v[122:125], v[138:141], v[186:189], v[122:125]
	v_mfma_f32_16x16x32_bf16 v[114:117], v[138:141], v[194:197], v[114:117]
	v_mfma_f32_16x16x32_bf16 v[114:117], v[142:145], v[198:201], v[114:117]
	v_mfma_f32_16x16x32_bf16 v[118:121], v[134:137], v[198:201], v[118:121]
	v_mfma_f32_16x16x32_bf16 v[118:121], v[130:133], v[194:197], v[118:121]
	v_mfma_f32_16x16x32_bf16 v[110:113], v[130:133], v[202:205], v[110:113]
	v_mfma_f32_16x16x32_bf16 v[110:113], v[134:137], v[206:209], v[110:113]
	v_mfma_f32_16x16x32_bf16 v[106:109], v[142:145], v[206:209], v[106:109]
	v_mfma_f32_16x16x32_bf16 v[106:109], v[138:141], v[202:205], v[106:109]
	v_mfma_f32_16x16x32_bf16 v[98:101], v[138:141], v[210:213], v[98:101]
	v_mfma_f32_16x16x32_bf16 v[98:101], v[142:145], v[214:217], v[98:101]
	v_mfma_f32_16x16x32_bf16 v[102:105], v[134:137], v[214:217], v[102:105]
	v_mfma_f32_16x16x32_bf16 v[102:105], v[130:133], v[210:213], v[102:105]
	v_mfma_f32_16x16x32_bf16 v[62:65], v[146:149], v[186:189], v[62:65]
	v_mfma_f32_16x16x32_bf16 v[62:65], v[164:167], v[190:193], v[62:65]
	v_mfma_f32_16x16x32_bf16 v[58:61], v[182:185], v[190:193], v[58:61]
	v_mfma_f32_16x16x32_bf16 v[58:61], v[168:171], v[186:189], v[58:61]
	v_mfma_f32_16x16x32_bf16 v[50:53], v[168:171], v[194:197], v[50:53]
	v_mfma_f32_16x16x32_bf16 v[50:53], v[182:185], v[198:201], v[50:53]
	v_mfma_f32_16x16x32_bf16 v[54:57], v[164:167], v[198:201], v[54:57]
	v_mfma_f32_16x16x32_bf16 v[54:57], v[146:149], v[194:197], v[54:57]
	v_mfma_f32_16x16x32_bf16 v[46:49], v[146:149], v[202:205], v[46:49]
	v_mfma_f32_16x16x32_bf16 v[46:49], v[164:167], v[206:209], v[46:49]
	v_mfma_f32_16x16x32_bf16 v[42:45], v[182:185], v[206:209], v[42:45]
	v_mfma_f32_16x16x32_bf16 v[42:45], v[168:171], v[202:205], v[42:45]
	v_mfma_f32_16x16x32_bf16 v[34:37], v[168:171], v[210:213], v[34:37]
	v_mfma_f32_16x16x32_bf16 v[34:37], v[182:185], v[214:217], v[34:37]
	v_mfma_f32_16x16x32_bf16 v[38:41], v[164:167], v[214:217], v[38:41]
	v_mfma_f32_16x16x32_bf16 v[38:41], v[146:149], v[210:213], v[38:41]
	s_barrier
	s_mov_b32 m0, s23
	s_or_b32 s70, s69, 0x80
	ds_read_b128 v[186:189], v158 offset:49152
	ds_read_b128 v[190:193], v158 offset:50176
	ds_read_b128 v[194:197], v158 offset:51200
	ds_read_b128 v[198:201], v158 offset:52224
	ds_read_b128 v[202:205], v158 offset:53248
	ds_read_b128 v[206:209], v158 offset:54272
	ds_read_b128 v[210:213], v158 offset:55296
	ds_read_b128 v[214:217], v158 offset:56320
	buffer_load_dwordx4 v151, s[40:43], s70 offen lds
	s_mov_b32 m0, s24
	s_add_i32 s69, s69, 0x80080
	buffer_load_dwordx4 v153, s[40:43], s70 offen lds
	s_mov_b32 m0, s27
	s_nop 0
	buffer_load_dwordx4 v151, s[40:43], s69 offen lds
	s_mov_b32 m0, s28
	s_nop 0
	buffer_load_dwordx4 v153, s[40:43], s69 offen lds
	s_mov_b32 m0, s25
	s_nop 0
	buffer_load_dwordx4 v150, s[76:79], s68 offen lds
	s_mov_b32 m0, s26
	s_nop 0
	buffer_load_dwordx4 v152, s[76:79], s68 offen lds
	s_waitcnt vmcnt(8)
	s_waitcnt lgkmcnt(0)
	s_barrier
	v_mfma_f32_16x16x32_bf16 v[94:97], v[130:133], v[186:189], v[94:97]
	v_mfma_f32_16x16x32_bf16 v[94:97], v[134:137], v[190:193], v[94:97]
	v_mfma_f32_16x16x32_bf16 v[90:93], v[142:145], v[190:193], v[90:93]
	v_mfma_f32_16x16x32_bf16 v[90:93], v[138:141], v[186:189], v[90:93]
	v_mfma_f32_16x16x32_bf16 v[82:85], v[138:141], v[194:197], v[82:85]
	v_mfma_f32_16x16x32_bf16 v[82:85], v[142:145], v[198:201], v[82:85]
	v_mfma_f32_16x16x32_bf16 v[86:89], v[134:137], v[198:201], v[86:89]
	v_mfma_f32_16x16x32_bf16 v[86:89], v[130:133], v[194:197], v[86:89]
	v_mfma_f32_16x16x32_bf16 v[78:81], v[130:133], v[202:205], v[78:81]
	v_mfma_f32_16x16x32_bf16 v[78:81], v[134:137], v[206:209], v[78:81]
	v_mfma_f32_16x16x32_bf16 v[74:77], v[142:145], v[206:209], v[74:77]
	v_mfma_f32_16x16x32_bf16 v[74:77], v[138:141], v[202:205], v[74:77]
	v_mfma_f32_16x16x32_bf16 v[66:69], v[138:141], v[210:213], v[66:69]
	v_mfma_f32_16x16x32_bf16 v[66:69], v[142:145], v[214:217], v[66:69]
	v_mfma_f32_16x16x32_bf16 v[70:73], v[134:137], v[214:217], v[70:73]
	v_mfma_f32_16x16x32_bf16 v[70:73], v[130:133], v[210:213], v[70:73]
	v_mfma_f32_16x16x32_bf16 v[30:33], v[146:149], v[186:189], v[30:33]
	v_mfma_f32_16x16x32_bf16 v[30:33], v[164:167], v[190:193], v[30:33]
	v_mfma_f32_16x16x32_bf16 v[26:29], v[182:185], v[190:193], v[26:29]
	v_mfma_f32_16x16x32_bf16 v[26:29], v[168:171], v[186:189], v[26:29]
	v_mfma_f32_16x16x32_bf16 v[18:21], v[168:171], v[194:197], v[18:21]
	v_mfma_f32_16x16x32_bf16 v[18:21], v[182:185], v[198:201], v[18:21]
	v_mfma_f32_16x16x32_bf16 v[22:25], v[164:167], v[198:201], v[22:25]
	v_mfma_f32_16x16x32_bf16 v[22:25], v[146:149], v[194:197], v[22:25]
	v_mfma_f32_16x16x32_bf16 v[14:17], v[146:149], v[202:205], v[14:17]
	v_mfma_f32_16x16x32_bf16 v[14:17], v[164:167], v[206:209], v[14:17]
	v_mfma_f32_16x16x32_bf16 v[10:13], v[182:185], v[206:209], v[10:13]
	v_mfma_f32_16x16x32_bf16 v[10:13], v[168:171], v[202:205], v[10:13]
	v_mfma_f32_16x16x32_bf16 v[2:5], v[168:171], v[210:213], v[2:5]
	v_mfma_f32_16x16x32_bf16 v[2:5], v[182:185], v[214:217], v[2:5]
	v_mfma_f32_16x16x32_bf16 v[6:9], v[164:167], v[214:217], v[6:9]
	v_mfma_f32_16x16x32_bf16 v[6:9], v[146:149], v[210:213], v[6:9]
	s_barrier
	s_add_i32 s67, s67, 2
	s_addk_i32 s62, 0x100
	s_addk_i32 s63, 0x100
	s_cmp_gt_u32 s67, 29
	s_cbranch_scc0 .LBB0_1274
	s_setprio 0
	s_and_b64 vcc, exec, s[50:51]
	s_cbranch_vccz .LBB0_1277
	s_barrier

;     ...
;         bool has_next; if constexpr (QV == 2) has_next = S.next_tail(ui + 1, nxt); else has_next = S.next(ui + 1, nxt);
;         const unsigned nA = has_next ? (unsigned)nxt.pm * tstepA + nxt.aoff : cA, nB = has_next ? (unsigned)nxt.pn * tstepB + nxt.boff : cB;
;         if constexpr (QV == 0) {
; #pragma nounroll
;         for (int t = 0; t < nt; t += 2) {
;             const bool last = (t == nt - 2);
;             const unsigned a1 = cA + (unsigned)(t + 1) * kstep;
;             const unsigned a2 = last ? nA : cA + (unsigned)(t + 2) * kstep, b2 = last ? nB : cB + (unsigned)(t + 2) * kstep;
;             const unsigned a3 = a2 + kstep, b3 = b2 + kstep;
.LBB0_1376:
	s_mul_i32 s55, s54, 0x180000
	s_add_i32 s55, s55, s29
	s_and_b64 s[30:31], s[38:39], exec
	s_cselect_b32 s30, s55, s43
	s_lshl_b32 s58, s26, 19
	s_add_i32 s58, s58, s28
	s_and_b64 s[50:51], s[38:39], exec
	s_cselect_b32 s31, s58, s59
	s_add_i32 s43, s43, 0xc0080
	s_addk_i32 s59, 0x100
	s_mov_b32 s60, -2
	s_and_b64 vcc, exec, s[46:47]
	s_cbranch_vccz .Lsp_1377
	s_setprio 1

; #define PG8_STAGEX(rs, bufoff, soff, voff) do { _Pragma("unroll") for (int _i = 0; _i < 2; ++_i) \
;         __builtin_amdgcn_raw_ptr_buffer_load_lds(rs, (LAS unsigned*)(lds + (bufoff) + ldsw + _i * 8192), 16, (voff)[_i], (soff), 0, 0); } while (0)
; #define PG8_LDA(dst, b, h) do { _Pragma("unroll") for (int m = 0; m < 4; ++m) _Pragma("unroll") for (int k = 0; k < 2; ++k) dst[m][k] = *(const LAS bf16x8*)(lds + PG8_SA(b, h) + aoff + m * 2048 + k * 1024); } while (0)
; #define PG8_LDB(dst, b, h) do { _Pragma("unroll") for (int n = 0; n < 2; ++n) _Pragma("unroll") for (int k = 0; k < 2; ++k) dst[n][k] = *(const LAS bf16x8*)(lds + PG8_SB(b, h) + boff + n * 2048 + k * 1024); } while (0)
; #define PG8_WAIT_V(n) asm volatile("s_waitcnt vmcnt(" #n ")" ::: "memory")
; #define PG8_WAIT_L(n) asm volatile("s_waitcnt lgkmcnt(" #n ")" ::: "memory")
; #define PG8_BAR __builtin_amdgcn_s_barrier()
; #define PG8_SCHED __builtin_amdgcn_sched_barrier(0)
;     ...
;             PG8_LDB(B0, 0, 0); PG8_LDB(B1, 0, 1); PG8_SCHED; PG8_LDA(At, 0, 0); PG8_STAGEX(rsA, PG8_SA(1, 1), a1 + hstepA, voffA);
;             PG8_WAIT_V(8); PG8_WAIT_L(0); PG8_BAR; PG8_MMA(0, 0, At, B0); PG8_MMA(0, 1, At, B1); PG8_BAR; PG8_SCHED;
;             PG8_LDA(At, 0, 1); PG8_STAGEX(rsB, PG8_SB(0, 0), b2, voffB); PG8_STAGEX(rsB, PG8_SB(0, 1), b2 + hstepB, voffB); PG8_STAGEX(rsA, PG8_SA(0, 0), a2, voffA);
;             PG8_WAIT_V(8); PG8_WAIT_L(0); PG8_BAR; PG8_MMA(1, 0, At, B0); PG8_MMA(1, 1, At, B1); PG8_BAR; PG8_SCHED;
.LBB0_1377:
	v_add_u32_e32 v142, 0x10000, v185
	v_add_u32_e32 v158, 0x14000, v185
	ds_read_b128 v[130:133], v142
	ds_read_b128 v[134:137], v142 offset:1024
	ds_read_b128 v[138:141], v142 offset:2048
	ds_read_b128 v[142:145], v142 offset:3072
	ds_read_b128 v[146:149], v158
	ds_read_b128 v[150:153], v158 offset:1024
	ds_read_b128 v[154:157], v158 offset:2048
	ds_read_b128 v[158:161], v158 offset:3072
	s_add_i32 s50, s43, 0xfff40080
	s_cmp_eq_u32 s60, 12
	s_cselect_b32 s63, s30, s50
	s_cselect_b32 s62, s31, s59
	s_add_i32 s61, s63, 0x80
	s_mov_b32 m0, s23
	ds_read_b128 v[162:165], v186
	ds_read_b128 v[166:169], v186 offset:1024
	ds_read_b128 v[190:193], v186 offset:2048
	ds_read_b128 v[194:197], v186 offset:3072
	ds_read_b128 v[198:201], v186 offset:4096
	ds_read_b128 v[202:205], v186 offset:5120
	ds_read_b128 v[206:209], v186 offset:6144
	ds_read_b128 v[210:213], v186 offset:7168
	buffer_load_dwordx4 v173, s[76:79], s43 offen lds
	s_mov_b32 m0, s24
	s_nop 0
	buffer_load_dwordx4 v178, s[76:79], s43 offen lds
	s_waitcnt vmcnt(8)
	s_waitcnt lgkmcnt(0)
	s_barrier
	v_mfma_f32_16x16x32_bf16 v[126:129], v[130:133], v[162:165], v[126:129]
	v_mfma_f32_16x16x32_bf16 v[126:129], v[134:137], v[166:169], v[126:129]
	v_mfma_f32_16x16x32_bf16 v[122:125], v[142:145], v[166:169], v[122:125]
	v_mfma_f32_16x16x32_bf16 v[122:125], v[138:141], v[162:165], v[122:125]
	v_mfma_f32_16x16x32_bf16 v[114:117], v[138:141], v[190:193], v[114:117]
	v_mfma_f32_16x16x32_bf16 v[114:117], v[142:145], v[194:197], v[114:117]
	v_mfma_f32_16x16x32_bf16 v[118:121], v[134:137], v[194:197], v[118:121]
	v_mfma_f32_16x16x32_bf16 v[118:121], v[130:133], v[190:193], v[118:121]
	v_mfma_f32_16x16x32_bf16 v[110:113], v[130:133], v[198:201], v[110:113]
	v_mfma_f32_16x16x32_bf16 v[110:113], v[134:137], v[202:205], v[110:113]
	v_mfma_f32_16x16x32_bf16 v[106:109], v[142:145], v[202:205], v[106:109]
	v_mfma_f32_16x16x32_bf16 v[106:109], v[138:141], v[198:201], v[106:109]
	v_mfma_f32_16x16x32_bf16 v[98:101], v[138:141], v[206:209], v[98:101]
	v_mfma_f32_16x16x32_bf16 v[98:101], v[142:145], v[210:213], v[98:101]
	v_mfma_f32_16x16x32_bf16 v[102:105], v[134:137], v[210:213], v[102:105]
	v_mfma_f32_16x16x32_bf16 v[102:105], v[130:133], v[206:209], v[102:105]
	v_mfma_f32_16x16x32_bf16 v[94:97], v[146:149], v[162:165], v[94:97]
	v_mfma_f32_16x16x32_bf16 v[94:97], v[150:153], v[166:169], v[94:97]
	v_mfma_f32_16x16x32_bf16 v[90:93], v[158:161], v[166:169], v[90:93]
	v_mfma_f32_16x16x32_bf16 v[90:93], v[154:157], v[162:165], v[90:93]
	v_mfma_f32_16x16x32_bf16 v[82:85], v[154:157], v[190:193], v[82:85]
	v_mfma_f32_16x16x32_bf16 v[82:85], v[158:161], v[194:197], v[82:85]
	v_mfma_f32_16x16x32_bf16 v[86:89], v[150:153], v[194:197], v[86:89]
	v_mfma_f32_16x16x32_bf16 v[86:89], v[146:149], v[190:193], v[86:89]
	v_mfma_f32_16x16x32_bf16 v[78:81], v[146:149], v[198:201], v[78:81]
	v_mfma_f32_16x16x32_bf16 v[78:81], v[150:153], v[202:205], v[78:81]
	v_mfma_f32_16x16x32_bf16 v[74:77], v[158:161], v[202:205], v[74:77]
	v_mfma_f32_16x16x32_bf16 v[74:77], v[154:157], v[198:201], v[74:77]
	v_mfma_f32_16x16x32_bf16 v[66:69], v[154:157], v[206:209], v[66:69]
	v_mfma_f32_16x16x32_bf16 v[66:69], v[158:161], v[210:213], v[66:69]
	v_mfma_f32_16x16x32_bf16 v[70:73], v[150:153], v[210:213], v[70:73]
	v_mfma_f32_16x16x32_bf16 v[70:73], v[146:149], v[206:209], v[70:73]
	s_barrier
	s_mov_b32 m0, s7
	s_mov_b32 s50, s78
	s_mov_b32 s51, s79
	ds_read_b128 v[162:165], v186 offset:16384
	ds_read_b128 v[166:169], v186 offset:17408
	ds_read_b128 v[190:193], v186 offset:18432
	ds_read_b128 v[194:197], v186 offset:19456
	ds_read_b128 v[198:201], v186 offset:20480
	ds_read_b128 v[202:205], v186 offset:21504
	ds_read_b128 v[206:209], v186 offset:22528
	ds_read_b128 v[210:213], v186 offset:23552
	buffer_load_dwordx4 v177, s[48:51], s62 offen lds
	s_mov_b32 m0, s11
	s_add_i32 s64, s62, 0x40000
	buffer_load_dwordx4 v179, s[48:51], s62 offen lds
	s_mov_b32 m0, s12
	s_nop 0
	buffer_load_dwordx4 v177, s[48:51], s64 offen lds
	s_mov_b32 m0, s13
	s_nop 0
	buffer_load_dwordx4 v179, s[48:51], s64 offen lds
	s_mov_b32 m0, s5
	s_nop 0
	buffer_load_dwordx4 v173, s[76:79], s63 offen lds
	s_mov_b32 m0, s14
	s_nop 0
	buffer_load_dwordx4 v178, s[76:79], s63 offen lds
	s_waitcnt vmcnt(8)
	s_waitcnt lgkmcnt(0)
	s_barrier
	v_mfma_f32_16x16x32_bf16 v[62:65], v[130:133], v[162:165], v[62:65]
	v_mfma_f32_16x16x32_bf16 v[62:65], v[134:137], v[166:169], v[62:65]
	v_mfma_f32_16x16x32_bf16 v[58:61], v[142:145], v[166:169], v[58:61]
	v_mfma_f32_16x16x32_bf16 v[58:61], v[138:141], v[162:165], v[58:61]
	v_mfma_f32_16x16x32_bf16 v[50:53], v[138:141], v[190:193], v[50:53]
	v_mfma_f32_16x16x32_bf16 v[50:53], v[142:145], v[194:197], v[50:53]
	v_mfma_f32_16x16x32_bf16 v[54:57], v[134:137], v[194:197], v[54:57]
	v_mfma_f32_16x16x32_bf16 v[54:57], v[130:133], v[190:193], v[54:57]
	v_mfma_f32_16x16x32_bf16 v[46:49], v[130:133], v[198:201], v[46:49]
	v_mfma_f32_16x16x32_bf16 v[46:49], v[134:137], v[202:205], v[46:49]
	v_mfma_f32_16x16x32_bf16 v[42:45], v[142:145], v[202:205], v[42:45]
	v_mfma_f32_16x16x32_bf16 v[42:45], v[138:141], v[198:201], v[42:45]
	v_mfma_f32_16x16x32_bf16 v[34:37], v[138:141], v[206:209], v[34:37]
	v_mfma_f32_16x16x32_bf16 v[34:37], v[142:145], v[210:213], v[34:37]
	v_mfma_f32_16x16x32_bf16 v[38:41], v[134:137], v[210:213], v[38:41]
	v_mfma_f32_16x16x32_bf16 v[38:41], v[130:133], v[206:209], v[38:41]
	v_mfma_f32_16x16x32_bf16 v[30:33], v[146:149], v[162:165], v[30:33]
	v_mfma_f32_16x16x32_bf16 v[30:33], v[150:153], v[166:169], v[30:33]
	v_mfma_f32_16x16x32_bf16 v[26:29], v[158:161], v[166:169], v[26:29]
	v_mfma_f32_16x16x32_bf16 v[26:29], v[154:157], v[162:165], v[26:29]
	v_mfma_f32_16x16x32_bf16 v[18:21], v[154:157], v[190:193], v[18:21]
	v_mfma_f32_16x16x32_bf16 v[18:21], v[158:161], v[194:197], v[18:21]
	v_mfma_f32_16x16x32_bf16 v[22:25], v[150:153], v[194:197], v[22:25]
	v_mfma_f32_16x16x32_bf16 v[22:25], v[146:149], v[190:193], v[22:25]
	v_mfma_f32_16x16x32_bf16 v[14:17], v[146:149], v[198:201], v[14:17]
	v_mfma_f32_16x16x32_bf16 v[14:17], v[150:153], v[202:205], v[14:17]
	v_mfma_f32_16x16x32_bf16 v[10:13], v[158:161], v[202:205], v[10:13]
	v_mfma_f32_16x16x32_bf16 v[10:13], v[154:157], v[198:201], v[10:13]
	v_mfma_f32_16x16x32_bf16 v[2:5], v[154:157], v[206:209], v[2:5]
	v_mfma_f32_16x16x32_bf16 v[2:5], v[158:161], v[210:213], v[2:5]
	v_mfma_f32_16x16x32_bf16 v[6:9], v[150:153], v[210:213], v[6:9]
	v_mfma_f32_16x16x32_bf16 v[6:9], v[146:149], v[206:209], v[6:9]
	s_barrier
; #define PG8_STAGEX(rs, bufoff, soff, voff) do { _Pragma("unroll") for (int _i = 0; _i < 2; ++_i) \
;         __builtin_amdgcn_raw_ptr_buffer_load_lds(rs, (LAS unsigned*)(lds + (bufoff) + ldsw + _i * 8192), 16, (voff)[_i], (soff), 0, 0); } while (0)
; #define PG8_LDA(dst, b, h) do { _Pragma("unroll") for (int m = 0; m < 4; ++m) _Pragma("unroll") for (int k = 0; k < 2; ++k) dst[m][k] = *(const LAS bf16x8*)(lds + PG8_SA(b, h) + aoff + m * 2048 + k * 1024); } while (0)
; #define PG8_LDB(dst, b, h) do { _Pragma("unroll") for (int n = 0; n < 2; ++n) _Pragma("unroll") for (int k = 0; k < 2; ++k) dst[n][k] = *(const LAS bf16x8*)(lds + PG8_SB(b, h) + boff + n * 2048 + k * 1024); } while (0)
; #define PG8_WAIT_V(n) asm volatile("s_waitcnt vmcnt(" #n ")" ::: "memory")
; #define PG8_WAIT_L(n) asm volatile("s_waitcnt lgkmcnt(" #n ")" ::: "memory")
; #define PG8_BAR __builtin_amdgcn_s_barrier()
; #define PG8_SCHED __builtin_amdgcn_sched_barrier(0)
;     ...
;             PG8_LDB(B0, 1, 0); PG8_LDB(B1, 1, 1); PG8_SCHED; PG8_LDA(At, 1, 0); PG8_STAGEX(rsA, PG8_SA(0, 1), a2 + hstepA, voffA);
;             PG8_WAIT_V(8); PG8_WAIT_L(0); PG8_BAR; PG8_MMA(0, 0, At, B0); PG8_MMA(0, 1, At, B1); PG8_BAR; PG8_SCHED;
;             PG8_LDA(At, 1, 1); PG8_STAGEX(rsB, PG8_SB(1, 0), b3, voffB); PG8_STAGEX(rsB, PG8_SB(1, 1), b3 + hstepB, voffB); PG8_STAGEX(rsA, PG8_SA(1, 0), a3, voffA);
;             PG8_WAIT_V(8); PG8_WAIT_L(0); PG8_BAR; PG8_MMA(1, 0, At, B0); PG8_MMA(1, 1, At, B1); PG8_BAR; PG8_SCHED;
;         }
;     ...
;         if (wr == 0) PG8_BAR;
	v_add_u32_e32 v142, 0x18000, v185
	v_add_u32_e32 v158, 0x1c000, v185
	ds_read_b128 v[130:133], v142
	ds_read_b128 v[134:137], v142 offset:1024
	ds_read_b128 v[138:141], v142 offset:2048
	ds_read_b128 v[142:145], v142 offset:3072
	ds_read_b128 v[146:149], v158
	ds_read_b128 v[150:153], v158 offset:1024
	ds_read_b128 v[154:157], v158 offset:2048
	ds_read_b128 v[158:161], v158 offset:3072
	s_add_i32 s63, s63, 0xc0000
	s_mov_b32 m0, s15
	ds_read_b128 v[162:165], v186 offset:32768
	ds_read_b128 v[166:169], v186 offset:33792
	ds_read_b128 v[190:193], v186 offset:34816
	ds_read_b128 v[194:197], v186 offset:35840
	ds_read_b128 v[198:201], v186 offset:36864
	ds_read_b128 v[202:205], v186 offset:37888
	ds_read_b128 v[206:209], v186 offset:38912
	ds_read_b128 v[210:213], v186 offset:39936
	buffer_load_dwordx4 v173, s[76:79], s63 offen lds
	s_mov_b32 m0, s16
	s_nop 0
	buffer_load_dwordx4 v178, s[76:79], s63 offen lds
	s_waitcnt vmcnt(8)
	s_waitcnt lgkmcnt(0)
	s_barrier
	v_mfma_f32_16x16x32_bf16 v[126:129], v[130:133], v[162:165], v[126:129]
	v_mfma_f32_16x16x32_bf16 v[126:129], v[134:137], v[166:169], v[126:129]
	v_mfma_f32_16x16x32_bf16 v[122:125], v[142:145], v[166:169], v[122:125]
	v_mfma_f32_16x16x32_bf16 v[122:125], v[138:141], v[162:165], v[122:125]
	v_mfma_f32_16x16x32_bf16 v[114:117], v[138:141], v[190:193], v[114:117]
	v_mfma_f32_16x16x32_bf16 v[114:117], v[142:145], v[194:197], v[114:117]
	v_mfma_f32_16x16x32_bf16 v[118:121], v[134:137], v[194:197], v[118:121]
	v_mfma_f32_16x16x32_bf16 v[118:121], v[130:133], v[190:193], v[118:121]
	v_mfma_f32_16x16x32_bf16 v[110:113], v[130:133], v[198:201], v[110:113]
	v_mfma_f32_16x16x32_bf16 v[110:113], v[134:137], v[202:205], v[110:113]
	v_mfma_f32_16x16x32_bf16 v[106:109], v[142:145], v[202:205], v[106:109]
	v_mfma_f32_16x16x32_bf16 v[106:109], v[138:141], v[198:201], v[106:109]
	v_mfma_f32_16x16x32_bf16 v[98:101], v[138:141], v[206:209], v[98:101]
	v_mfma_f32_16x16x32_bf16 v[98:101], v[142:145], v[210:213], v[98:101]
	v_mfma_f32_16x16x32_bf16 v[102:105], v[134:137], v[210:213], v[102:105]
	v_mfma_f32_16x16x32_bf16 v[102:105], v[130:133], v[206:209], v[102:105]
	v_mfma_f32_16x16x32_bf16 v[94:97], v[146:149], v[162:165], v[94:97]
	v_mfma_f32_16x16x32_bf16 v[94:97], v[150:153], v[166:169], v[94:97]
	v_mfma_f32_16x16x32_bf16 v[90:93], v[158:161], v[166:169], v[90:93]
	v_mfma_f32_16x16x32_bf16 v[90:93], v[154:157], v[162:165], v[90:93]
	v_mfma_f32_16x16x32_bf16 v[82:85], v[154:157], v[190:193], v[82:85]
	v_mfma_f32_16x16x32_bf16 v[82:85], v[158:161], v[194:197], v[82:85]
	v_mfma_f32_16x16x32_bf16 v[86:89], v[150:153], v[194:197], v[86:89]
	v_mfma_f32_16x16x32_bf16 v[86:89], v[146:149], v[190:193], v[86:89]
	v_mfma_f32_16x16x32_bf16 v[78:81], v[146:149], v[198:201], v[78:81]
	v_mfma_f32_16x16x32_bf16 v[78:81], v[150:153], v[202:205], v[78:81]
	v_mfma_f32_16x16x32_bf16 v[74:77], v[158:161], v[202:205], v[74:77]
	v_mfma_f32_16x16x32_bf16 v[74:77], v[154:157], v[198:201], v[74:77]
	v_mfma_f32_16x16x32_bf16 v[66:69], v[154:157], v[206:209], v[66:69]
	v_mfma_f32_16x16x32_bf16 v[66:69], v[158:161], v[210:213], v[66:69]
	v_mfma_f32_16x16x32_bf16 v[70:73], v[150:153], v[210:213], v[70:73]
	v_mfma_f32_16x16x32_bf16 v[70:73], v[146:149], v[206:209], v[70:73]
	s_barrier
	s_mov_b32 m0, s17
	s_add_i32 s63, s62, 0x80
	ds_read_b128 v[162:165], v186 offset:49152
	ds_read_b128 v[166:169], v186 offset:50176
	ds_read_b128 v[190:193], v186 offset:51200
	ds_read_b128 v[194:197], v186 offset:52224
	ds_read_b128 v[198:201], v186 offset:53248
	ds_read_b128 v[202:205], v186 offset:54272
	ds_read_b128 v[206:209], v186 offset:55296
	ds_read_b128 v[210:213], v186 offset:56320
	buffer_load_dwordx4 v177, s[48:51], s63 offen lds
	s_mov_b32 m0, s18
	s_add_i32 s62, s62, 0x40080
	buffer_load_dwordx4 v179, s[48:51], s63 offen lds
	s_mov_b32 m0, s21
	s_nop 0
	buffer_load_dwordx4 v177, s[48:51], s62 offen lds
	s_mov_b32 m0, s22
	s_nop 0
	buffer_load_dwordx4 v179, s[48:51], s62 offen lds
	s_mov_b32 m0, s19
	s_nop 0
	buffer_load_dwordx4 v173, s[76:79], s61 offen lds
	s_mov_b32 m0, s20
	s_nop 0
	buffer_load_dwordx4 v178, s[76:79], s61 offen lds
	s_waitcnt vmcnt(8)
	s_waitcnt lgkmcnt(0)
	s_barrier
	v_mfma_f32_16x16x32_bf16 v[62:65], v[130:133], v[162:165], v[62:65]
	v_mfma_f32_16x16x32_bf16 v[62:65], v[134:137], v[166:169], v[62:65]
	v_mfma_f32_16x16x32_bf16 v[58:61], v[142:145], v[166:169], v[58:61]
	v_mfma_f32_16x16x32_bf16 v[58:61], v[138:141], v[162:165], v[58:61]
	v_mfma_f32_16x16x32_bf16 v[50:53], v[138:141], v[190:193], v[50:53]
	v_mfma_f32_16x16x32_bf16 v[50:53], v[142:145], v[194:197], v[50:53]
	v_mfma_f32_16x16x32_bf16 v[54:57], v[134:137], v[194:197], v[54:57]
	v_mfma_f32_16x16x32_bf16 v[54:57], v[130:133], v[190:193], v[54:57]
	v_mfma_f32_16x16x32_bf16 v[46:49], v[130:133], v[198:201], v[46:49]
	v_mfma_f32_16x16x32_bf16 v[46:49], v[134:137], v[202:205], v[46:49]
	v_mfma_f32_16x16x32_bf16 v[42:45], v[142:145], v[202:205], v[42:45]
	v_mfma_f32_16x16x32_bf16 v[42:45], v[138:141], v[198:201], v[42:45]
	v_mfma_f32_16x16x32_bf16 v[34:37], v[138:141], v[206:209], v[34:37]
	v_mfma_f32_16x16x32_bf16 v[34:37], v[142:145], v[210:213], v[34:37]
	v_mfma_f32_16x16x32_bf16 v[38:41], v[134:137], v[210:213], v[38:41]
	v_mfma_f32_16x16x32_bf16 v[38:41], v[130:133], v[206:209], v[38:41]
	v_mfma_f32_16x16x32_bf16 v[30:33], v[146:149], v[162:165], v[30:33]
	v_mfma_f32_16x16x32_bf16 v[30:33], v[150:153], v[166:169], v[30:33]
	v_mfma_f32_16x16x32_bf16 v[26:29], v[158:161], v[166:169], v[26:29]
	v_mfma_f32_16x16x32_bf16 v[26:29], v[154:157], v[162:165], v[26:29]
	v_mfma_f32_16x16x32_bf16 v[18:21], v[154:157], v[190:193], v[18:21]
	v_mfma_f32_16x16x32_bf16 v[18:21], v[158:161], v[194:197], v[18:21]
	v_mfma_f32_16x16x32_bf16 v[22:25], v[150:153], v[194:197], v[22:25]
	v_mfma_f32_16x16x32_bf16 v[22:25], v[146:149], v[190:193], v[22:25]
	v_mfma_f32_16x16x32_bf16 v[14:17], v[146:149], v[198:201], v[14:17]
	v_mfma_f32_16x16x32_bf16 v[14:17], v[150:153], v[202:205], v[14:17]
	v_mfma_f32_16x16x32_bf16 v[10:13], v[158:161], v[202:205], v[10:13]
	v_mfma_f32_16x16x32_bf16 v[10:13], v[154:157], v[198:201], v[10:13]
	v_mfma_f32_16x16x32_bf16 v[2:5], v[154:157], v[206:209], v[2:5]
	v_mfma_f32_16x16x32_bf16 v[2:5], v[158:161], v[210:213], v[2:5]
	v_mfma_f32_16x16x32_bf16 v[6:9], v[150:153], v[210:213], v[6:9]
	v_mfma_f32_16x16x32_bf16 v[6:9], v[146:149], v[206:209], v[6:9]
	s_barrier
	s_add_i32 s60, s60, 2
	s_addk_i32 s43, 0x100
	s_addk_i32 s59, 0x100
	s_cmp_gt_u32 s60, 13
	s_cbranch_scc0 .LBB0_1377
	s_setprio 0
	s_and_b64 vcc, exec, s[52:53]
	s_cbranch_vccz .LBB0_1380
	s_barrier

;     ...
;         bool has_next; if constexpr (QV == 2) has_next = S.next_tail(ui + 1, nxt); else has_next = S.next(ui + 1, nxt);
;         const unsigned nA = has_next ? (unsigned)nxt.pm * tstepA + nxt.aoff : cA, nB = has_next ? (unsigned)nxt.pn * tstepB + nxt.boff : cB;
;         if constexpr (QV == 0) {
; #pragma nounroll
;         for (int t = 0; t < nt; t += 2) {
;             const bool last = (t == nt - 2);
;             const unsigned a1 = cA + (unsigned)(t + 1) * kstep;
;             const unsigned a2 = last ? nA : cA + (unsigned)(t + 2) * kstep, b2 = last ? nB : cB + (unsigned)(t + 2) * kstep;
;             const unsigned a3 = a2 + kstep, b3 = b2 + kstep;
;     ...
;         if (!cur.keep) {
; #pragma unroll
;             for (int a = 0; a < 2; ++a)
; #pragma unroll
;                 for (int b = 0; b < 2; ++b)
; #pragma unroll
;                     for (int m = 0; m < 4; ++m)
; #pragma unroll
;                         for (int n = 0; n < 2; ++n) { f32x2 z0, z1; asm("v_mov_b64 %0, 0\n\tv_mov_b64 %1, 0" : "=v"(z0), "=v"(z1));
;                     acc[a][b][m][n] = __builtin_shufflevector(z0, z1, 0, 1, 2, 3); }
.LBB0_1528:
	s_lshl_b32 s86, s65, 20
	s_and_b64 s[30:31], s[60:61], exec
	s_cselect_b32 s30, s86, s59
	s_lshl_b32 s87, s47, 20
	s_mov_b32 s84, s47
	s_and_b64 s[46:47], s[60:61], exec
	s_waitcnt lgkmcnt(0)
	v_mov_b64_e32 v[8:9], v[4:5]
	v_mov_b64_e32 v[12:13], v[4:5]
	v_mov_b64_e32 v[16:17], v[4:5]
	v_mov_b64_e32 v[20:21], v[4:5]
	v_mov_b64_e32 v[24:25], v[4:5]
	s_waitcnt vmcnt(15)
	v_mov_b64_e32 v[28:29], v[4:5]
	v_mov_b64_e32 v[32:33], v[4:5]
	v_mov_b64_e32 v[68:69], v[4:5]
	v_mov_b64_e32 v[72:73], v[4:5]
	v_mov_b64_e32 v[76:77], v[4:5]
	v_mov_b64_e32 v[80:81], v[4:5]
	v_mov_b64_e32 v[84:85], v[4:5]
	v_mov_b64_e32 v[88:89], v[4:5]
	v_mov_b64_e32 v[92:93], v[4:5]
	v_mov_b64_e32 v[96:97], v[4:5]
	v_mov_b64_e32 v[36:37], v[4:5]
	v_mov_b64_e32 v[40:41], v[4:5]
	v_mov_b64_e32 v[44:45], v[4:5]
	v_mov_b64_e32 v[48:49], v[4:5]
	v_mov_b64_e32 v[52:53], v[4:5]
	v_mov_b64_e32 v[56:57], v[4:5]
	v_mov_b64_e32 v[60:61], v[4:5]
	v_mov_b64_e32 v[64:65], v[4:5]
	v_mov_b64_e32 v[100:101], v[4:5]
	v_mov_b64_e32 v[104:105], v[4:5]
	v_mov_b64_e32 v[136:137], v[4:5]
	v_mov_b64_e32 v[140:141], v[4:5]
	v_mov_b64_e32 v[148:149], v[4:5]
	v_mov_b64_e32 v[152:153], v[4:5]
	v_mov_b64_e32 v[156:157], v[4:5]
	v_mov_b64_e32 v[160:161], v[4:5]
	s_mov_b32 s85, s65
	s_cselect_b32 s31, s87, s63
	s_add_i32 s59, s59, 0x80080
	s_addk_i32 s63, 0x100
	s_mov_b32 s64, -2
	v_mov_b64_e32 v[6:7], v[2:3]
	v_mov_b64_e32 v[10:11], v[2:3]
	v_mov_b64_e32 v[14:15], v[2:3]
	v_mov_b64_e32 v[18:19], v[2:3]
	v_mov_b64_e32 v[22:23], v[2:3]
	v_mov_b64_e32 v[26:27], v[2:3]
	v_mov_b64_e32 v[30:31], v[2:3]
	v_mov_b64_e32 v[66:67], v[2:3]
	v_mov_b64_e32 v[70:71], v[2:3]
	v_mov_b64_e32 v[74:75], v[2:3]
	v_mov_b64_e32 v[78:79], v[2:3]
	v_mov_b64_e32 v[82:83], v[2:3]
	v_mov_b64_e32 v[86:87], v[2:3]
	v_mov_b64_e32 v[90:91], v[2:3]
	v_mov_b64_e32 v[94:95], v[2:3]
	v_mov_b64_e32 v[34:35], v[2:3]
	v_mov_b64_e32 v[38:39], v[2:3]
	v_mov_b64_e32 v[42:43], v[2:3]
	v_mov_b64_e32 v[46:47], v[2:3]
	v_mov_b64_e32 v[50:51], v[2:3]
	v_mov_b64_e32 v[54:55], v[2:3]
	v_mov_b64_e32 v[58:59], v[2:3]
	v_mov_b64_e32 v[62:63], v[2:3]
	v_mov_b64_e32 v[98:99], v[2:3]
	v_mov_b64_e32 v[102:103], v[2:3]
	v_mov_b64_e32 v[134:135], v[2:3]
	v_mov_b64_e32 v[138:139], v[2:3]
	v_mov_b64_e32 v[146:147], v[2:3]
	v_mov_b64_e32 v[150:151], v[2:3]
	v_mov_b64_e32 v[154:155], v[2:3]
	v_mov_b64_e32 v[158:159], v[2:3]
	s_and_b64 vcc, exec, s[50:51]
	s_cbranch_vccz .Lsp_1529
	s_setprio 1

; #define PG8_STAGEX(rs, bufoff, soff, voff) do { _Pragma("unroll") for (int _i = 0; _i < 2; ++_i) \
;         __builtin_amdgcn_raw_ptr_buffer_load_lds(rs, (LAS unsigned*)(lds + (bufoff) + ldsw + _i * 8192), 16, (voff)[_i], (soff), 0, 0); } while (0)
; #define PG8_LDA(dst, b, h) do { _Pragma("unroll") for (int m = 0; m < 4; ++m) _Pragma("unroll") for (int k = 0; k < 2; ++k) dst[m][k] = *(const LAS bf16x8*)(lds + PG8_SA(b, h) + aoff + m * 2048 + k * 1024); } while (0)
; #define PG8_LDB(dst, b, h) do { _Pragma("unroll") for (int n = 0; n < 2; ++n) _Pragma("unroll") for (int k = 0; k < 2; ++k) dst[n][k] = *(const LAS bf16x8*)(lds + PG8_SB(b, h) + boff + n * 2048 + k * 1024); } while (0)
; #define PG8_WAIT_V(n) asm volatile("s_waitcnt vmcnt(" #n ")" ::: "memory")
; #define PG8_WAIT_L(n) asm volatile("s_waitcnt lgkmcnt(" #n ")" ::: "memory")
; #define PG8_BAR __builtin_amdgcn_s_barrier()
; #define PG8_SCHED __builtin_amdgcn_sched_barrier(0)
;     ...
;             PG8_LDB(B0, 0, 0); PG8_LDB(B1, 0, 1); PG8_SCHED; PG8_LDA(At, 0, 0); PG8_STAGEX(rsA, PG8_SA(1, 1), a1 + hstepA, voffA);
;             PG8_WAIT_V(8); PG8_WAIT_L(0); PG8_BAR; PG8_MMA(0, 0, At, B0); PG8_MMA(0, 1, At, B1); PG8_BAR; PG8_SCHED;
;             PG8_LDA(At, 0, 1); PG8_STAGEX(rsB, PG8_SB(0, 0), b2, voffB); PG8_STAGEX(rsB, PG8_SB(0, 1), b2 + hstepB, voffB); PG8_STAGEX(rsA, PG8_SA(0, 0), a2, voffA);
;             PG8_WAIT_V(8); PG8_WAIT_L(0); PG8_BAR; PG8_MMA(1, 0, At, B0); PG8_MMA(1, 1, At, B1); PG8_BAR; PG8_SCHED;
.LBB0_1529:
	v_add_u32_e32 v118, 0x10000, v210
	v_add_u32_e32 v142, 0x14000, v210
	ds_read_b128 v[106:109], v118
	ds_read_b128 v[110:113], v118 offset:1024
	ds_read_b128 v[114:117], v118 offset:2048
	ds_read_b128 v[118:121], v118 offset:3072
	ds_read_b128 v[122:125], v142
	ds_read_b128 v[126:129], v142 offset:1024
	ds_read_b128 v[130:133], v142 offset:2048
	ds_read_b128 v[142:145], v142 offset:3072
	s_add_i32 s46, s59, 0xfff80080
	s_cmp_eq_u32 s64, 28
	s_cselect_b32 s67, s30, s46
	s_cselect_b32 s66, s31, s63
	s_or_b32 s65, s67, 0x80
	s_mov_b32 m0, s76
	ds_read_b128 v[164:167], v211
	ds_read_b128 v[168:171], v211 offset:1024
	ds_read_b128 v[182:185], v211 offset:2048
	ds_read_b128 v[186:189], v211 offset:3072
	ds_read_b128 v[190:193], v211 offset:4096
	ds_read_b128 v[194:197], v211 offset:5120
	ds_read_b128 v[198:201], v211 offset:6144
	ds_read_b128 v[202:205], v211 offset:7168
	buffer_load_dwordx4 v178, s[40:43], s59 offen lds
	s_mov_b32 m0, s77
	s_nop 0
	buffer_load_dwordx4 v206, s[40:43], s59 offen lds
	s_waitcnt vmcnt(8)
	s_waitcnt lgkmcnt(0)
	s_barrier
	v_mfma_f32_16x16x32_bf16 v[158:161], v[106:109], v[164:167], v[158:161]
	v_mfma_f32_16x16x32_bf16 v[158:161], v[110:113], v[168:171], v[158:161]
	v_mfma_f32_16x16x32_bf16 v[154:157], v[118:121], v[168:171], v[154:157]
	v_mfma_f32_16x16x32_bf16 v[154:157], v[114:117], v[164:167], v[154:157]
	v_mfma_f32_16x16x32_bf16 v[146:149], v[114:117], v[182:185], v[146:149]
	v_mfma_f32_16x16x32_bf16 v[146:149], v[118:121], v[186:189], v[146:149]
	v_mfma_f32_16x16x32_bf16 v[150:153], v[110:113], v[186:189], v[150:153]
	v_mfma_f32_16x16x32_bf16 v[150:153], v[106:109], v[182:185], v[150:153]
	v_mfma_f32_16x16x32_bf16 v[138:141], v[106:109], v[190:193], v[138:141]
	v_mfma_f32_16x16x32_bf16 v[138:141], v[110:113], v[194:197], v[138:141]
	v_mfma_f32_16x16x32_bf16 v[134:137], v[118:121], v[194:197], v[134:137]
	v_mfma_f32_16x16x32_bf16 v[134:137], v[114:117], v[190:193], v[134:137]
	v_mfma_f32_16x16x32_bf16 v[98:101], v[114:117], v[198:201], v[98:101]
	v_mfma_f32_16x16x32_bf16 v[98:101], v[118:121], v[202:205], v[98:101]
	v_mfma_f32_16x16x32_bf16 v[102:105], v[110:113], v[202:205], v[102:105]
	v_mfma_f32_16x16x32_bf16 v[102:105], v[106:109], v[198:201], v[102:105]
	v_mfma_f32_16x16x32_bf16 v[62:65], v[122:125], v[164:167], v[62:65]
	v_mfma_f32_16x16x32_bf16 v[62:65], v[126:129], v[168:171], v[62:65]
	v_mfma_f32_16x16x32_bf16 v[58:61], v[142:145], v[168:171], v[58:61]
	v_mfma_f32_16x16x32_bf16 v[58:61], v[130:133], v[164:167], v[58:61]
	v_mfma_f32_16x16x32_bf16 v[50:53], v[130:133], v[182:185], v[50:53]
	v_mfma_f32_16x16x32_bf16 v[50:53], v[142:145], v[186:189], v[50:53]
	v_mfma_f32_16x16x32_bf16 v[54:57], v[126:129], v[186:189], v[54:57]
	v_mfma_f32_16x16x32_bf16 v[54:57], v[122:125], v[182:185], v[54:57]
	v_mfma_f32_16x16x32_bf16 v[46:49], v[122:125], v[190:193], v[46:49]
	v_mfma_f32_16x16x32_bf16 v[46:49], v[126:129], v[194:197], v[46:49]
	v_mfma_f32_16x16x32_bf16 v[42:45], v[142:145], v[194:197], v[42:45]
	v_mfma_f32_16x16x32_bf16 v[42:45], v[130:133], v[190:193], v[42:45]
	v_mfma_f32_16x16x32_bf16 v[34:37], v[130:133], v[198:201], v[34:37]
	v_mfma_f32_16x16x32_bf16 v[34:37], v[142:145], v[202:205], v[34:37]
	v_mfma_f32_16x16x32_bf16 v[38:41], v[126:129], v[202:205], v[38:41]
	v_mfma_f32_16x16x32_bf16 v[38:41], v[122:125], v[198:201], v[38:41]
	s_barrier
	s_mov_b32 m0, s17
	s_mov_b32 s46, s42
	s_mov_b32 s47, s43
	ds_read_b128 v[164:167], v211 offset:16384
	ds_read_b128 v[168:171], v211 offset:17408
	ds_read_b128 v[182:185], v211 offset:18432
	ds_read_b128 v[186:189], v211 offset:19456
	ds_read_b128 v[190:193], v211 offset:20480
	ds_read_b128 v[194:197], v211 offset:21504
	ds_read_b128 v[198:201], v211 offset:22528
	ds_read_b128 v[202:205], v211 offset:23552
	buffer_load_dwordx4 v179, s[44:47], s66 offen lds
	s_mov_b32 m0, s18
	s_add_i32 s68, s66, 0x80000
	buffer_load_dwordx4 v207, s[44:47], s66 offen lds
	s_mov_b32 m0, s19
	s_nop 0
	buffer_load_dwordx4 v179, s[44:47], s68 offen lds
	s_mov_b32 m0, s20
	s_nop 0
	buffer_load_dwordx4 v207, s[44:47], s68 offen lds
	s_mov_b32 m0, s16
	s_nop 0
	buffer_load_dwordx4 v178, s[40:43], s67 offen lds
	s_mov_b32 m0, s21
	s_nop 0
	buffer_load_dwordx4 v206, s[40:43], s67 offen lds
	s_waitcnt vmcnt(8)
	s_waitcnt lgkmcnt(0)
	s_barrier
	v_mfma_f32_16x16x32_bf16 v[94:97], v[106:109], v[164:167], v[94:97]
	v_mfma_f32_16x16x32_bf16 v[94:97], v[110:113], v[168:171], v[94:97]
	v_mfma_f32_16x16x32_bf16 v[90:93], v[118:121], v[168:171], v[90:93]
	v_mfma_f32_16x16x32_bf16 v[90:93], v[114:117], v[164:167], v[90:93]
	v_mfma_f32_16x16x32_bf16 v[82:85], v[114:117], v[182:185], v[82:85]
	v_mfma_f32_16x16x32_bf16 v[82:85], v[118:121], v[186:189], v[82:85]
	v_mfma_f32_16x16x32_bf16 v[86:89], v[110:113], v[186:189], v[86:89]
	v_mfma_f32_16x16x32_bf16 v[86:89], v[106:109], v[182:185], v[86:89]
	v_mfma_f32_16x16x32_bf16 v[78:81], v[106:109], v[190:193], v[78:81]
	v_mfma_f32_16x16x32_bf16 v[78:81], v[110:113], v[194:197], v[78:81]
	v_mfma_f32_16x16x32_bf16 v[74:77], v[118:121], v[194:197], v[74:77]
	v_mfma_f32_16x16x32_bf16 v[74:77], v[114:117], v[190:193], v[74:77]
	v_mfma_f32_16x16x32_bf16 v[66:69], v[114:117], v[198:201], v[66:69]
	v_mfma_f32_16x16x32_bf16 v[66:69], v[118:121], v[202:205], v[66:69]
	v_mfma_f32_16x16x32_bf16 v[70:73], v[110:113], v[202:205], v[70:73]
	v_mfma_f32_16x16x32_bf16 v[70:73], v[106:109], v[198:201], v[70:73]
	v_mfma_f32_16x16x32_bf16 v[30:33], v[122:125], v[164:167], v[30:33]
	v_mfma_f32_16x16x32_bf16 v[30:33], v[126:129], v[168:171], v[30:33]
	v_mfma_f32_16x16x32_bf16 v[26:29], v[142:145], v[168:171], v[26:29]
	v_mfma_f32_16x16x32_bf16 v[26:29], v[130:133], v[164:167], v[26:29]
	v_mfma_f32_16x16x32_bf16 v[18:21], v[130:133], v[182:185], v[18:21]
	v_mfma_f32_16x16x32_bf16 v[18:21], v[142:145], v[186:189], v[18:21]
	v_mfma_f32_16x16x32_bf16 v[22:25], v[126:129], v[186:189], v[22:25]
	v_mfma_f32_16x16x32_bf16 v[22:25], v[122:125], v[182:185], v[22:25]
	v_mfma_f32_16x16x32_bf16 v[14:17], v[122:125], v[190:193], v[14:17]
	v_mfma_f32_16x16x32_bf16 v[14:17], v[126:129], v[194:197], v[14:17]
	v_mfma_f32_16x16x32_bf16 v[10:13], v[142:145], v[194:197], v[10:13]
	v_mfma_f32_16x16x32_bf16 v[10:13], v[130:133], v[190:193], v[10:13]
	v_mfma_f32_16x16x32_bf16 v[2:5], v[130:133], v[198:201], v[2:5]
	v_mfma_f32_16x16x32_bf16 v[2:5], v[142:145], v[202:205], v[2:5]
	v_mfma_f32_16x16x32_bf16 v[6:9], v[126:129], v[202:205], v[6:9]
	v_mfma_f32_16x16x32_bf16 v[6:9], v[122:125], v[198:201], v[6:9]
	s_barrier
; #define PG8_STAGEX(rs, bufoff, soff, voff) do { _Pragma("unroll") for (int _i = 0; _i < 2; ++_i) \
;         __builtin_amdgcn_raw_ptr_buffer_load_lds(rs, (LAS unsigned*)(lds + (bufoff) + ldsw + _i * 8192), 16, (voff)[_i], (soff), 0, 0); } while (0)
; #define PG8_LDA(dst, b, h) do { _Pragma("unroll") for (int m = 0; m < 4; ++m) _Pragma("unroll") for (int k = 0; k < 2; ++k) dst[m][k] = *(const LAS bf16x8*)(lds + PG8_SA(b, h) + aoff + m * 2048 + k * 1024); } while (0)
; #define PG8_LDB(dst, b, h) do { _Pragma("unroll") for (int n = 0; n < 2; ++n) _Pragma("unroll") for (int k = 0; k < 2; ++k) dst[n][k] = *(const LAS bf16x8*)(lds + PG8_SB(b, h) + boff + n * 2048 + k * 1024); } while (0)
; #define PG8_WAIT_V(n) asm volatile("s_waitcnt vmcnt(" #n ")" ::: "memory")
; #define PG8_WAIT_L(n) asm volatile("s_waitcnt lgkmcnt(" #n ")" ::: "memory")
; #define PG8_BAR __builtin_amdgcn_s_barrier()
; #define PG8_SCHED __builtin_amdgcn_sched_barrier(0)
;     ...
;             PG8_LDB(B0, 1, 0); PG8_LDB(B1, 1, 1); PG8_SCHED; PG8_LDA(At, 1, 0); PG8_STAGEX(rsA, PG8_SA(0, 1), a2 + hstepA, voffA);
;             PG8_WAIT_V(8); PG8_WAIT_L(0); PG8_BAR; PG8_MMA(0, 0, At, B0); PG8_MMA(0, 1, At, B1); PG8_BAR; PG8_SCHED;
;             PG8_LDA(At, 1, 1); PG8_STAGEX(rsB, PG8_SB(1, 0), b3, voffB); PG8_STAGEX(rsB, PG8_SB(1, 1), b3 + hstepB, voffB); PG8_STAGEX(rsA, PG8_SA(1, 0), a3, voffA);
;             PG8_WAIT_V(8); PG8_WAIT_L(0); PG8_BAR; PG8_MMA(1, 0, At, B0); PG8_MMA(1, 1, At, B1); PG8_BAR; PG8_SCHED;
;         }
;     ...
;         if (wr == 0) PG8_BAR;
	v_add_u32_e32 v118, 0x18000, v210
	v_add_u32_e32 v142, 0x1c000, v210
	ds_read_b128 v[106:109], v118
	ds_read_b128 v[110:113], v118 offset:1024
	ds_read_b128 v[114:117], v118 offset:2048
	ds_read_b128 v[118:121], v118 offset:3072
	ds_read_b128 v[122:125], v142
	ds_read_b128 v[126:129], v142 offset:1024
	ds_read_b128 v[130:133], v142 offset:2048
	ds_read_b128 v[142:145], v142 offset:3072
	s_add_i32 s67, s67, 0x80000
	s_mov_b32 m0, s22
	ds_read_b128 v[164:167], v211 offset:32768
	ds_read_b128 v[168:171], v211 offset:33792
	ds_read_b128 v[182:185], v211 offset:34816
	ds_read_b128 v[186:189], v211 offset:35840
	ds_read_b128 v[190:193], v211 offset:36864
	ds_read_b128 v[194:197], v211 offset:37888
	ds_read_b128 v[198:201], v211 offset:38912
	ds_read_b128 v[202:205], v211 offset:39936
	buffer_load_dwordx4 v178, s[40:43], s67 offen lds
	s_mov_b32 m0, s23
	s_nop 0
	buffer_load_dwordx4 v206, s[40:43], s67 offen lds
	s_waitcnt vmcnt(8)
	s_waitcnt lgkmcnt(0)
	s_barrier
	v_mfma_f32_16x16x32_bf16 v[158:161], v[106:109], v[164:167], v[158:161]
	v_mfma_f32_16x16x32_bf16 v[158:161], v[110:113], v[168:171], v[158:161]
	v_mfma_f32_16x16x32_bf16 v[154:157], v[118:121], v[168:171], v[154:157]
	v_mfma_f32_16x16x32_bf16 v[154:157], v[114:117], v[164:167], v[154:157]
	v_mfma_f32_16x16x32_bf16 v[146:149], v[114:117], v[182:185], v[146:149]
	v_mfma_f32_16x16x32_bf16 v[146:149], v[118:121], v[186:189], v[146:149]
	v_mfma_f32_16x16x32_bf16 v[150:153], v[110:113], v[186:189], v[150:153]
	v_mfma_f32_16x16x32_bf16 v[150:153], v[106:109], v[182:185], v[150:153]
	v_mfma_f32_16x16x32_bf16 v[138:141], v[106:109], v[190:193], v[138:141]
	v_mfma_f32_16x16x32_bf16 v[138:141], v[110:113], v[194:197], v[138:141]
	v_mfma_f32_16x16x32_bf16 v[134:137], v[118:121], v[194:197], v[134:137]
	v_mfma_f32_16x16x32_bf16 v[134:137], v[114:117], v[190:193], v[134:137]
	v_mfma_f32_16x16x32_bf16 v[98:101], v[114:117], v[198:201], v[98:101]
	v_mfma_f32_16x16x32_bf16 v[98:101], v[118:121], v[202:205], v[98:101]
	v_mfma_f32_16x16x32_bf16 v[102:105], v[110:113], v[202:205], v[102:105]
	v_mfma_f32_16x16x32_bf16 v[102:105], v[106:109], v[198:201], v[102:105]
	v_mfma_f32_16x16x32_bf16 v[62:65], v[122:125], v[164:167], v[62:65]
	v_mfma_f32_16x16x32_bf16 v[62:65], v[126:129], v[168:171], v[62:65]
	v_mfma_f32_16x16x32_bf16 v[58:61], v[142:145], v[168:171], v[58:61]
	v_mfma_f32_16x16x32_bf16 v[58:61], v[130:133], v[164:167], v[58:61]
	v_mfma_f32_16x16x32_bf16 v[50:53], v[130:133], v[182:185], v[50:53]
	v_mfma_f32_16x16x32_bf16 v[50:53], v[142:145], v[186:189], v[50:53]
	v_mfma_f32_16x16x32_bf16 v[54:57], v[126:129], v[186:189], v[54:57]
	v_mfma_f32_16x16x32_bf16 v[54:57], v[122:125], v[182:185], v[54:57]
	v_mfma_f32_16x16x32_bf16 v[46:49], v[122:125], v[190:193], v[46:49]
	v_mfma_f32_16x16x32_bf16 v[46:49], v[126:129], v[194:197], v[46:49]
	v_mfma_f32_16x16x32_bf16 v[42:45], v[142:145], v[194:197], v[42:45]
	v_mfma_f32_16x16x32_bf16 v[42:45], v[130:133], v[190:193], v[42:45]
	v_mfma_f32_16x16x32_bf16 v[34:37], v[130:133], v[198:201], v[34:37]
	v_mfma_f32_16x16x32_bf16 v[34:37], v[142:145], v[202:205], v[34:37]
	v_mfma_f32_16x16x32_bf16 v[38:41], v[126:129], v[202:205], v[38:41]
	v_mfma_f32_16x16x32_bf16 v[38:41], v[122:125], v[198:201], v[38:41]
	s_barrier
	s_mov_b32 m0, s54
	s_or_b32 s67, s66, 0x80
	ds_read_b128 v[164:167], v211 offset:49152
	ds_read_b128 v[168:171], v211 offset:50176
	ds_read_b128 v[182:185], v211 offset:51200
	ds_read_b128 v[186:189], v211 offset:52224
	ds_read_b128 v[190:193], v211 offset:53248
	ds_read_b128 v[194:197], v211 offset:54272
	ds_read_b128 v[198:201], v211 offset:55296
	ds_read_b128 v[202:205], v211 offset:56320
	buffer_load_dwordx4 v179, s[44:47], s67 offen lds
	s_mov_b32 m0, s55
	s_add_i32 s66, s66, 0x80080
	buffer_load_dwordx4 v207, s[44:47], s67 offen lds
	s_mov_b32 m0, s74
	s_nop 0
	buffer_load_dwordx4 v179, s[44:47], s66 offen lds
	s_mov_b32 m0, s75
	s_nop 0
	buffer_load_dwordx4 v207, s[44:47], s66 offen lds
	s_mov_b32 m0, s72
	s_nop 0
	buffer_load_dwordx4 v178, s[40:43], s65 offen lds
	s_mov_b32 m0, s73
	s_nop 0
	buffer_load_dwordx4 v206, s[40:43], s65 offen lds
	s_waitcnt vmcnt(8)
	s_waitcnt lgkmcnt(0)
	s_barrier
	v_mfma_f32_16x16x32_bf16 v[94:97], v[106:109], v[164:167], v[94:97]
	v_mfma_f32_16x16x32_bf16 v[94:97], v[110:113], v[168:171], v[94:97]
	v_mfma_f32_16x16x32_bf16 v[90:93], v[118:121], v[168:171], v[90:93]
	v_mfma_f32_16x16x32_bf16 v[90:93], v[114:117], v[164:167], v[90:93]
	v_mfma_f32_16x16x32_bf16 v[82:85], v[114:117], v[182:185], v[82:85]
	v_mfma_f32_16x16x32_bf16 v[82:85], v[118:121], v[186:189], v[82:85]
	v_mfma_f32_16x16x32_bf16 v[86:89], v[110:113], v[186:189], v[86:89]
	v_mfma_f32_16x16x32_bf16 v[86:89], v[106:109], v[182:185], v[86:89]
	v_mfma_f32_16x16x32_bf16 v[78:81], v[106:109], v[190:193], v[78:81]
	v_mfma_f32_16x16x32_bf16 v[78:81], v[110:113], v[194:197], v[78:81]
	v_mfma_f32_16x16x32_bf16 v[74:77], v[118:121], v[194:197], v[74:77]
	v_mfma_f32_16x16x32_bf16 v[74:77], v[114:117], v[190:193], v[74:77]
	v_mfma_f32_16x16x32_bf16 v[66:69], v[114:117], v[198:201], v[66:69]
	v_mfma_f32_16x16x32_bf16 v[66:69], v[118:121], v[202:205], v[66:69]
	v_mfma_f32_16x16x32_bf16 v[70:73], v[110:113], v[202:205], v[70:73]
	v_mfma_f32_16x16x32_bf16 v[70:73], v[106:109], v[198:201], v[70:73]
	v_mfma_f32_16x16x32_bf16 v[30:33], v[122:125], v[164:167], v[30:33]
	v_mfma_f32_16x16x32_bf16 v[30:33], v[126:129], v[168:171], v[30:33]
	v_mfma_f32_16x16x32_bf16 v[26:29], v[142:145], v[168:171], v[26:29]
	v_mfma_f32_16x16x32_bf16 v[26:29], v[130:133], v[164:167], v[26:29]
	v_mfma_f32_16x16x32_bf16 v[18:21], v[130:133], v[182:185], v[18:21]
	v_mfma_f32_16x16x32_bf16 v[18:21], v[142:145], v[186:189], v[18:21]
	v_mfma_f32_16x16x32_bf16 v[22:25], v[126:129], v[186:189], v[22:25]
	v_mfma_f32_16x16x32_bf16 v[22:25], v[122:125], v[182:185], v[22:25]
	v_mfma_f32_16x16x32_bf16 v[14:17], v[122:125], v[190:193], v[14:17]
	v_mfma_f32_16x16x32_bf16 v[14:17], v[126:129], v[194:197], v[14:17]
	v_mfma_f32_16x16x32_bf16 v[10:13], v[142:145], v[194:197], v[10:13]
	v_mfma_f32_16x16x32_bf16 v[10:13], v[130:133], v[190:193], v[10:13]
	v_mfma_f32_16x16x32_bf16 v[2:5], v[130:133], v[198:201], v[2:5]
	v_mfma_f32_16x16x32_bf16 v[2:5], v[142:145], v[202:205], v[2:5]
	v_mfma_f32_16x16x32_bf16 v[6:9], v[126:129], v[202:205], v[6:9]
	v_mfma_f32_16x16x32_bf16 v[6:9], v[122:125], v[198:201], v[6:9]
	s_barrier
	s_add_i32 s64, s64, 2
	s_addk_i32 s59, 0x100
	s_addk_i32 s63, 0x100
	s_cmp_gt_u32 s64, 29
	s_cbranch_scc0 .LBB0_1529
	s_setprio 0
	s_and_b64 vcc, exec, s[52:53]
	s_cbranch_vccz .LBB0_1532
	s_barrier

;     ...
;         bool has_next; if constexpr (QV == 2) has_next = S.next_tail(ui + 1, nxt); else has_next = S.next(ui + 1, nxt);
;         const unsigned nA = has_next ? (unsigned)nxt.pm * tstepA + nxt.aoff : cA, nB = has_next ? (unsigned)nxt.pn * tstepB + nxt.boff : cB;
;         if constexpr (QV == 0) {
; #pragma nounroll
;         for (int t = 0; t < nt; t += 2) {
;             const bool last = (t == nt - 2);
;             const unsigned a1 = cA + (unsigned)(t + 1) * kstep;
;             const unsigned a2 = last ? nA : cA + (unsigned)(t + 2) * kstep, b2 = last ? nB : cB + (unsigned)(t + 2) * kstep;
;             const unsigned a3 = a2 + kstep, b3 = b2 + kstep;
;     ...
;         if (!cur.keep) {
; #pragma unroll
;             for (int a = 0; a < 2; ++a)
; #pragma unroll
;                 for (int b = 0; b < 2; ++b)
; #pragma unroll
;                     for (int m = 0; m < 4; ++m)
; #pragma unroll
;                         for (int n = 0; n < 2; ++n) { f32x2 z0, z1; asm("v_mov_b64 %0, 0\n\tv_mov_b64 %1, 0" : "=v"(z0), "=v"(z1));
;                     acc[a][b][m][n] = __builtin_shufflevector(z0, z1, 0, 1, 2, 3); }
.LBB0_1650:
	s_lshl_b32 s55, s54, 20
	s_and_b64 s[30:31], s[38:39], exec
	s_cselect_b32 s30, s55, s61
	s_lshl_b32 s58, s53, 20
	s_and_b64 s[42:43], s[38:39], exec
	v_mov_b64_e32 v[12:13], v[4:5]
	v_mov_b64_e32 v[20:21], v[4:5]
	s_waitcnt vmcnt(15)
	v_mov_b64_e32 v[28:29], v[4:5]
	v_mov_b64_e32 v[36:37], v[4:5]
	v_mov_b64_e32 v[44:45], v[4:5]
	v_mov_b64_e32 v[52:53], v[4:5]
	v_mov_b64_e32 v[60:61], v[4:5]
	v_mov_b64_e32 v[8:9], v[4:5]
	v_mov_b64_e32 v[16:17], v[4:5]
	v_mov_b64_e32 v[24:25], v[4:5]
	v_mov_b64_e32 v[32:33], v[4:5]
	v_mov_b64_e32 v[40:41], v[4:5]
	v_mov_b64_e32 v[48:49], v[4:5]
	v_mov_b64_e32 v[56:57], v[4:5]
	v_mov_b64_e32 v[64:65], v[4:5]
	v_mov_b64_e32 v[68:69], v[4:5]
	v_mov_b64_e32 v[76:77], v[4:5]
	v_mov_b64_e32 v[92:93], v[4:5]
	v_mov_b64_e32 v[108:109], v[4:5]
	v_mov_b64_e32 v[116:117], v[4:5]
	v_mov_b64_e32 v[124:125], v[4:5]
	v_mov_b64_e32 v[132:133], v[4:5]
	v_mov_b64_e32 v[140:141], v[4:5]
	v_mov_b64_e32 v[72:73], v[4:5]
	v_mov_b64_e32 v[80:81], v[4:5]
	v_mov_b64_e32 v[96:97], v[4:5]
	v_mov_b64_e32 v[112:113], v[4:5]
	v_mov_b64_e32 v[120:121], v[4:5]
	v_mov_b64_e32 v[128:129], v[4:5]
	v_mov_b64_e32 v[136:137], v[4:5]
	v_mov_b64_e32 v[144:145], v[4:5]
	s_cselect_b32 s31, s58, s62
	s_add_i32 s61, s61, 0x80080
	s_addk_i32 s62, 0x100
	s_mov_b32 s63, -2
	v_mov_b64_e32 v[10:11], v[2:3]
	v_mov_b64_e32 v[18:19], v[2:3]
	v_mov_b64_e32 v[26:27], v[2:3]
	v_mov_b64_e32 v[34:35], v[2:3]
	v_mov_b64_e32 v[42:43], v[2:3]
	v_mov_b64_e32 v[50:51], v[2:3]
	v_mov_b64_e32 v[58:59], v[2:3]
	v_mov_b64_e32 v[6:7], v[2:3]
	v_mov_b64_e32 v[14:15], v[2:3]
	v_mov_b64_e32 v[22:23], v[2:3]
	v_mov_b64_e32 v[30:31], v[2:3]
	v_mov_b64_e32 v[38:39], v[2:3]
	v_mov_b64_e32 v[46:47], v[2:3]
	v_mov_b64_e32 v[54:55], v[2:3]
	v_mov_b64_e32 v[62:63], v[2:3]
	v_mov_b64_e32 v[66:67], v[2:3]
	v_mov_b64_e32 v[74:75], v[2:3]
	v_mov_b64_e32 v[90:91], v[2:3]
	v_mov_b64_e32 v[106:107], v[2:3]
	v_mov_b64_e32 v[114:115], v[2:3]
	v_mov_b64_e32 v[122:123], v[2:3]
	v_mov_b64_e32 v[130:131], v[2:3]
	v_mov_b64_e32 v[138:139], v[2:3]
	v_mov_b64_e32 v[70:71], v[2:3]
	v_mov_b64_e32 v[78:79], v[2:3]
	v_mov_b64_e32 v[94:95], v[2:3]
	v_mov_b64_e32 v[110:111], v[2:3]
	v_mov_b64_e32 v[118:119], v[2:3]
	v_mov_b64_e32 v[126:127], v[2:3]
	v_mov_b64_e32 v[134:135], v[2:3]
	v_mov_b64_e32 v[142:143], v[2:3]
	s_and_b64 vcc, exec, s[46:47]
	s_cbranch_vccz .Lsp_1651
	s_setprio 1

; #define PG8_STAGEX(rs, bufoff, soff, voff) do { _Pragma("unroll") for (int _i = 0; _i < 2; ++_i) \
;         __builtin_amdgcn_raw_ptr_buffer_load_lds(rs, (LAS unsigned*)(lds + (bufoff) + ldsw + _i * 8192), 16, (voff)[_i], (soff), 0, 0); } while (0)
; #define PG8_LDA(dst, b, h) do { _Pragma("unroll") for (int m = 0; m < 4; ++m) _Pragma("unroll") for (int k = 0; k < 2; ++k) dst[m][k] = *(const LAS bf16x8*)(lds + PG8_SA(b, h) + aoff + m * 2048 + k * 1024); } while (0)
; #define PG8_LDB(dst, b, h) do { _Pragma("unroll") for (int n = 0; n < 2; ++n) _Pragma("unroll") for (int k = 0; k < 2; ++k) dst[n][k] = *(const LAS bf16x8*)(lds + PG8_SB(b, h) + boff + n * 2048 + k * 1024); } while (0)
; #define PG8_WAIT_V(n) asm volatile("s_waitcnt vmcnt(" #n ")" ::: "memory")
; #define PG8_WAIT_L(n) asm volatile("s_waitcnt lgkmcnt(" #n ")" ::: "memory")
; #define PG8_BAR __builtin_amdgcn_s_barrier()
; #define PG8_SCHED __builtin_amdgcn_sched_barrier(0)
;     ...
;             PG8_LDB(B0, 0, 0); PG8_LDB(B1, 0, 1); PG8_SCHED; PG8_LDA(At, 0, 0); PG8_STAGEX(rsA, PG8_SA(1, 1), a1 + hstepA, voffA);
;             PG8_WAIT_V(8); PG8_WAIT_L(0); PG8_BAR; PG8_MMA(0, 0, At, B0); PG8_MMA(0, 1, At, B1); PG8_BAR; PG8_SCHED;
;             PG8_LDA(At, 0, 1); PG8_STAGEX(rsB, PG8_SB(0, 0), b2, voffB); PG8_STAGEX(rsB, PG8_SB(0, 1), b2 + hstepB, voffB); PG8_STAGEX(rsA, PG8_SA(0, 0), a2, voffA);
;             PG8_WAIT_V(8); PG8_WAIT_L(0); PG8_BAR; PG8_MMA(1, 0, At, B0); PG8_MMA(1, 1, At, B1); PG8_BAR; PG8_SCHED;
.LBB0_1651:
	v_add_u32_e32 v102, 0x10000, v172
	v_add_u32_e32 v146, 0x14000, v172
	ds_read_b128 v[82:85], v102
	ds_read_b128 v[86:89], v102 offset:1024
	ds_read_b128 v[98:101], v102 offset:2048
	ds_read_b128 v[102:105], v102 offset:3072
	ds_read_b128 v[150:153], v146
	ds_read_b128 v[154:157], v146 offset:1024
	ds_read_b128 v[182:185], v146 offset:2048
	ds_read_b128 v[186:189], v146 offset:3072
	s_add_i32 s42, s61, 0xfff80080
	s_cmp_eq_u32 s63, 28
	s_cselect_b32 s66, s30, s42
	s_cselect_b32 s65, s31, s62
	s_or_b32 s64, s66, 0x80
	s_mov_b32 m0, s29
	ds_read_b128 v[190:193], v173
	ds_read_b128 v[194:197], v173 offset:1024
	ds_read_b128 v[198:201], v173 offset:2048
	ds_read_b128 v[202:205], v173 offset:3072
	ds_read_b128 v[206:209], v173 offset:4096
	ds_read_b128 v[210:213], v173 offset:5120
	ds_read_b128 v[214:217], v173 offset:6144
	ds_read_b128 v[218:221], v173 offset:7168
	buffer_load_dwordx4 v159, s[76:79], s61 offen lds
	s_mov_b32 m0, s50
	s_nop 0
	buffer_load_dwordx4 v163, s[76:79], s61 offen lds
	s_waitcnt vmcnt(8)
	s_waitcnt lgkmcnt(0)
	s_barrier
	v_mfma_f32_16x16x32_bf16 v[142:145], v[82:85], v[190:193], v[142:145]
	v_mfma_f32_16x16x32_bf16 v[142:145], v[86:89], v[194:197], v[142:145]
	v_mfma_f32_16x16x32_bf16 v[134:137], v[102:105], v[194:197], v[134:137]
	v_mfma_f32_16x16x32_bf16 v[134:137], v[98:101], v[190:193], v[134:137]
	v_mfma_f32_16x16x32_bf16 v[118:121], v[98:101], v[198:201], v[118:121]
	v_mfma_f32_16x16x32_bf16 v[118:121], v[102:105], v[202:205], v[118:121]
	v_mfma_f32_16x16x32_bf16 v[126:129], v[86:89], v[202:205], v[126:129]
	v_mfma_f32_16x16x32_bf16 v[126:129], v[82:85], v[198:201], v[126:129]
	v_mfma_f32_16x16x32_bf16 v[110:113], v[82:85], v[206:209], v[110:113]
	v_mfma_f32_16x16x32_bf16 v[110:113], v[86:89], v[210:213], v[110:113]
	v_mfma_f32_16x16x32_bf16 v[94:97], v[102:105], v[210:213], v[94:97]
	v_mfma_f32_16x16x32_bf16 v[94:97], v[98:101], v[206:209], v[94:97]
	v_mfma_f32_16x16x32_bf16 v[70:73], v[98:101], v[214:217], v[70:73]
	v_mfma_f32_16x16x32_bf16 v[70:73], v[102:105], v[218:221], v[70:73]
	v_mfma_f32_16x16x32_bf16 v[78:81], v[86:89], v[218:221], v[78:81]
	v_mfma_f32_16x16x32_bf16 v[78:81], v[82:85], v[214:217], v[78:81]
	v_mfma_f32_16x16x32_bf16 v[138:141], v[150:153], v[190:193], v[138:141]
	v_mfma_f32_16x16x32_bf16 v[138:141], v[154:157], v[194:197], v[138:141]
	v_mfma_f32_16x16x32_bf16 v[130:133], v[186:189], v[194:197], v[130:133]
	v_mfma_f32_16x16x32_bf16 v[130:133], v[182:185], v[190:193], v[130:133]
	v_mfma_f32_16x16x32_bf16 v[114:117], v[182:185], v[198:201], v[114:117]
	v_mfma_f32_16x16x32_bf16 v[114:117], v[186:189], v[202:205], v[114:117]
	v_mfma_f32_16x16x32_bf16 v[122:125], v[154:157], v[202:205], v[122:125]
	v_mfma_f32_16x16x32_bf16 v[122:125], v[150:153], v[198:201], v[122:125]
	v_mfma_f32_16x16x32_bf16 v[106:109], v[150:153], v[206:209], v[106:109]
	v_mfma_f32_16x16x32_bf16 v[106:109], v[154:157], v[210:213], v[106:109]
	v_mfma_f32_16x16x32_bf16 v[90:93], v[186:189], v[210:213], v[90:93]
	v_mfma_f32_16x16x32_bf16 v[90:93], v[182:185], v[206:209], v[90:93]
	v_mfma_f32_16x16x32_bf16 v[66:69], v[182:185], v[214:217], v[66:69]
	v_mfma_f32_16x16x32_bf16 v[66:69], v[186:189], v[218:221], v[66:69]
	v_mfma_f32_16x16x32_bf16 v[74:77], v[154:157], v[218:221], v[74:77]
	v_mfma_f32_16x16x32_bf16 v[74:77], v[150:153], v[214:217], v[74:77]
	s_barrier
	s_mov_b32 m0, s16
	s_mov_b32 s42, s78
	s_mov_b32 s43, s79
	ds_read_b128 v[190:193], v173 offset:16384
	ds_read_b128 v[194:197], v173 offset:17408
	ds_read_b128 v[198:201], v173 offset:18432
	ds_read_b128 v[202:205], v173 offset:19456
	ds_read_b128 v[206:209], v173 offset:20480
	ds_read_b128 v[210:213], v173 offset:21504
	ds_read_b128 v[214:217], v173 offset:22528
	ds_read_b128 v[218:221], v173 offset:23552
	buffer_load_dwordx4 v161, s[40:43], s65 offen lds
	s_mov_b32 m0, s17
	s_add_i32 s67, s65, 0x80000
	buffer_load_dwordx4 v165, s[40:43], s65 offen lds
	s_mov_b32 m0, s18
	s_nop 0
	buffer_load_dwordx4 v161, s[40:43], s67 offen lds
	s_mov_b32 m0, s19
	s_nop 0
	buffer_load_dwordx4 v165, s[40:43], s67 offen lds
	s_mov_b32 m0, s15
	s_nop 0
	buffer_load_dwordx4 v159, s[76:79], s66 offen lds
	s_mov_b32 m0, s20
	s_nop 0
	buffer_load_dwordx4 v163, s[76:79], s66 offen lds
	s_waitcnt vmcnt(8)
	s_waitcnt lgkmcnt(0)
	s_barrier
	v_mfma_f32_16x16x32_bf16 v[62:65], v[82:85], v[190:193], v[62:65]
	v_mfma_f32_16x16x32_bf16 v[62:65], v[86:89], v[194:197], v[62:65]
	v_mfma_f32_16x16x32_bf16 v[54:57], v[102:105], v[194:197], v[54:57]
	v_mfma_f32_16x16x32_bf16 v[54:57], v[98:101], v[190:193], v[54:57]
	v_mfma_f32_16x16x32_bf16 v[38:41], v[98:101], v[198:201], v[38:41]
	v_mfma_f32_16x16x32_bf16 v[38:41], v[102:105], v[202:205], v[38:41]
	v_mfma_f32_16x16x32_bf16 v[46:49], v[86:89], v[202:205], v[46:49]
	v_mfma_f32_16x16x32_bf16 v[46:49], v[82:85], v[198:201], v[46:49]
	v_mfma_f32_16x16x32_bf16 v[30:33], v[82:85], v[206:209], v[30:33]
	v_mfma_f32_16x16x32_bf16 v[30:33], v[86:89], v[210:213], v[30:33]
	v_mfma_f32_16x16x32_bf16 v[22:25], v[102:105], v[210:213], v[22:25]
	v_mfma_f32_16x16x32_bf16 v[22:25], v[98:101], v[206:209], v[22:25]
	v_mfma_f32_16x16x32_bf16 v[6:9], v[98:101], v[214:217], v[6:9]
	v_mfma_f32_16x16x32_bf16 v[6:9], v[102:105], v[218:221], v[6:9]
	v_mfma_f32_16x16x32_bf16 v[14:17], v[86:89], v[218:221], v[14:17]
	v_mfma_f32_16x16x32_bf16 v[14:17], v[82:85], v[214:217], v[14:17]
	v_mfma_f32_16x16x32_bf16 v[58:61], v[150:153], v[190:193], v[58:61]
	v_mfma_f32_16x16x32_bf16 v[58:61], v[154:157], v[194:197], v[58:61]
	v_mfma_f32_16x16x32_bf16 v[50:53], v[186:189], v[194:197], v[50:53]
	v_mfma_f32_16x16x32_bf16 v[50:53], v[182:185], v[190:193], v[50:53]
	v_mfma_f32_16x16x32_bf16 v[34:37], v[182:185], v[198:201], v[34:37]
	v_mfma_f32_16x16x32_bf16 v[34:37], v[186:189], v[202:205], v[34:37]
	v_mfma_f32_16x16x32_bf16 v[42:45], v[154:157], v[202:205], v[42:45]
	v_mfma_f32_16x16x32_bf16 v[42:45], v[150:153], v[198:201], v[42:45]
	v_mfma_f32_16x16x32_bf16 v[26:29], v[150:153], v[206:209], v[26:29]
	v_mfma_f32_16x16x32_bf16 v[26:29], v[154:157], v[210:213], v[26:29]
	v_mfma_f32_16x16x32_bf16 v[18:21], v[186:189], v[210:213], v[18:21]
	v_mfma_f32_16x16x32_bf16 v[18:21], v[182:185], v[206:209], v[18:21]
	v_mfma_f32_16x16x32_bf16 v[2:5], v[182:185], v[214:217], v[2:5]
	v_mfma_f32_16x16x32_bf16 v[2:5], v[186:189], v[218:221], v[2:5]
	v_mfma_f32_16x16x32_bf16 v[10:13], v[154:157], v[218:221], v[10:13]
	v_mfma_f32_16x16x32_bf16 v[10:13], v[150:153], v[214:217], v[10:13]
	s_barrier
; #define PG8_STAGEX(rs, bufoff, soff, voff) do { _Pragma("unroll") for (int _i = 0; _i < 2; ++_i) \
;         __builtin_amdgcn_raw_ptr_buffer_load_lds(rs, (LAS unsigned*)(lds + (bufoff) + ldsw + _i * 8192), 16, (voff)[_i], (soff), 0, 0); } while (0)
; #define PG8_LDA(dst, b, h) do { _Pragma("unroll") for (int m = 0; m < 4; ++m) _Pragma("unroll") for (int k = 0; k < 2; ++k) dst[m][k] = *(const LAS bf16x8*)(lds + PG8_SA(b, h) + aoff + m * 2048 + k * 1024); } while (0)
; #define PG8_LDB(dst, b, h) do { _Pragma("unroll") for (int n = 0; n < 2; ++n) _Pragma("unroll") for (int k = 0; k < 2; ++k) dst[n][k] = *(const LAS bf16x8*)(lds + PG8_SB(b, h) + boff + n * 2048 + k * 1024); } while (0)
; #define PG8_WAIT_V(n) asm volatile("s_waitcnt vmcnt(" #n ")" ::: "memory")
; #define PG8_WAIT_L(n) asm volatile("s_waitcnt lgkmcnt(" #n ")" ::: "memory")
; #define PG8_BAR __builtin_amdgcn_s_barrier()
; #define PG8_SCHED __builtin_amdgcn_sched_barrier(0)
;     ...
;         for (int t = 0; t < nt; t += 2) {
;             const bool last = (t == nt - 2);
;             const unsigned a1 = cA + (unsigned)(t + 1) * kstep;
;             const unsigned a2 = last ? nA : cA + (unsigned)(t + 2) * kstep, b2 = last ? nB : cB + (unsigned)(t + 2) * kstep;
;             const unsigned a3 = a2 + kstep, b3 = b2 + kstep;
;             PG8_LDB(B0, 0, 0); PG8_LDB(B1, 0, 1); PG8_SCHED; PG8_LDA(At, 0, 0); PG8_STAGEX(rsA, PG8_SA(1, 1), a1 + hstepA, voffA);
;             PG8_WAIT_V(8); PG8_WAIT_L(0); PG8_BAR; PG8_MMA(0, 0, At, B0); PG8_MMA(0, 1, At, B1); PG8_BAR; PG8_SCHED;
;             PG8_LDA(At, 0, 1); PG8_STAGEX(rsB, PG8_SB(0, 0), b2, voffB); PG8_STAGEX(rsB, PG8_SB(0, 1), b2 + hstepB, voffB); PG8_STAGEX(rsA, PG8_SA(0, 0), a2, voffA);
;             PG8_WAIT_V(8); PG8_WAIT_L(0); PG8_BAR; PG8_MMA(1, 0, At, B0); PG8_MMA(1, 1, At, B1); PG8_BAR; PG8_SCHED;
;             PG8_LDB(B0, 1, 0); PG8_LDB(B1, 1, 1); PG8_SCHED; PG8_LDA(At, 1, 0); PG8_STAGEX(rsA, PG8_SA(0, 1), a2 + hstepA, voffA);
;             PG8_WAIT_V(8); PG8_WAIT_L(0); PG8_BAR; PG8_MMA(0, 0, At, B0); PG8_MMA(0, 1, At, B1); PG8_BAR; PG8_SCHED;
;             PG8_LDA(At, 1, 1); PG8_STAGEX(rsB, PG8_SB(1, 0), b3, voffB); PG8_STAGEX(rsB, PG8_SB(1, 1), b3 + hstepB, voffB); PG8_STAGEX(rsA, PG8_SA(1, 0), a3, voffA);
;             PG8_WAIT_V(8); PG8_WAIT_L(0); PG8_BAR; PG8_MMA(1, 0, At, B0); PG8_MMA(1, 1, At, B1); PG8_BAR; PG8_SCHED;
	v_add_u32_e32 v102, 0x18000, v172
	v_add_u32_e32 v146, 0x1c000, v172
	ds_read_b128 v[82:85], v102
	ds_read_b128 v[86:89], v102 offset:1024
	ds_read_b128 v[98:101], v102 offset:2048
	ds_read_b128 v[102:105], v102 offset:3072
	ds_read_b128 v[150:153], v146
	ds_read_b128 v[154:157], v146 offset:1024
	ds_read_b128 v[182:185], v146 offset:2048
	ds_read_b128 v[186:189], v146 offset:3072
	s_add_i32 s66, s66, 0x80000
	s_mov_b32 m0, s21
	ds_read_b128 v[190:193], v173 offset:32768
	ds_read_b128 v[194:197], v173 offset:33792
	ds_read_b128 v[198:201], v173 offset:34816
	ds_read_b128 v[202:205], v173 offset:35840
	ds_read_b128 v[206:209], v173 offset:36864
	ds_read_b128 v[210:213], v173 offset:37888
	ds_read_b128 v[214:217], v173 offset:38912
	ds_read_b128 v[218:221], v173 offset:39936
	buffer_load_dwordx4 v159, s[76:79], s66 offen lds
	s_mov_b32 m0, s22
	s_nop 0
	buffer_load_dwordx4 v163, s[76:79], s66 offen lds
	s_waitcnt vmcnt(8)
	s_waitcnt lgkmcnt(0)
	s_barrier
	v_mfma_f32_16x16x32_bf16 v[142:145], v[82:85], v[190:193], v[142:145]
	v_mfma_f32_16x16x32_bf16 v[142:145], v[86:89], v[194:197], v[142:145]
	v_mfma_f32_16x16x32_bf16 v[134:137], v[102:105], v[194:197], v[134:137]
	v_mfma_f32_16x16x32_bf16 v[134:137], v[98:101], v[190:193], v[134:137]
	v_mfma_f32_16x16x32_bf16 v[118:121], v[98:101], v[198:201], v[118:121]
	v_mfma_f32_16x16x32_bf16 v[118:121], v[102:105], v[202:205], v[118:121]
	v_mfma_f32_16x16x32_bf16 v[126:129], v[86:89], v[202:205], v[126:129]
	v_mfma_f32_16x16x32_bf16 v[126:129], v[82:85], v[198:201], v[126:129]
	v_mfma_f32_16x16x32_bf16 v[110:113], v[82:85], v[206:209], v[110:113]
	v_mfma_f32_16x16x32_bf16 v[110:113], v[86:89], v[210:213], v[110:113]
	v_mfma_f32_16x16x32_bf16 v[94:97], v[102:105], v[210:213], v[94:97]
	v_mfma_f32_16x16x32_bf16 v[94:97], v[98:101], v[206:209], v[94:97]
	v_mfma_f32_16x16x32_bf16 v[70:73], v[98:101], v[214:217], v[70:73]
	v_mfma_f32_16x16x32_bf16 v[70:73], v[102:105], v[218:221], v[70:73]
	v_mfma_f32_16x16x32_bf16 v[78:81], v[86:89], v[218:221], v[78:81]
	v_mfma_f32_16x16x32_bf16 v[78:81], v[82:85], v[214:217], v[78:81]
	v_mfma_f32_16x16x32_bf16 v[138:141], v[150:153], v[190:193], v[138:141]
	v_mfma_f32_16x16x32_bf16 v[138:141], v[154:157], v[194:197], v[138:141]
	v_mfma_f32_16x16x32_bf16 v[130:133], v[186:189], v[194:197], v[130:133]
	v_mfma_f32_16x16x32_bf16 v[130:133], v[182:185], v[190:193], v[130:133]
	v_mfma_f32_16x16x32_bf16 v[114:117], v[182:185], v[198:201], v[114:117]
	v_mfma_f32_16x16x32_bf16 v[114:117], v[186:189], v[202:205], v[114:117]
	v_mfma_f32_16x16x32_bf16 v[122:125], v[154:157], v[202:205], v[122:125]
	v_mfma_f32_16x16x32_bf16 v[122:125], v[150:153], v[198:201], v[122:125]
	v_mfma_f32_16x16x32_bf16 v[106:109], v[150:153], v[206:209], v[106:109]
	v_mfma_f32_16x16x32_bf16 v[106:109], v[154:157], v[210:213], v[106:109]
	v_mfma_f32_16x16x32_bf16 v[90:93], v[186:189], v[210:213], v[90:93]
	v_mfma_f32_16x16x32_bf16 v[90:93], v[182:185], v[206:209], v[90:93]
	v_mfma_f32_16x16x32_bf16 v[66:69], v[182:185], v[214:217], v[66:69]
	v_mfma_f32_16x16x32_bf16 v[66:69], v[186:189], v[218:221], v[66:69]
	v_mfma_f32_16x16x32_bf16 v[74:77], v[154:157], v[218:221], v[74:77]
	v_mfma_f32_16x16x32_bf16 v[74:77], v[150:153], v[214:217], v[74:77]
	s_barrier
	s_mov_b32 m0, s23
	s_or_b32 s66, s65, 0x80
	ds_read_b128 v[190:193], v173 offset:49152
	ds_read_b128 v[194:197], v173 offset:50176
	ds_read_b128 v[198:201], v173 offset:51200
	ds_read_b128 v[202:205], v173 offset:52224
	ds_read_b128 v[206:209], v173 offset:53248
	ds_read_b128 v[210:213], v173 offset:54272
	ds_read_b128 v[214:217], v173 offset:55296
	ds_read_b128 v[218:221], v173 offset:56320
	buffer_load_dwordx4 v161, s[40:43], s66 offen lds
	s_mov_b32 m0, s24
	s_add_i32 s65, s65, 0x80080
	buffer_load_dwordx4 v165, s[40:43], s66 offen lds
	s_mov_b32 m0, s27
	s_nop 0
	buffer_load_dwordx4 v161, s[40:43], s65 offen lds
	s_mov_b32 m0, s28
	s_nop 0
	buffer_load_dwordx4 v165, s[40:43], s65 offen lds
	s_mov_b32 m0, s25
	s_nop 0
	buffer_load_dwordx4 v159, s[76:79], s64 offen lds
	s_mov_b32 m0, s26
	s_nop 0
	buffer_load_dwordx4 v163, s[76:79], s64 offen lds
	s_waitcnt vmcnt(8)
	s_waitcnt lgkmcnt(0)
	s_barrier
	v_mfma_f32_16x16x32_bf16 v[62:65], v[82:85], v[190:193], v[62:65]
	v_mfma_f32_16x16x32_bf16 v[62:65], v[86:89], v[194:197], v[62:65]
	v_mfma_f32_16x16x32_bf16 v[54:57], v[102:105], v[194:197], v[54:57]
	v_mfma_f32_16x16x32_bf16 v[54:57], v[98:101], v[190:193], v[54:57]
	v_mfma_f32_16x16x32_bf16 v[38:41], v[98:101], v[198:201], v[38:41]
	v_mfma_f32_16x16x32_bf16 v[38:41], v[102:105], v[202:205], v[38:41]
	v_mfma_f32_16x16x32_bf16 v[46:49], v[86:89], v[202:205], v[46:49]
	v_mfma_f32_16x16x32_bf16 v[46:49], v[82:85], v[198:201], v[46:49]
	v_mfma_f32_16x16x32_bf16 v[30:33], v[82:85], v[206:209], v[30:33]
	v_mfma_f32_16x16x32_bf16 v[30:33], v[86:89], v[210:213], v[30:33]
	v_mfma_f32_16x16x32_bf16 v[22:25], v[102:105], v[210:213], v[22:25]
	v_mfma_f32_16x16x32_bf16 v[22:25], v[98:101], v[206:209], v[22:25]
	v_mfma_f32_16x16x32_bf16 v[6:9], v[98:101], v[214:217], v[6:9]
	v_mfma_f32_16x16x32_bf16 v[6:9], v[102:105], v[218:221], v[6:9]
	v_mfma_f32_16x16x32_bf16 v[14:17], v[86:89], v[218:221], v[14:17]
	v_mfma_f32_16x16x32_bf16 v[14:17], v[82:85], v[214:217], v[14:17]
	v_mfma_f32_16x16x32_bf16 v[58:61], v[150:153], v[190:193], v[58:61]
	v_mfma_f32_16x16x32_bf16 v[58:61], v[154:157], v[194:197], v[58:61]
	v_mfma_f32_16x16x32_bf16 v[50:53], v[186:189], v[194:197], v[50:53]
	v_mfma_f32_16x16x32_bf16 v[50:53], v[182:185], v[190:193], v[50:53]
	v_mfma_f32_16x16x32_bf16 v[34:37], v[182:185], v[198:201], v[34:37]
	v_mfma_f32_16x16x32_bf16 v[34:37], v[186:189], v[202:205], v[34:37]
	v_mfma_f32_16x16x32_bf16 v[42:45], v[154:157], v[202:205], v[42:45]
	v_mfma_f32_16x16x32_bf16 v[42:45], v[150:153], v[198:201], v[42:45]
	v_mfma_f32_16x16x32_bf16 v[26:29], v[150:153], v[206:209], v[26:29]
	v_mfma_f32_16x16x32_bf16 v[26:29], v[154:157], v[210:213], v[26:29]
	v_mfma_f32_16x16x32_bf16 v[18:21], v[186:189], v[210:213], v[18:21]
	v_mfma_f32_16x16x32_bf16 v[18:21], v[182:185], v[206:209], v[18:21]
	v_mfma_f32_16x16x32_bf16 v[2:5], v[182:185], v[214:217], v[2:5]
	v_mfma_f32_16x16x32_bf16 v[2:5], v[186:189], v[218:221], v[2:5]
	v_mfma_f32_16x16x32_bf16 v[10:13], v[154:157], v[218:221], v[10:13]
	v_mfma_f32_16x16x32_bf16 v[10:13], v[150:153], v[214:217], v[10:13]
	s_barrier
	s_add_i32 s63, s63, 2
	s_addk_i32 s61, 0x100
	s_addk_i32 s62, 0x100
	s_cmp_gt_u32 s63, 29
	s_cbranch_scc0 .LBB0_1651
	s_setprio 0
	s_and_b64 vcc, exec, s[48:49]
	s_cbranch_vccz .LBB0_1654
	s_barrier

;     ...
;         bool has_next; if constexpr (QV == 2) has_next = S.next_tail(ui + 1, nxt); else has_next = S.next(ui + 1, nxt);
;         const unsigned nA = has_next ? (unsigned)nxt.pm * tstepA + nxt.aoff : cA, nB = has_next ? (unsigned)nxt.pn * tstepB + nxt.boff : cB;
;         if constexpr (QV == 0) {
; #pragma nounroll
;         for (int t = 0; t < nt; t += 2) {
;             const bool last = (t == nt - 2);
;             const unsigned a1 = cA + (unsigned)(t + 1) * kstep;
;             const unsigned a2 = last ? nA : cA + (unsigned)(t + 2) * kstep, b2 = last ? nB : cB + (unsigned)(t + 2) * kstep;
;     ...
;         if (!cur.keep) {
; #pragma unroll
;             for (int a = 0; a < 2; ++a)
; #pragma unroll
;                 for (int b = 0; b < 2; ++b)
; #pragma unroll
;                     for (int m = 0; m < 4; ++m)
; #pragma unroll
;                         for (int n = 0; n < 2; ++n) { f32x2 z0, z1; asm("v_mov_b64 %0, 0\n\tv_mov_b64 %1, 0" : "=v"(z0), "=v"(z1));
;                     acc[a][b][m][n] = __builtin_shufflevector(z0, z1, 0, 1, 2, 3); }
;         }
;         cur = nxt; cA = nA; cB = nB; ++ui;
.LBB0_1749:
	s_mul_i32 s84, s47, 0x2b0000
	s_and_b64 s[30:31], s[58:59], exec
	s_mul_i32 s85, s41, 0x2b0000
	s_waitcnt lgkmcnt(0)
	v_mov_b64_e32 v[8:9], v[4:5]
	v_mov_b64_e32 v[12:13], v[4:5]
	v_mov_b64_e32 v[16:17], v[4:5]
	v_mov_b64_e32 v[20:21], v[4:5]
	v_mov_b64_e32 v[24:25], v[4:5]
	s_waitcnt vmcnt(15)
	v_mov_b64_e32 v[28:29], v[4:5]
	v_mov_b64_e32 v[32:33], v[4:5]
	v_mov_b64_e32 v[68:69], v[4:5]
	v_mov_b64_e32 v[74:75], v[4:5]
	v_mov_b64_e32 v[80:81], v[4:5]
	v_mov_b64_e32 v[84:85], v[4:5]
	v_mov_b64_e32 v[88:89], v[4:5]
	v_mov_b64_e32 v[92:93], v[4:5]
	v_mov_b64_e32 v[96:97], v[4:5]
	v_mov_b64_e32 v[100:101], v[4:5]
	v_mov_b64_e32 v[36:37], v[4:5]
	v_mov_b64_e32 v[40:41], v[4:5]
	v_mov_b64_e32 v[44:45], v[4:5]
	v_mov_b64_e32 v[48:49], v[4:5]
	v_mov_b64_e32 v[52:53], v[4:5]
	v_mov_b64_e32 v[56:57], v[4:5]
	v_mov_b64_e32 v[60:61], v[4:5]
	v_mov_b64_e32 v[64:65], v[4:5]
	v_mov_b64_e32 v[104:105], v[4:5]
	v_mov_b64_e32 v[108:109], v[4:5]
	v_mov_b64_e32 v[112:113], v[4:5]
	v_mov_b64_e32 v[116:117], v[4:5]
	v_mov_b64_e32 v[120:121], v[4:5]
	v_mov_b64_e32 v[124:125], v[4:5]
	v_mov_b64_e32 v[128:129], v[4:5]
	v_mov_b64_e32 v[132:133], v[4:5]
	s_mov_b32 s83, s47
	s_mov_b32 s82, s41
	s_cselect_b32 s30, s84, s61
	s_cselect_b32 s31, s85, s60
	s_add_i32 s40, s61, 0x158080
	s_add_i32 s41, s60, 0x100
	s_mov_b32 s60, -2
	v_mov_b64_e32 v[6:7], v[2:3]
	v_mov_b64_e32 v[10:11], v[2:3]
	v_mov_b64_e32 v[14:15], v[2:3]
	v_mov_b64_e32 v[18:19], v[2:3]
	v_mov_b64_e32 v[22:23], v[2:3]
	v_mov_b64_e32 v[26:27], v[2:3]
	v_mov_b64_e32 v[30:31], v[2:3]
	v_mov_b64_e32 v[66:67], v[2:3]
	v_mov_b64_e32 v[72:73], v[2:3]
	v_mov_b64_e32 v[78:79], v[2:3]
	v_mov_b64_e32 v[82:83], v[2:3]
	v_mov_b64_e32 v[86:87], v[2:3]
	v_mov_b64_e32 v[90:91], v[2:3]
	v_mov_b64_e32 v[94:95], v[2:3]
	v_mov_b64_e32 v[98:99], v[2:3]
	v_mov_b64_e32 v[34:35], v[2:3]
	v_mov_b64_e32 v[38:39], v[2:3]
	v_mov_b64_e32 v[42:43], v[2:3]
	v_mov_b64_e32 v[46:47], v[2:3]
	v_mov_b64_e32 v[50:51], v[2:3]
	v_mov_b64_e32 v[54:55], v[2:3]
	v_mov_b64_e32 v[58:59], v[2:3]
	v_mov_b64_e32 v[62:63], v[2:3]
	v_mov_b64_e32 v[102:103], v[2:3]
	v_mov_b64_e32 v[106:107], v[2:3]
	v_mov_b64_e32 v[110:111], v[2:3]
	v_mov_b64_e32 v[114:115], v[2:3]
	v_mov_b64_e32 v[118:119], v[2:3]
	v_mov_b64_e32 v[122:123], v[2:3]
	v_mov_b64_e32 v[126:127], v[2:3]
	v_mov_b64_e32 v[130:131], v[2:3]
	s_and_b64 vcc, exec, s[48:49]
	s_cbranch_vccz .Lsp_1750
	s_setprio 1

; #define PG8_STAGEX(rs, bufoff, soff, voff) do { _Pragma("unroll") for (int _i = 0; _i < 2; ++_i) \
;         __builtin_amdgcn_raw_ptr_buffer_load_lds(rs, (LAS unsigned*)(lds + (bufoff) + ldsw + _i * 8192), 16, (voff)[_i], (soff), 0, 0); } while (0)
; #define PG8_LDA(dst, b, h) do { _Pragma("unroll") for (int m = 0; m < 4; ++m) _Pragma("unroll") for (int k = 0; k < 2; ++k) dst[m][k] = *(const LAS bf16x8*)(lds + PG8_SA(b, h) + aoff + m * 2048 + k * 1024); } while (0)
; #define PG8_LDB(dst, b, h) do { _Pragma("unroll") for (int n = 0; n < 2; ++n) _Pragma("unroll") for (int k = 0; k < 2; ++k) dst[n][k] = *(const LAS bf16x8*)(lds + PG8_SB(b, h) + boff + n * 2048 + k * 1024); } while (0)
; #define PG8_WAIT_V(n) asm volatile("s_waitcnt vmcnt(" #n ")" ::: "memory")
; #define PG8_WAIT_L(n) asm volatile("s_waitcnt lgkmcnt(" #n ")" ::: "memory")
; #define PG8_BAR __builtin_amdgcn_s_barrier()
; #define PG8_SCHED __builtin_amdgcn_sched_barrier(0)
;     ...
;             const unsigned a2 = last ? nA : cA + (unsigned)(t + 2) * kstep, b2 = last ? nB : cB + (unsigned)(t + 2) * kstep;
;             const unsigned a3 = a2 + kstep, b3 = b2 + kstep;
;             PG8_LDB(B0, 0, 0); PG8_LDB(B1, 0, 1); PG8_SCHED; PG8_LDA(At, 0, 0); PG8_STAGEX(rsA, PG8_SA(1, 1), a1 + hstepA, voffA);
;             PG8_WAIT_V(8); PG8_WAIT_L(0); PG8_BAR; PG8_MMA(0, 0, At, B0); PG8_MMA(0, 1, At, B1); PG8_BAR; PG8_SCHED;
;             PG8_LDA(At, 0, 1); PG8_STAGEX(rsB, PG8_SB(0, 0), b2, voffB); PG8_STAGEX(rsB, PG8_SB(0, 1), b2 + hstepB, voffB); PG8_STAGEX(rsA, PG8_SA(0, 0), a2, voffA);
;             PG8_WAIT_V(8); PG8_WAIT_L(0); PG8_BAR; PG8_MMA(1, 0, At, B0); PG8_MMA(1, 1, At, B1); PG8_BAR; PG8_SCHED;
.LBB0_1750:
	v_add_u32_e32 v70, 0x10000, v241
	ds_read_b128 v[134:137], v70
	ds_read_b128 v[138:141], v70 offset:1024
	ds_read_b128 v[142:145], v70 offset:2048
	ds_read_b128 v[146:149], v70 offset:3072
	v_add_u32_e32 v70, 0x14000, v241
	ds_read_b128 v[150:153], v70
	ds_read_b128 v[154:157], v70 offset:1024
	ds_read_b128 v[158:161], v70 offset:2048
	ds_read_b128 v[162:165], v70 offset:3072
	s_add_i32 s46, s40, 0xffea8080
	s_cmpk_eq_i32 s60, 0x52
	s_cselect_b32 s63, s30, s46
	s_cselect_b32 s62, s31, s41
	s_or_b32 s61, s63, 0x80
	s_mov_b32 m0, s72
	ds_read_b128 v[166:169], v242
	ds_read_b128 v[170:173], v242 offset:1024
	ds_read_b128 v[184:187], v242 offset:2048
	ds_read_b128 v[188:191], v242 offset:3072
	ds_read_b128 v[192:195], v242 offset:4096
	ds_read_b128 v[196:199], v242 offset:5120
	ds_read_b128 v[200:203], v242 offset:6144
	ds_read_b128 v[204:207], v242 offset:7168
	buffer_load_dwordx4 v178, s[76:79], s40 offen lds
	s_mov_b32 m0, s73
	s_nop 0
	buffer_load_dwordx4 v237, s[76:79], s40 offen lds
	s_waitcnt vmcnt(8)
	s_waitcnt lgkmcnt(0)
	s_barrier
	v_mfma_f32_16x16x32_bf16 v[130:133], v[134:137], v[166:169], v[130:133]
	v_mfma_f32_16x16x32_bf16 v[130:133], v[138:141], v[170:173], v[130:133]
	v_mfma_f32_16x16x32_bf16 v[126:129], v[146:149], v[170:173], v[126:129]
	v_mfma_f32_16x16x32_bf16 v[126:129], v[142:145], v[166:169], v[126:129]
	v_mfma_f32_16x16x32_bf16 v[118:121], v[142:145], v[184:187], v[118:121]
	v_mfma_f32_16x16x32_bf16 v[118:121], v[146:149], v[188:191], v[118:121]
	v_mfma_f32_16x16x32_bf16 v[122:125], v[138:141], v[188:191], v[122:125]
	v_mfma_f32_16x16x32_bf16 v[122:125], v[134:137], v[184:187], v[122:125]
	v_mfma_f32_16x16x32_bf16 v[114:117], v[134:137], v[192:195], v[114:117]
	v_mfma_f32_16x16x32_bf16 v[114:117], v[138:141], v[196:199], v[114:117]
	v_mfma_f32_16x16x32_bf16 v[110:113], v[146:149], v[196:199], v[110:113]
	v_mfma_f32_16x16x32_bf16 v[110:113], v[142:145], v[192:195], v[110:113]
	v_mfma_f32_16x16x32_bf16 v[102:105], v[142:145], v[200:203], v[102:105]
	v_mfma_f32_16x16x32_bf16 v[102:105], v[146:149], v[204:207], v[102:105]
	v_mfma_f32_16x16x32_bf16 v[106:109], v[138:141], v[204:207], v[106:109]
	v_mfma_f32_16x16x32_bf16 v[106:109], v[134:137], v[200:203], v[106:109]
	v_mfma_f32_16x16x32_bf16 v[62:65], v[150:153], v[166:169], v[62:65]
	v_mfma_f32_16x16x32_bf16 v[62:65], v[154:157], v[170:173], v[62:65]
	v_mfma_f32_16x16x32_bf16 v[58:61], v[162:165], v[170:173], v[58:61]
	v_mfma_f32_16x16x32_bf16 v[58:61], v[158:161], v[166:169], v[58:61]
	v_mfma_f32_16x16x32_bf16 v[50:53], v[158:161], v[184:187], v[50:53]
	v_mfma_f32_16x16x32_bf16 v[50:53], v[162:165], v[188:191], v[50:53]
	v_mfma_f32_16x16x32_bf16 v[54:57], v[154:157], v[188:191], v[54:57]
	v_mfma_f32_16x16x32_bf16 v[54:57], v[150:153], v[184:187], v[54:57]
	v_mfma_f32_16x16x32_bf16 v[46:49], v[150:153], v[192:195], v[46:49]
	v_mfma_f32_16x16x32_bf16 v[46:49], v[154:157], v[196:199], v[46:49]
	v_mfma_f32_16x16x32_bf16 v[42:45], v[162:165], v[196:199], v[42:45]
	v_mfma_f32_16x16x32_bf16 v[42:45], v[158:161], v[192:195], v[42:45]
	v_mfma_f32_16x16x32_bf16 v[34:37], v[158:161], v[200:203], v[34:37]
	v_mfma_f32_16x16x32_bf16 v[34:37], v[162:165], v[204:207], v[34:37]
	v_mfma_f32_16x16x32_bf16 v[38:41], v[154:157], v[204:207], v[38:41]
	v_mfma_f32_16x16x32_bf16 v[38:41], v[150:153], v[200:203], v[38:41]
	s_barrier
	s_mov_b32 m0, s17
	s_mov_b32 s46, s78
	s_mov_b32 s47, s79
	ds_read_b128 v[166:169], v242 offset:16384
	ds_read_b128 v[170:173], v242 offset:17408
	ds_read_b128 v[184:187], v242 offset:18432
	ds_read_b128 v[188:191], v242 offset:19456
	ds_read_b128 v[192:195], v242 offset:20480
	ds_read_b128 v[196:199], v242 offset:21504
	ds_read_b128 v[200:203], v242 offset:22528
	ds_read_b128 v[204:207], v242 offset:23552
	buffer_load_dwordx4 v179, s[44:47], s62 offen lds
	s_mov_b32 m0, s18
	s_add_i32 s64, s62, 0x158000
	buffer_load_dwordx4 v238, s[44:47], s62 offen lds
	s_mov_b32 m0, s19
	s_nop 0
	buffer_load_dwordx4 v179, s[44:47], s64 offen lds
	s_mov_b32 m0, s20
	s_nop 0
	buffer_load_dwordx4 v238, s[44:47], s64 offen lds
	s_mov_b32 m0, s16
	s_nop 0
	buffer_load_dwordx4 v178, s[76:79], s63 offen lds
	s_mov_b32 m0, s21
	s_nop 0
	buffer_load_dwordx4 v237, s[76:79], s63 offen lds
	s_waitcnt vmcnt(8)
	s_waitcnt lgkmcnt(0)
	s_barrier
	v_mfma_f32_16x16x32_bf16 v[98:101], v[134:137], v[166:169], v[98:101]
	v_mfma_f32_16x16x32_bf16 v[94:97], v[142:145], v[166:169], v[94:97]
	v_mfma_f32_16x16x32_bf16 v[90:93], v[134:137], v[184:187], v[90:93]
	v_mfma_f32_16x16x32_bf16 v[86:89], v[142:145], v[184:187], v[86:89]
	v_mfma_f32_16x16x32_bf16 v[82:85], v[134:137], v[192:195], v[82:85]
	v_mfma_f32_16x16x32_bf16 v[76:79], v[142:145], v[192:195], v[78:81]
	v_mfma_f32_16x16x32_bf16 v[70:73], v[134:137], v[200:203], v[72:75]
	v_mfma_f32_16x16x32_bf16 v[66:69], v[142:145], v[200:203], v[66:69]
	v_mfma_f32_16x16x32_bf16 v[98:101], v[138:141], v[170:173], v[98:101]
	v_mfma_f32_16x16x32_bf16 v[94:97], v[146:149], v[170:173], v[94:97]
	v_mfma_f32_16x16x32_bf16 v[90:93], v[138:141], v[188:191], v[90:93]
	v_mfma_f32_16x16x32_bf16 v[86:89], v[146:149], v[188:191], v[86:89]
	v_mfma_f32_16x16x32_bf16 v[82:85], v[138:141], v[196:199], v[82:85]
	v_mfma_f32_16x16x32_bf16 v[76:79], v[146:149], v[196:199], v[76:79]
	v_mfma_f32_16x16x32_bf16 v[70:73], v[138:141], v[204:207], v[70:73]
	v_mfma_f32_16x16x32_bf16 v[66:69], v[146:149], v[204:207], v[66:69]
	v_mfma_f32_16x16x32_bf16 v[30:33], v[150:153], v[166:169], v[30:33]
	v_mfma_f32_16x16x32_bf16 v[26:29], v[158:161], v[166:169], v[26:29]
	v_mfma_f32_16x16x32_bf16 v[22:25], v[150:153], v[184:187], v[22:25]
	v_mfma_f32_16x16x32_bf16 v[18:21], v[158:161], v[184:187], v[18:21]
	v_mfma_f32_16x16x32_bf16 v[14:17], v[150:153], v[192:195], v[14:17]
	v_mfma_f32_16x16x32_bf16 v[10:13], v[158:161], v[192:195], v[10:13]
	v_mfma_f32_16x16x32_bf16 v[6:9], v[150:153], v[200:203], v[6:9]
	v_mfma_f32_16x16x32_bf16 v[2:5], v[158:161], v[200:203], v[2:5]
	v_mfma_f32_16x16x32_bf16 v[30:33], v[154:157], v[170:173], v[30:33]
	v_mfma_f32_16x16x32_bf16 v[26:29], v[162:165], v[170:173], v[26:29]
	v_mfma_f32_16x16x32_bf16 v[22:25], v[154:157], v[188:191], v[22:25]
	v_mfma_f32_16x16x32_bf16 v[18:21], v[162:165], v[188:191], v[18:21]
	v_mfma_f32_16x16x32_bf16 v[14:17], v[154:157], v[196:199], v[14:17]
	v_mfma_f32_16x16x32_bf16 v[10:13], v[162:165], v[196:199], v[10:13]
	v_mfma_f32_16x16x32_bf16 v[6:9], v[154:157], v[204:207], v[6:9]
	v_mfma_f32_16x16x32_bf16 v[2:5], v[162:165], v[204:207], v[2:5]
	s_barrier
; #define PG8_STAGEX(rs, bufoff, soff, voff) do { _Pragma("unroll") for (int _i = 0; _i < 2; ++_i) \
;         __builtin_amdgcn_raw_ptr_buffer_load_lds(rs, (LAS unsigned*)(lds + (bufoff) + ldsw + _i * 8192), 16, (voff)[_i], (soff), 0, 0); } while (0)
; #define PG8_LDA(dst, b, h) do { _Pragma("unroll") for (int m = 0; m < 4; ++m) _Pragma("unroll") for (int k = 0; k < 2; ++k) dst[m][k] = *(const LAS bf16x8*)(lds + PG8_SA(b, h) + aoff + m * 2048 + k * 1024); } while (0)
; #define PG8_LDB(dst, b, h) do { _Pragma("unroll") for (int n = 0; n < 2; ++n) _Pragma("unroll") for (int k = 0; k < 2; ++k) dst[n][k] = *(const LAS bf16x8*)(lds + PG8_SB(b, h) + boff + n * 2048 + k * 1024); } while (0)
; #define PG8_WAIT_V(n) asm volatile("s_waitcnt vmcnt(" #n ")" ::: "memory")
; #define PG8_WAIT_L(n) asm volatile("s_waitcnt lgkmcnt(" #n ")" ::: "memory")
; #define PG8_BAR __builtin_amdgcn_s_barrier()
; #define PG8_SCHED __builtin_amdgcn_sched_barrier(0)
;     ...
;             PG8_LDB(B0, 1, 0); PG8_LDB(B1, 1, 1); PG8_SCHED; PG8_LDA(At, 1, 0); PG8_STAGEX(rsA, PG8_SA(0, 1), a2 + hstepA, voffA);
;             PG8_WAIT_V(8); PG8_WAIT_L(0); PG8_BAR; PG8_MMA(0, 0, At, B0); PG8_MMA(0, 1, At, B1); PG8_BAR; PG8_SCHED;
;             PG8_LDA(At, 1, 1); PG8_STAGEX(rsB, PG8_SB(1, 0), b3, voffB); PG8_STAGEX(rsB, PG8_SB(1, 1), b3 + hstepB, voffB); PG8_STAGEX(rsA, PG8_SA(1, 0), a3, voffA);
;             PG8_WAIT_V(8); PG8_WAIT_L(0); PG8_BAR; PG8_MMA(1, 0, At, B0); PG8_MMA(1, 1, At, B1); PG8_BAR; PG8_SCHED;
	v_add_u32_e32 v74, 0x18000, v241
	ds_read_b128 v[134:137], v74
	ds_read_b128 v[138:141], v74 offset:1024
	ds_read_b128 v[142:145], v74 offset:2048
	ds_read_b128 v[146:149], v74 offset:3072
	v_add_u32_e32 v74, 0x1c000, v241
	ds_read_b128 v[150:153], v74
	ds_read_b128 v[154:157], v74 offset:1024
	ds_read_b128 v[158:161], v74 offset:2048
	ds_read_b128 v[162:165], v74 offset:3072
	s_add_i32 s63, s63, 0x158000
	s_mov_b32 m0, s22
	ds_read_b128 v[166:169], v242 offset:32768
	ds_read_b128 v[170:173], v242 offset:33792
	ds_read_b128 v[184:187], v242 offset:34816
	ds_read_b128 v[188:191], v242 offset:35840
	ds_read_b128 v[192:195], v242 offset:36864
	ds_read_b128 v[196:199], v242 offset:37888
	ds_read_b128 v[200:203], v242 offset:38912
	ds_read_b128 v[204:207], v242 offset:39936
	buffer_load_dwordx4 v178, s[76:79], s63 offen lds
	s_mov_b32 m0, s23
	s_nop 0
	buffer_load_dwordx4 v237, s[76:79], s63 offen lds
	s_waitcnt vmcnt(8)
	s_waitcnt lgkmcnt(0)
	s_barrier
	v_mfma_f32_16x16x32_bf16 v[130:133], v[134:137], v[166:169], v[130:133]
	v_mfma_f32_16x16x32_bf16 v[130:133], v[138:141], v[170:173], v[130:133]
	v_mfma_f32_16x16x32_bf16 v[126:129], v[146:149], v[170:173], v[126:129]
	v_mfma_f32_16x16x32_bf16 v[126:129], v[142:145], v[166:169], v[126:129]
	v_mfma_f32_16x16x32_bf16 v[118:121], v[142:145], v[184:187], v[118:121]
	v_mfma_f32_16x16x32_bf16 v[118:121], v[146:149], v[188:191], v[118:121]
	v_mfma_f32_16x16x32_bf16 v[122:125], v[138:141], v[188:191], v[122:125]
	v_mfma_f32_16x16x32_bf16 v[122:125], v[134:137], v[184:187], v[122:125]
	v_mfma_f32_16x16x32_bf16 v[114:117], v[134:137], v[192:195], v[114:117]
	v_mfma_f32_16x16x32_bf16 v[114:117], v[138:141], v[196:199], v[114:117]
	v_mfma_f32_16x16x32_bf16 v[110:113], v[146:149], v[196:199], v[110:113]
	v_mfma_f32_16x16x32_bf16 v[110:113], v[142:145], v[192:195], v[110:113]
	v_mfma_f32_16x16x32_bf16 v[102:105], v[142:145], v[200:203], v[102:105]
	v_mfma_f32_16x16x32_bf16 v[102:105], v[146:149], v[204:207], v[102:105]
	v_mfma_f32_16x16x32_bf16 v[106:109], v[138:141], v[204:207], v[106:109]
	v_mfma_f32_16x16x32_bf16 v[106:109], v[134:137], v[200:203], v[106:109]
	v_mfma_f32_16x16x32_bf16 v[62:65], v[150:153], v[166:169], v[62:65]
	v_mfma_f32_16x16x32_bf16 v[62:65], v[154:157], v[170:173], v[62:65]
	v_mfma_f32_16x16x32_bf16 v[58:61], v[162:165], v[170:173], v[58:61]
	v_mfma_f32_16x16x32_bf16 v[58:61], v[158:161], v[166:169], v[58:61]
	v_mfma_f32_16x16x32_bf16 v[50:53], v[158:161], v[184:187], v[50:53]
	v_mfma_f32_16x16x32_bf16 v[50:53], v[162:165], v[188:191], v[50:53]
	v_mfma_f32_16x16x32_bf16 v[54:57], v[154:157], v[188:191], v[54:57]
	v_mfma_f32_16x16x32_bf16 v[54:57], v[150:153], v[184:187], v[54:57]
	v_mfma_f32_16x16x32_bf16 v[46:49], v[150:153], v[192:195], v[46:49]
	v_mfma_f32_16x16x32_bf16 v[46:49], v[154:157], v[196:199], v[46:49]
	v_mfma_f32_16x16x32_bf16 v[42:45], v[162:165], v[196:199], v[42:45]
	v_mfma_f32_16x16x32_bf16 v[42:45], v[158:161], v[192:195], v[42:45]
	v_mfma_f32_16x16x32_bf16 v[34:37], v[158:161], v[200:203], v[34:37]
	v_mfma_f32_16x16x32_bf16 v[34:37], v[162:165], v[204:207], v[34:37]
	v_mfma_f32_16x16x32_bf16 v[38:41], v[154:157], v[204:207], v[38:41]
	v_mfma_f32_16x16x32_bf16 v[38:41], v[150:153], v[200:203], v[38:41]
	s_barrier
	s_mov_b32 m0, s54
	s_or_b32 s63, s62, 0x80
	ds_read_b128 v[166:169], v242 offset:49152
	ds_read_b128 v[170:173], v242 offset:50176
	ds_read_b128 v[184:187], v242 offset:51200
	ds_read_b128 v[188:191], v242 offset:52224
	ds_read_b128 v[192:195], v242 offset:53248
	ds_read_b128 v[196:199], v242 offset:54272
	ds_read_b128 v[200:203], v242 offset:55296
	ds_read_b128 v[204:207], v242 offset:56320
	buffer_load_dwordx4 v179, s[44:47], s63 offen lds
	s_mov_b32 m0, s55
	s_add_i32 s62, s62, 0x158080
	buffer_load_dwordx4 v238, s[44:47], s63 offen lds
	s_mov_b32 m0, s70
	s_nop 0
	buffer_load_dwordx4 v179, s[44:47], s62 offen lds
	s_mov_b32 m0, s71
	s_nop 0
	buffer_load_dwordx4 v238, s[44:47], s62 offen lds
	s_mov_b32 m0, s68
	s_nop 0
	buffer_load_dwordx4 v178, s[76:79], s61 offen lds
	s_mov_b32 m0, s69
	s_nop 0
	buffer_load_dwordx4 v237, s[76:79], s61 offen lds
	s_waitcnt vmcnt(8)
	s_waitcnt lgkmcnt(0)
	s_barrier
	v_mfma_f32_16x16x32_bf16 v[98:101], v[134:137], v[166:169], v[98:101]
	v_mfma_f32_16x16x32_bf16 v[94:97], v[142:145], v[166:169], v[94:97]
	v_mfma_f32_16x16x32_bf16 v[90:93], v[134:137], v[184:187], v[90:93]
	v_mfma_f32_16x16x32_bf16 v[86:89], v[142:145], v[184:187], v[86:89]
	v_mfma_f32_16x16x32_bf16 v[80:83], v[134:137], v[192:195], v[82:85]
	v_mfma_f32_16x16x32_bf16 v[74:77], v[142:145], v[192:195], v[76:79]
	v_mfma_f32_16x16x32_bf16 v[70:73], v[134:137], v[200:203], v[70:73]
	v_mfma_f32_16x16x32_bf16 v[66:69], v[142:145], v[200:203], v[66:69]
	v_mfma_f32_16x16x32_bf16 v[98:101], v[138:141], v[170:173], v[98:101]
	v_mfma_f32_16x16x32_bf16 v[94:97], v[146:149], v[170:173], v[94:97]
	v_mfma_f32_16x16x32_bf16 v[90:93], v[138:141], v[188:191], v[90:93]
	v_mfma_f32_16x16x32_bf16 v[86:89], v[146:149], v[188:191], v[86:89]
	v_mfma_f32_16x16x32_bf16 v[82:85], v[138:141], v[196:199], v[80:83]
	v_mfma_f32_16x16x32_bf16 v[78:81], v[146:149], v[196:199], v[74:77]
	v_mfma_f32_16x16x32_bf16 v[72:75], v[138:141], v[204:207], v[70:73]
	v_mfma_f32_16x16x32_bf16 v[66:69], v[146:149], v[204:207], v[66:69]
	v_mfma_f32_16x16x32_bf16 v[30:33], v[150:153], v[166:169], v[30:33]
	v_mfma_f32_16x16x32_bf16 v[26:29], v[158:161], v[166:169], v[26:29]
	v_mfma_f32_16x16x32_bf16 v[22:25], v[150:153], v[184:187], v[22:25]
	v_mfma_f32_16x16x32_bf16 v[18:21], v[158:161], v[184:187], v[18:21]
	v_mfma_f32_16x16x32_bf16 v[14:17], v[150:153], v[192:195], v[14:17]
	v_mfma_f32_16x16x32_bf16 v[10:13], v[158:161], v[192:195], v[10:13]
	v_mfma_f32_16x16x32_bf16 v[6:9], v[150:153], v[200:203], v[6:9]
	v_mfma_f32_16x16x32_bf16 v[2:5], v[158:161], v[200:203], v[2:5]
	v_mfma_f32_16x16x32_bf16 v[30:33], v[154:157], v[170:173], v[30:33]
	v_mfma_f32_16x16x32_bf16 v[26:29], v[162:165], v[170:173], v[26:29]
	v_mfma_f32_16x16x32_bf16 v[22:25], v[154:157], v[188:191], v[22:25]
	v_mfma_f32_16x16x32_bf16 v[18:21], v[162:165], v[188:191], v[18:21]
	v_mfma_f32_16x16x32_bf16 v[14:17], v[154:157], v[196:199], v[14:17]
	v_mfma_f32_16x16x32_bf16 v[10:13], v[162:165], v[196:199], v[10:13]
	v_mfma_f32_16x16x32_bf16 v[6:9], v[154:157], v[204:207], v[6:9]
	v_mfma_f32_16x16x32_bf16 v[2:5], v[162:165], v[204:207], v[2:5]
	s_barrier
	s_add_i32 s60, s60, 2
	s_addk_i32 s40, 0x100
	s_addk_i32 s41, 0x100
	s_cmpk_gt_u32 s60, 0x53
	s_cbranch_scc0 .LBB0_1750
	s_setprio 0
	s_and_b64 vcc, exec, s[50:51]
	s_cbranch_vccz .LBB0_1753
	s_barrier
